# GEMM main loops: s_setprio 1 issued before the barrier instead of after it (one fewer instruction between barrier release and the first MFMA); prep wave-0 logit/bias loads hoisted to the unit top
# speedup vs baseline: 1.0035x; 1.0035x over previous
; #define PG8_STAGE(bufoff, gbase, voff) do { _Pragma("unroll") for (int _i = 0; _i < 2; ++_i) \
;         __builtin_amdgcn_global_load_lds((const unsigned*)((const char*)(gbase) + (voff)[_i]), (LAS unsigned*)(lds + (bufoff) + ldsw + _i * 8192), 16, 0, 0); } while (0)
; #define PG8_LDA(dst, b, h) do { _Pragma("unroll") for (int m = 0; m < 4; ++m) _Pragma("unroll") for (int k = 0; k < 2; ++k) dst[m][k] = *(const LAS bf16x8*)(lds + PG8_SA(b, h) + aoff + m * 2048 + k * 1024); } while (0)
; #define PG8_LDB(dst, b, h) do { _Pragma("unroll") for (int n = 0; n < 2; ++n) _Pragma("unroll") for (int k = 0; k < 2; ++k) dst[n][k] = *(const LAS bf16x8*)(lds + PG8_SB(b, h) + boff + n * 2048 + k * 1024); } while (0)
; #define PG8_MMA(ai, bj, At, Bt) do { __builtin_amdgcn_s_setprio(1); _Pragma("unroll") for (int m = 0; m < 4; ++m) _Pragma("unroll") for (int n = 0; n < 2; ++n) _Pragma("unroll") for (int k = 0; k < 2; ++k) \
;         acc[ai][bj][m][n] = __builtin_amdgcn_mfma_f32_16x16x32_bf16(Bt[n][k], At[m][k], acc[ai][bj][m][n], 0, 0, 0); __builtin_amdgcn_s_setprio(0); } while (0)
; template <class Epi>
; __device__ __forceinline__ void gemm_phase(LAS unsigned char* lds, const Gemm g, const Epi& E) {
;     ...
;         for (int t = 0; t < nt; t += 2) {
;             const bool last = (t == nt - 2);
;             const char* a1 = cA + (size_t)(t + 1) * kstep;
;             const char* a2 = last ? nA : cA + (size_t)(t + 2) * kstep; const char* b2 = last ? nB : cB + (size_t)(t + 2) * kstep;
;             const char* a3 = a2 + kstep; const char* b3 = b2 + kstep;
;             PG8_LDB(B0, 0, 0); PG8_SCHED; PG8_LDA(At, 0, 0); PG8_STAGE(PG8_SA(1, 1), a1 + hstep, voffA);
;             PG8_WAIT_L(8); PG8_BAR; PG8_WAIT_L(0); PG8_MMA(0, 0, At, B0); PG8_BAR; PG8_SCHED;
;             PG8_LDB(B1, 0, 1); PG8_STAGE(PG8_SB(0, 0), b2, voffB);
;             PG8_BAR; PG8_WAIT_L(0); PG8_MMA(0, 1, At, B1); PG8_BAR;
;             PG8_LDA(At, 0, 1); PG8_STAGE(PG8_SA(0, 0), a2, voffA);
;             PG8_BAR; PG8_WAIT_L(0); PG8_MMA(1, 0, At, B0); PG8_BAR; PG8_SCHED;
;             PG8_STAGE(PG8_SB(0, 1), b2 + hstep, voffB);
;             PG8_WAIT_V(6); PG8_BAR; PG8_MMA(1, 1, At, B1); PG8_BAR;
;             PG8_LDB(B0, 1, 0); PG8_SCHED; PG8_LDA(At, 1, 0); PG8_STAGE(PG8_SA(0, 1), a2 + hstep, voffA);
;             PG8_WAIT_L(8); PG8_BAR; PG8_WAIT_L(0); PG8_MMA(0, 0, At, B0); PG8_BAR; PG8_SCHED;
.LBB0_30:
	s_add_u32 s28, s26, 0xfff80080
	s_addc_u32 s29, s27, -1
	s_add_i32 s34, 0, 0x10000
	v_add_u32_e32 v143, s34, v141
	ds_read_b128 v[144:147], v143
	ds_read_b128 v[148:151], v143 offset:1024
	ds_read_b128 v[152:155], v143 offset:2048
	ds_read_b128 v[156:159], v143 offset:3072
	s_cmp_eq_u32 s89, 28
	s_cselect_b32 s37, s45, s29
	s_cselect_b32 s36, s78, s28
	s_cselect_b32 s29, s43, s83
	s_cselect_b32 s28, s79, s82
	s_add_i32 m0, s39, 0xc000
	ds_read_b128 v[160:163], v142
	ds_read_b128 v[164:167], v142 offset:1024
	ds_read_b128 v[168:171], v142 offset:2048
	ds_read_b128 v[172:175], v142 offset:3072
	ds_read_b128 v[176:179], v142 offset:4096
	ds_read_b128 v[180:183], v142 offset:5120
	ds_read_b128 v[184:187], v142 offset:6144
	ds_read_b128 v[188:191], v142 offset:7168
	global_load_lds_dwordx4 v136, s[26:27]
	s_add_i32 m0, s39, 0xe000
	s_nop 0
	global_load_lds_dwordx4 v138, s[26:27]
	s_waitcnt lgkmcnt(8)
	s_setprio 1
	s_barrier
	s_waitcnt lgkmcnt(0)
	v_mfma_f32_16x16x32_bf16 v[124:127], v[144:147], v[160:163], v[124:127]
	v_mfma_f32_16x16x32_bf16 v[116:119], v[152:155], v[160:163], v[116:119]
	v_mfma_f32_16x16x32_bf16 v[108:111], v[144:147], v[168:171], v[108:111]
	v_mfma_f32_16x16x32_bf16 v[100:103], v[152:155], v[168:171], v[100:103]
	v_mfma_f32_16x16x32_bf16 v[92:95], v[144:147], v[176:179], v[92:95]
	v_mfma_f32_16x16x32_bf16 v[84:87], v[152:155], v[176:179], v[84:87]
	v_mfma_f32_16x16x32_bf16 v[76:79], v[144:147], v[184:187], v[76:79]
	v_mfma_f32_16x16x32_bf16 v[68:71], v[152:155], v[184:187], v[68:71]
	v_mfma_f32_16x16x32_bf16 v[124:127], v[148:151], v[164:167], v[124:127]
	v_mfma_f32_16x16x32_bf16 v[116:119], v[156:159], v[164:167], v[116:119]
	v_mfma_f32_16x16x32_bf16 v[108:111], v[148:151], v[172:175], v[108:111]
	v_mfma_f32_16x16x32_bf16 v[100:103], v[156:159], v[172:175], v[100:103]
	v_mfma_f32_16x16x32_bf16 v[92:95], v[148:151], v[180:183], v[92:95]
	v_mfma_f32_16x16x32_bf16 v[84:87], v[156:159], v[180:183], v[84:87]
	v_mfma_f32_16x16x32_bf16 v[76:79], v[148:151], v[188:191], v[76:79]
	v_mfma_f32_16x16x32_bf16 v[68:71], v[156:159], v[188:191], v[68:71]
	s_setprio 0
	s_barrier
	s_add_i32 s46, 0, 0x14000
	s_add_i32 s34, s34, s31
	v_add_u32_e32 v143, s46, v141
	s_mov_b32 m0, s34
	ds_read_b128 v[192:195], v143
	ds_read_b128 v[196:199], v143 offset:1024
	ds_read_b128 v[200:203], v143 offset:2048
	ds_read_b128 v[204:207], v143 offset:3072
	global_load_lds_dwordx4 v132, s[28:29]
	s_add_i32 m0, s34, 0x2000
	s_nop 0
	global_load_lds_dwordx4 v128, s[28:29]
	s_setprio 1
	s_barrier
	s_waitcnt lgkmcnt(0)
	v_mfma_f32_16x16x32_bf16 v[120:123], v[192:195], v[160:163], v[120:123]
	v_mfma_f32_16x16x32_bf16 v[112:115], v[200:203], v[160:163], v[112:115]
	v_mfma_f32_16x16x32_bf16 v[104:107], v[192:195], v[168:171], v[104:107]
	v_mfma_f32_16x16x32_bf16 v[96:99], v[200:203], v[168:171], v[96:99]
	v_mfma_f32_16x16x32_bf16 v[88:91], v[192:195], v[176:179], v[88:91]
	v_mfma_f32_16x16x32_bf16 v[80:83], v[200:203], v[176:179], v[80:83]
	v_mfma_f32_16x16x32_bf16 v[72:75], v[192:195], v[184:187], v[72:75]
	v_mfma_f32_16x16x32_bf16 v[64:67], v[200:203], v[184:187], v[64:67]
	v_mfma_f32_16x16x32_bf16 v[120:123], v[196:199], v[164:167], v[120:123]
	v_mfma_f32_16x16x32_bf16 v[112:115], v[204:207], v[164:167], v[112:115]
	v_mfma_f32_16x16x32_bf16 v[104:107], v[196:199], v[172:175], v[104:107]
	v_mfma_f32_16x16x32_bf16 v[96:99], v[204:207], v[172:175], v[96:99]
	v_mfma_f32_16x16x32_bf16 v[88:91], v[196:199], v[180:183], v[88:91]
	v_mfma_f32_16x16x32_bf16 v[80:83], v[204:207], v[180:183], v[80:83]
	v_mfma_f32_16x16x32_bf16 v[72:75], v[196:199], v[188:191], v[72:75]
	v_mfma_f32_16x16x32_bf16 v[64:67], v[204:207], v[188:191], v[64:67]
	s_setprio 0
	s_mov_b32 m0, s39
	s_barrier
	ds_read_b128 v[160:163], v142 offset:16384
	ds_read_b128 v[164:167], v142 offset:17408
	ds_read_b128 v[168:171], v142 offset:18432
	ds_read_b128 v[172:175], v142 offset:19456
	ds_read_b128 v[176:179], v142 offset:20480
	ds_read_b128 v[180:183], v142 offset:21504
	ds_read_b128 v[184:187], v142 offset:22528
	ds_read_b128 v[188:191], v142 offset:23552
	global_load_lds_dwordx4 v134, s[36:37]
	s_mov_b32 m0, s68
	s_nop 0
	global_load_lds_dwordx4 v130, s[36:37]
	s_setprio 1
	s_barrier
	s_waitcnt lgkmcnt(0)
	v_mfma_f32_16x16x32_bf16 v[60:63], v[144:147], v[160:163], v[60:63]
	v_mfma_f32_16x16x32_bf16 v[52:55], v[152:155], v[160:163], v[52:55]
	v_mfma_f32_16x16x32_bf16 v[44:47], v[144:147], v[168:171], v[44:47]
	v_mfma_f32_16x16x32_bf16 v[36:39], v[152:155], v[168:171], v[36:39]
	v_mfma_f32_16x16x32_bf16 v[28:31], v[144:147], v[176:179], v[28:31]
	v_mfma_f32_16x16x32_bf16 v[20:23], v[152:155], v[176:179], v[20:23]
	v_mfma_f32_16x16x32_bf16 v[12:15], v[144:147], v[184:187], v[12:15]
	v_mfma_f32_16x16x32_bf16 v[4:7], v[152:155], v[184:187], v[4:7]
	v_mfma_f32_16x16x32_bf16 v[60:63], v[148:151], v[164:167], v[60:63]
	v_mfma_f32_16x16x32_bf16 v[52:55], v[156:159], v[164:167], v[52:55]
	v_mfma_f32_16x16x32_bf16 v[44:47], v[148:151], v[172:175], v[44:47]
	v_mfma_f32_16x16x32_bf16 v[36:39], v[156:159], v[172:175], v[36:39]
	v_mfma_f32_16x16x32_bf16 v[28:31], v[148:151], v[180:183], v[28:31]
	v_mfma_f32_16x16x32_bf16 v[20:23], v[156:159], v[180:183], v[20:23]
	v_mfma_f32_16x16x32_bf16 v[12:15], v[148:151], v[188:191], v[12:15]
	v_mfma_f32_16x16x32_bf16 v[4:7], v[156:159], v[188:191], v[4:7]
	s_setprio 0
	s_barrier
	s_add_u32 s34, s28, 0x80000
	s_addc_u32 s35, s29, 0
	s_add_i32 s46, s46, s31
	s_mov_b32 m0, s46
	s_nop 0
	global_load_lds_dwordx4 v132, s[34:35]
	s_add_i32 m0, s46, 0x2000
	s_nop 0
	global_load_lds_dwordx4 v128, s[34:35]
	s_waitcnt vmcnt(6)
	s_setprio 1
	s_barrier
; #define PG8_STAGE(bufoff, gbase, voff) do { _Pragma("unroll") for (int _i = 0; _i < 2; ++_i) \
;         __builtin_amdgcn_global_load_lds((const unsigned*)((const char*)(gbase) + (voff)[_i]), (LAS unsigned*)(lds + (bufoff) + ldsw + _i * 8192), 16, 0, 0); } while (0)
; #define PG8_LDA(dst, b, h) do { _Pragma("unroll") for (int m = 0; m < 4; ++m) _Pragma("unroll") for (int k = 0; k < 2; ++k) dst[m][k] = *(const LAS bf16x8*)(lds + PG8_SA(b, h) + aoff + m * 2048 + k * 1024); } while (0)
; #define PG8_LDB(dst, b, h) do { _Pragma("unroll") for (int n = 0; n < 2; ++n) _Pragma("unroll") for (int k = 0; k < 2; ++k) dst[n][k] = *(const LAS bf16x8*)(lds + PG8_SB(b, h) + boff + n * 2048 + k * 1024); } while (0)
; #define PG8_MMA(ai, bj, At, Bt) do { __builtin_amdgcn_s_setprio(1); _Pragma("unroll") for (int m = 0; m < 4; ++m) _Pragma("unroll") for (int n = 0; n < 2; ++n) _Pragma("unroll") for (int k = 0; k < 2; ++k) \
;         acc[ai][bj][m][n] = __builtin_amdgcn_mfma_f32_16x16x32_bf16(Bt[n][k], At[m][k], acc[ai][bj][m][n], 0, 0, 0); __builtin_amdgcn_s_setprio(0); } while (0)
; #define PG8_WAIT_V(n) asm volatile("s_waitcnt vmcnt(" #n ")" ::: "memory")
; #define PG8_WAIT_L(n) asm volatile("s_waitcnt lgkmcnt(" #n ")" ::: "memory")
; #define PG8_BAR __builtin_amdgcn_s_barrier()
; #define PG8_SCHED __builtin_amdgcn_sched_barrier(0)
; template <class Epi>
; __device__ __forceinline__ void gemm_phase(LAS unsigned char* lds, const Gemm g, const Epi& E) {
;     ...
;             PG8_WAIT_V(6); PG8_BAR; PG8_MMA(1, 1, At, B1); PG8_BAR;
;             PG8_LDB(B0, 1, 0); PG8_SCHED; PG8_LDA(At, 1, 0); PG8_STAGE(PG8_SA(0, 1), a2 + hstep, voffA);
;             PG8_WAIT_L(8); PG8_BAR; PG8_WAIT_L(0); PG8_MMA(0, 0, At, B0); PG8_BAR; PG8_SCHED;
;             PG8_LDB(B1, 1, 1); PG8_STAGE(PG8_SB(1, 0), b3, voffB);
;             PG8_BAR; PG8_WAIT_L(0); PG8_MMA(0, 1, At, B1); PG8_BAR;
;             PG8_LDA(At, 1, 1); PG8_STAGE(PG8_SA(1, 0), a3, voffA);
;             PG8_BAR; PG8_WAIT_L(0); PG8_MMA(1, 0, At, B0); PG8_BAR; PG8_SCHED;
;             PG8_STAGE(PG8_SB(1, 1), b3 + hstep, voffB);
;             PG8_WAIT_V(6); PG8_BAR; PG8_MMA(1, 1, At, B1); PG8_BAR;
	v_mfma_f32_16x16x32_bf16 v[56:59], v[192:195], v[160:163], v[56:59]
	v_mfma_f32_16x16x32_bf16 v[48:51], v[200:203], v[160:163], v[48:51]
	v_mfma_f32_16x16x32_bf16 v[40:43], v[192:195], v[168:171], v[40:43]
	v_mfma_f32_16x16x32_bf16 v[32:35], v[200:203], v[168:171], v[32:35]
	v_mfma_f32_16x16x32_bf16 v[24:27], v[192:195], v[176:179], v[24:27]
	v_mfma_f32_16x16x32_bf16 v[16:19], v[200:203], v[176:179], v[16:19]
	v_mfma_f32_16x16x32_bf16 v[8:11], v[192:195], v[184:187], v[8:11]
	v_mfma_f32_16x16x32_bf16 v[0:3], v[200:203], v[184:187], v[0:3]
	v_mfma_f32_16x16x32_bf16 v[56:59], v[196:199], v[164:167], v[56:59]
	v_mfma_f32_16x16x32_bf16 v[48:51], v[204:207], v[164:167], v[48:51]
	v_mfma_f32_16x16x32_bf16 v[40:43], v[196:199], v[172:175], v[40:43]
	v_mfma_f32_16x16x32_bf16 v[32:35], v[204:207], v[172:175], v[32:35]
	v_mfma_f32_16x16x32_bf16 v[24:27], v[196:199], v[180:183], v[24:27]
	v_mfma_f32_16x16x32_bf16 v[16:19], v[204:207], v[180:183], v[16:19]
	v_mfma_f32_16x16x32_bf16 v[8:11], v[196:199], v[188:191], v[8:11]
	v_mfma_f32_16x16x32_bf16 v[0:3], v[204:207], v[188:191], v[0:3]
	s_setprio 0
	s_add_i32 s46, 0, 0x18000
	v_add_u32_e32 v143, s46, v141
	s_barrier
	ds_read_b128 v[144:147], v143
	ds_read_b128 v[148:151], v143 offset:1024
	ds_read_b128 v[152:155], v143 offset:2048
	ds_read_b128 v[156:159], v143 offset:3072
	s_add_u32 s34, s36, 0x80000
	s_addc_u32 s35, s37, 0
	s_mov_b32 m0, s69
	ds_read_b128 v[160:163], v142 offset:32768
	ds_read_b128 v[164:167], v142 offset:33792
	ds_read_b128 v[168:171], v142 offset:34816
	ds_read_b128 v[172:175], v142 offset:35840
	ds_read_b128 v[176:179], v142 offset:36864
	ds_read_b128 v[180:183], v142 offset:37888
	ds_read_b128 v[184:187], v142 offset:38912
	ds_read_b128 v[188:191], v142 offset:39936
	global_load_lds_dwordx4 v134, s[34:35]
	s_mov_b32 m0, s70
	s_nop 0
	global_load_lds_dwordx4 v130, s[34:35]
	s_waitcnt lgkmcnt(8)
	s_setprio 1
	s_barrier
	s_waitcnt lgkmcnt(0)
	v_mfma_f32_16x16x32_bf16 v[124:127], v[144:147], v[160:163], v[124:127]
	v_mfma_f32_16x16x32_bf16 v[116:119], v[152:155], v[160:163], v[116:119]
	v_mfma_f32_16x16x32_bf16 v[108:111], v[144:147], v[168:171], v[108:111]
	v_mfma_f32_16x16x32_bf16 v[100:103], v[152:155], v[168:171], v[100:103]
	v_mfma_f32_16x16x32_bf16 v[92:95], v[144:147], v[176:179], v[92:95]
	v_mfma_f32_16x16x32_bf16 v[84:87], v[152:155], v[176:179], v[84:87]
	v_mfma_f32_16x16x32_bf16 v[76:79], v[144:147], v[184:187], v[76:79]
	v_mfma_f32_16x16x32_bf16 v[68:71], v[152:155], v[184:187], v[68:71]
	v_mfma_f32_16x16x32_bf16 v[124:127], v[148:151], v[164:167], v[124:127]
	v_mfma_f32_16x16x32_bf16 v[116:119], v[156:159], v[164:167], v[116:119]
	v_mfma_f32_16x16x32_bf16 v[108:111], v[148:151], v[172:175], v[108:111]
	v_mfma_f32_16x16x32_bf16 v[100:103], v[156:159], v[172:175], v[100:103]
	v_mfma_f32_16x16x32_bf16 v[92:95], v[148:151], v[180:183], v[92:95]
	v_mfma_f32_16x16x32_bf16 v[84:87], v[156:159], v[180:183], v[84:87]
	v_mfma_f32_16x16x32_bf16 v[76:79], v[148:151], v[188:191], v[76:79]
	v_mfma_f32_16x16x32_bf16 v[68:71], v[156:159], v[188:191], v[68:71]
	s_setprio 0
	s_barrier
	s_add_i32 s34, 0, 0x1c000
	s_add_i32 s35, s46, s31
	v_add_u32_e32 v143, s34, v141
	s_mov_b32 m0, s35
	ds_read_b128 v[192:195], v143
	ds_read_b128 v[196:199], v143 offset:1024
	ds_read_b128 v[200:203], v143 offset:2048
	ds_read_b128 v[204:207], v143 offset:3072
	s_add_u32 s98, s28, 0x80
	s_addc_u32 s99, s29, 0
	global_load_lds_dwordx4 v132, s[98:99]
	s_add_i32 m0, s35, 0x2000
	s_add_u32 s100, s28, 0x80
	s_addc_u32 s101, s29, 0
	global_load_lds_dwordx4 v128, s[100:101]
	s_setprio 1
	s_barrier
	s_waitcnt lgkmcnt(0)
	v_mfma_f32_16x16x32_bf16 v[120:123], v[192:195], v[160:163], v[120:123]
	v_mfma_f32_16x16x32_bf16 v[112:115], v[200:203], v[160:163], v[112:115]
	v_mfma_f32_16x16x32_bf16 v[104:107], v[192:195], v[168:171], v[104:107]
	v_mfma_f32_16x16x32_bf16 v[96:99], v[200:203], v[168:171], v[96:99]
	v_mfma_f32_16x16x32_bf16 v[88:91], v[192:195], v[176:179], v[88:91]
	v_mfma_f32_16x16x32_bf16 v[80:83], v[200:203], v[176:179], v[80:83]
	v_mfma_f32_16x16x32_bf16 v[72:75], v[192:195], v[184:187], v[72:75]
	v_mfma_f32_16x16x32_bf16 v[64:67], v[200:203], v[184:187], v[64:67]
	v_mfma_f32_16x16x32_bf16 v[120:123], v[196:199], v[164:167], v[120:123]
	v_mfma_f32_16x16x32_bf16 v[112:115], v[204:207], v[164:167], v[112:115]
	v_mfma_f32_16x16x32_bf16 v[104:107], v[196:199], v[172:175], v[104:107]
	v_mfma_f32_16x16x32_bf16 v[96:99], v[204:207], v[172:175], v[96:99]
	v_mfma_f32_16x16x32_bf16 v[88:91], v[196:199], v[180:183], v[88:91]
	v_mfma_f32_16x16x32_bf16 v[80:83], v[204:207], v[180:183], v[80:83]
	v_mfma_f32_16x16x32_bf16 v[72:75], v[196:199], v[188:191], v[72:75]
	v_mfma_f32_16x16x32_bf16 v[64:67], v[204:207], v[188:191], v[64:67]
	s_setprio 0
	s_mov_b32 m0, s2
	s_barrier
	ds_read_b128 v[160:163], v142 offset:49152
	ds_read_b128 v[164:167], v142 offset:50176
	ds_read_b128 v[168:171], v142 offset:51200
	ds_read_b128 v[172:175], v142 offset:52224
	ds_read_b128 v[176:179], v142 offset:53248
	ds_read_b128 v[180:183], v142 offset:54272
	ds_read_b128 v[184:187], v142 offset:55296
	ds_read_b128 v[188:191], v142 offset:56320
	s_add_u32 s98, s36, 0x80
	s_addc_u32 s99, s37, 0
	global_load_lds_dwordx4 v134, s[98:99]
	s_mov_b32 m0, s71
	s_add_u32 s100, s36, 0x80
	s_addc_u32 s101, s37, 0
	global_load_lds_dwordx4 v130, s[100:101]
	s_setprio 1
	s_barrier
; __device__ __forceinline__ u32x4 pack8u(f32x4 a, f32x4 b) { u32x4 w = {cvt_pk_bf16(a[0], a[1]), cvt_pk_bf16(a[2], a[3]), cvt_pk_bf16(b[0], b[1]), cvt_pk_bf16(b[2], b[3])}; return w; }
; __device__ __forceinline__ float siluf_(float x) { return x * __builtin_amdgcn_rcpf(1.0f + __expf(-x)); }
; #define PG8_STAGE(bufoff, gbase, voff) do { _Pragma("unroll") for (int _i = 0; _i < 2; ++_i) \
;         __builtin_amdgcn_global_load_lds((const unsigned*)((const char*)(gbase) + (voff)[_i]), (LAS unsigned*)(lds + (bufoff) + ldsw + _i * 8192), 16, 0, 0); } while (0)
; #define PG8_MMA(ai, bj, At, Bt) do { __builtin_amdgcn_s_setprio(1); _Pragma("unroll") for (int m = 0; m < 4; ++m) _Pragma("unroll") for (int n = 0; n < 2; ++n) _Pragma("unroll") for (int k = 0; k < 2; ++k) \
;         acc[ai][bj][m][n] = __builtin_amdgcn_mfma_f32_16x16x32_bf16(Bt[n][k], At[m][k], acc[ai][bj][m][n], 0, 0, 0); __builtin_amdgcn_s_setprio(0); } while (0)
; #define PG8_WAIT_V(n) asm volatile("s_waitcnt vmcnt(" #n ")" ::: "memory")
; #define PG8_WAIT_L(n) asm volatile("s_waitcnt lgkmcnt(" #n ")" ::: "memory")
; #define PG8_BAR __builtin_amdgcn_s_barrier()
; #define PG8_SCHED __builtin_amdgcn_sched_barrier(0)
; template <class Epi>
; __device__ __forceinline__ void gemm_phase(LAS unsigned char* lds, const Gemm g, const Epi& E) {
;     ...
;             PG8_BAR; PG8_WAIT_L(0); PG8_MMA(1, 0, At, B0); PG8_BAR; PG8_SCHED;
;             PG8_STAGE(PG8_SB(1, 1), b3 + hstep, voffB);
;             PG8_WAIT_V(6); PG8_BAR; PG8_MMA(1, 1, At, B1); PG8_BAR;
;         }
;         E(acc, cur, wr, wc, fr, fq);
;         if (!has_next) break;
;     __device__ __forceinline__ void operator()(const AccT& acc, const Unit& u, int wr, int wc, int fr, int fq) const {
;     ...
;         for (int ai = 0; ai < 2; ++ai)
; #pragma unroll
;             for (int m = 0; m < 4; ++m) {
;                 const int row = u.pm * 256 + ai * 128 + wr * 64 + m * 16 + fr;
;                 f32x4 o0, o1;
; #pragma unroll
;                 for (int j = 0; j < 4; ++j) { o0[j] = siluf_(acc[ai][0][m][0][j]) * acc[ai][1][m][0][j]; o1[j] = siluf_(acc[ai][0][m][1][j]) * acc[ai][1][m][1][j]; }
;                 *(u32x4*)(ACT + (size_t)row * DFF + u.pn * 128 + wc * 32 + fq * 8) = pack8u(o0, o1);
	s_waitcnt lgkmcnt(0)
	v_mfma_f32_16x16x32_bf16 v[60:63], v[144:147], v[160:163], v[60:63]
	v_mfma_f32_16x16x32_bf16 v[52:55], v[152:155], v[160:163], v[52:55]
	v_mfma_f32_16x16x32_bf16 v[44:47], v[144:147], v[168:171], v[44:47]
	v_mfma_f32_16x16x32_bf16 v[36:39], v[152:155], v[168:171], v[36:39]
	v_mfma_f32_16x16x32_bf16 v[28:31], v[144:147], v[176:179], v[28:31]
	v_mfma_f32_16x16x32_bf16 v[20:23], v[152:155], v[176:179], v[20:23]
	v_mfma_f32_16x16x32_bf16 v[12:15], v[144:147], v[184:187], v[12:15]
	v_mfma_f32_16x16x32_bf16 v[4:7], v[152:155], v[184:187], v[4:7]
	v_mfma_f32_16x16x32_bf16 v[60:63], v[148:151], v[164:167], v[60:63]
	v_mfma_f32_16x16x32_bf16 v[52:55], v[156:159], v[164:167], v[52:55]
	v_mfma_f32_16x16x32_bf16 v[44:47], v[148:151], v[172:175], v[44:47]
	v_mfma_f32_16x16x32_bf16 v[36:39], v[156:159], v[172:175], v[36:39]
	v_mfma_f32_16x16x32_bf16 v[28:31], v[148:151], v[180:183], v[28:31]
	v_mfma_f32_16x16x32_bf16 v[20:23], v[156:159], v[180:183], v[20:23]
	v_mfma_f32_16x16x32_bf16 v[12:15], v[148:151], v[188:191], v[12:15]
	v_mfma_f32_16x16x32_bf16 v[4:7], v[156:159], v[188:191], v[4:7]
	s_setprio 0
	s_barrier
	s_add_u32 s28, s28, 0x80080
	s_addc_u32 s29, s29, 0
	s_add_i32 s34, s34, s31
	s_mov_b32 m0, s34
	s_nop 0
	global_load_lds_dwordx4 v132, s[28:29]
	s_add_i32 m0, s34, 0x2000
	s_nop 0
	global_load_lds_dwordx4 v128, s[28:29]
	s_waitcnt vmcnt(6)
	s_setprio 1
	s_barrier
	v_mfma_f32_16x16x32_bf16 v[56:59], v[192:195], v[160:163], v[56:59]
	v_mfma_f32_16x16x32_bf16 v[48:51], v[200:203], v[160:163], v[48:51]
	v_mfma_f32_16x16x32_bf16 v[40:43], v[192:195], v[168:171], v[40:43]
	v_mfma_f32_16x16x32_bf16 v[32:35], v[200:203], v[168:171], v[32:35]
	v_mfma_f32_16x16x32_bf16 v[24:27], v[192:195], v[176:179], v[24:27]
	v_mfma_f32_16x16x32_bf16 v[16:19], v[200:203], v[176:179], v[16:19]
	v_mfma_f32_16x16x32_bf16 v[8:11], v[192:195], v[184:187], v[8:11]
	v_mfma_f32_16x16x32_bf16 v[0:3], v[200:203], v[184:187], v[0:3]
	v_mfma_f32_16x16x32_bf16 v[56:59], v[196:199], v[164:167], v[56:59]
	v_mfma_f32_16x16x32_bf16 v[48:51], v[204:207], v[164:167], v[48:51]
	v_mfma_f32_16x16x32_bf16 v[40:43], v[196:199], v[172:175], v[40:43]
	v_mfma_f32_16x16x32_bf16 v[32:35], v[204:207], v[172:175], v[32:35]
	v_mfma_f32_16x16x32_bf16 v[24:27], v[196:199], v[180:183], v[24:27]
	v_mfma_f32_16x16x32_bf16 v[16:19], v[204:207], v[180:183], v[16:19]
	v_mfma_f32_16x16x32_bf16 v[8:11], v[196:199], v[188:191], v[8:11]
	v_mfma_f32_16x16x32_bf16 v[0:3], v[204:207], v[188:191], v[0:3]
	s_setprio 0
	s_add_i32 s89, s89, 2
	s_add_u32 s26, s26, 0x100
	s_addc_u32 s27, s27, 0
	s_add_u32 s82, s82, 0x100
	s_addc_u32 s83, s83, 0
	s_cmp_gt_u32 s89, 29
	s_barrier
	s_cbranch_scc0 .LBB0_30
	v_mul_f32_e32 v145, 0xbfb8aa3b, v116
	v_exp_f32_e32 v145, v145
	v_mul_f32_e32 v144, 0xbfb8aa3b, v124
	v_exp_f32_e32 v144, v144
	v_readlane_b32 s28, v252, 37
	v_add_f32_e32 v145, 1.0, v145
	v_rcp_f32_e32 v146, v145
	v_mul_f32_e32 v145, 0xbfb8aa3b, v125
	v_exp_f32_e32 v145, v145
	v_add_f32_e32 v144, 1.0, v144
	v_rcp_f32_e32 v144, v144
	s_lshl_b32 s26, s76, 7
	v_add_f32_e32 v145, 1.0, v145
	v_rcp_f32_e32 v145, v145
	v_readlane_b32 s29, v252, 38
	v_lshl_add_u32 v143, s88, 8, v140
	s_ashr_i32 s27, s26, 31
	v_pk_mul_f32 v[124:125], v[124:125], v[144:145]
	s_movk_i32 s34, 0x2c00
	v_pk_mul_f32 v[120:121], v[124:125], v[120:121]
	v_mul_f32_e32 v124, 0xbfb8aa3b, v117
	v_exp_f32_e32 v124, v124
	s_lshl_b64 s[88:89], s[26:27], 1
	s_and_b64 vcc, exec, s[40:41]
	s_mov_b32 s76, s42
	v_add_f32_e32 v124, 1.0, v124
	v_rcp_f32_e32 v147, v124
	s_nop 0
	v_pk_mul_f32 v[116:117], v[116:117], v[146:147]
	s_nop 0
	v_pk_mul_f32 v[112:113], v[116:117], v[112:113]
	v_mul_f32_e32 v117, 0xbfb8aa3b, v118
	v_exp_f32_e32 v117, v117
	v_mul_f32_e32 v116, 0xbfb8aa3b, v126
	v_exp_f32_e32 v116, v116
	v_add_f32_e32 v117, 1.0, v117
	v_rcp_f32_e32 v124, v117
	v_mul_f32_e32 v117, 0xbfb8aa3b, v127
	v_exp_f32_e32 v117, v117
	v_add_f32_e32 v116, 1.0, v116
	v_rcp_f32_e32 v116, v116
	v_add_f32_e32 v117, 1.0, v117
	v_rcp_f32_e32 v117, v117
	s_nop 0
	v_pk_mul_f32 v[116:117], v[126:127], v[116:117]
	s_nop 0
	v_pk_mul_f32 v[116:117], v[116:117], v[122:123]
	v_mul_f32_e32 v122, 0xbfb8aa3b, v119
	v_exp_f32_e32 v122, v122
	s_nop 0
	v_add_f32_e32 v122, 1.0, v122
	v_rcp_f32_e32 v125, v122
	s_nop 0
	v_pk_mul_f32 v[118:119], v[118:119], v[124:125]
	s_nop 0
	v_pk_mul_f32 v[118:119], v[118:119], v[114:115]
	v_cvt_pk_bf16_f32 v115, v116, v117
	v_cvt_pk_bf16_f32 v116, v112, v113
	v_mov_b64_e32 v[112:113], s[28:29]
	v_cvt_pk_bf16_f32 v117, v118, v119
	v_mad_i64_i32 v[118:119], s[28:29], v143, s34, v[112:113]
	v_lshl_add_u64 v[118:119], v[118:119], 0, s[88:89]
	s_mov_b64 s[28:29], s[90:91]
	v_lshl_add_u64 v[118:119], v[118:119], 0, s[28:29]
	v_cvt_pk_bf16_f32 v114, v120, v121
	v_lshl_add_u64 v[118:119], v[118:119], 0, v[208:209]
	global_store_dwordx4 v[118:119], v[114:117], off
	s_nop 1
	v_mul_f32_e32 v115, 0xbfb8aa3b, v100
	v_exp_f32_e32 v115, v115
	v_mul_f32_e32 v114, 0xbfb8aa3b, v108
	v_exp_f32_e32 v114, v114
	v_add_f32_e32 v115, 1.0, v115
	v_rcp_f32_e32 v116, v115
	v_mul_f32_e32 v115, 0xbfb8aa3b, v109
	v_exp_f32_e32 v115, v115
	v_add_f32_e32 v114, 1.0, v114
	v_rcp_f32_e32 v114, v114
	v_add_f32_e32 v115, 1.0, v115
	v_rcp_f32_e32 v115, v115
	s_nop 0
	v_pk_mul_f32 v[108:109], v[108:109], v[114:115]
	s_nop 0
	v_pk_mul_f32 v[104:105], v[108:109], v[104:105]
	v_mul_f32_e32 v108, 0xbfb8aa3b, v101
	v_exp_f32_e32 v108, v108
	s_nop 0
	v_add_f32_e32 v108, 1.0, v108
	v_rcp_f32_e32 v117, v108
	s_nop 0
	v_pk_mul_f32 v[100:101], v[100:101], v[116:117]
	s_nop 0
	v_pk_mul_f32 v[100:101], v[100:101], v[96:97]
	v_mul_f32_e32 v97, 0xbfb8aa3b, v102
	v_exp_f32_e32 v97, v97
; __device__ __forceinline__ u32x4 pack8u(f32x4 a, f32x4 b) { u32x4 w = {cvt_pk_bf16(a[0], a[1]), cvt_pk_bf16(a[2], a[3]), cvt_pk_bf16(b[0], b[1]), cvt_pk_bf16(b[2], b[3])}; return w; }
; __device__ __forceinline__ float siluf_(float x) { return x * __builtin_amdgcn_rcpf(1.0f + __expf(-x)); }
;     __device__ __forceinline__ void operator()(const AccT& acc, const Unit& u, int wr, int wc, int fr, int fq) const {
;     ...
;         for (int ai = 0; ai < 2; ++ai)
; #pragma unroll
;             for (int m = 0; m < 4; ++m) {
;                 const int row = u.pm * 256 + ai * 128 + wr * 64 + m * 16 + fr;
;                 f32x4 o0, o1;
; #pragma unroll
;                 for (int j = 0; j < 4; ++j) { o0[j] = siluf_(acc[ai][0][m][0][j]) * acc[ai][1][m][0][j]; o1[j] = siluf_(acc[ai][0][m][1][j]) * acc[ai][1][m][1][j]; }
;                 *(u32x4*)(ACT + (size_t)row * DFF + u.pn * 128 + wc * 32 + fq * 8) = pack8u(o0, o1);
	v_mul_f32_e32 v96, 0xbfb8aa3b, v110
	v_exp_f32_e32 v96, v96
	v_add_f32_e32 v97, 1.0, v97
	v_rcp_f32_e32 v108, v97
	v_mul_f32_e32 v97, 0xbfb8aa3b, v111
	v_exp_f32_e32 v97, v97
	v_add_f32_e32 v96, 1.0, v96
	v_rcp_f32_e32 v96, v96
	v_add_f32_e32 v97, 1.0, v97
	v_rcp_f32_e32 v97, v97
	s_nop 0
	v_pk_mul_f32 v[96:97], v[110:111], v[96:97]
	s_nop 0
	v_pk_mul_f32 v[106:107], v[96:97], v[106:107]
	v_mul_f32_e32 v96, 0xbfb8aa3b, v103
	v_exp_f32_e32 v96, v96
	s_nop 0
	v_add_f32_e32 v96, 1.0, v96
	v_rcp_f32_e32 v109, v96
	s_nop 0
	v_pk_mul_f32 v[96:97], v[102:103], v[108:109]
	v_or_b32_e32 v108, 16, v143
	v_pk_mul_f32 v[102:103], v[96:97], v[98:99]
	v_cvt_pk_bf16_f32 v98, v100, v101
	v_mad_i64_i32 v[100:101], s[26:27], v108, s34, v[112:113]
	v_lshl_add_u64 v[100:101], v[100:101], 0, s[88:89]
	v_lshl_add_u64 v[100:101], v[100:101], 0, s[28:29]
	v_cvt_pk_bf16_f32 v96, v104, v105
	v_cvt_pk_bf16_f32 v97, v106, v107
	v_cvt_pk_bf16_f32 v99, v102, v103
	v_lshl_add_u64 v[100:101], v[100:101], 0, v[208:209]
	global_store_dwordx4 v[100:101], v[96:99], off
	s_nop 1
	v_mul_f32_e32 v97, 0xbfb8aa3b, v84
	v_exp_f32_e32 v97, v97
	v_mul_f32_e32 v96, 0xbfb8aa3b, v92
	v_exp_f32_e32 v96, v96
	v_add_f32_e32 v97, 1.0, v97
	v_rcp_f32_e32 v98, v97
	v_mul_f32_e32 v97, 0xbfb8aa3b, v93
	v_exp_f32_e32 v97, v97
	v_add_f32_e32 v96, 1.0, v96
	v_rcp_f32_e32 v96, v96
	v_add_f32_e32 v97, 1.0, v97
	v_rcp_f32_e32 v97, v97
	s_nop 0
	v_pk_mul_f32 v[92:93], v[92:93], v[96:97]
	s_nop 0
	v_pk_mul_f32 v[88:89], v[92:93], v[88:89]
	v_mul_f32_e32 v92, 0xbfb8aa3b, v85
	v_exp_f32_e32 v92, v92
	s_nop 0
	v_add_f32_e32 v92, 1.0, v92
	v_rcp_f32_e32 v99, v92
	s_nop 0
	v_pk_mul_f32 v[84:85], v[84:85], v[98:99]
	s_nop 0
	v_pk_mul_f32 v[84:85], v[84:85], v[80:81]
	v_mul_f32_e32 v81, 0xbfb8aa3b, v86
	v_exp_f32_e32 v81, v81
	v_mul_f32_e32 v80, 0xbfb8aa3b, v94
	v_exp_f32_e32 v80, v80
	v_add_f32_e32 v81, 1.0, v81
	v_rcp_f32_e32 v92, v81
	v_mul_f32_e32 v81, 0xbfb8aa3b, v95
	v_exp_f32_e32 v81, v81
	v_add_f32_e32 v80, 1.0, v80
	v_rcp_f32_e32 v80, v80
	v_add_f32_e32 v81, 1.0, v81
	v_rcp_f32_e32 v81, v81
	s_nop 0
	v_pk_mul_f32 v[80:81], v[94:95], v[80:81]
	s_nop 0
	v_pk_mul_f32 v[90:91], v[80:81], v[90:91]
	v_mul_f32_e32 v80, 0xbfb8aa3b, v87
	v_exp_f32_e32 v80, v80
	s_nop 0
	v_add_f32_e32 v80, 1.0, v80
	v_rcp_f32_e32 v93, v80
	s_nop 0
	v_pk_mul_f32 v[80:81], v[86:87], v[92:93]
	v_or_b32_e32 v92, 32, v143
	v_pk_mul_f32 v[86:87], v[80:81], v[82:83]
	v_cvt_pk_bf16_f32 v82, v84, v85
	v_mad_i64_i32 v[84:85], s[26:27], v92, s34, v[112:113]
	v_lshl_add_u64 v[84:85], v[84:85], 0, s[88:89]
	v_lshl_add_u64 v[84:85], v[84:85], 0, s[28:29]
	v_cvt_pk_bf16_f32 v80, v88, v89
	v_cvt_pk_bf16_f32 v81, v90, v91
	v_cvt_pk_bf16_f32 v83, v86, v87
	v_lshl_add_u64 v[84:85], v[84:85], 0, v[208:209]
	global_store_dwordx4 v[84:85], v[80:83], off
	s_nop 1
	v_mul_f32_e32 v81, 0xbfb8aa3b, v68
	v_exp_f32_e32 v81, v81
	v_mul_f32_e32 v80, 0xbfb8aa3b, v76
	v_exp_f32_e32 v80, v80
	v_add_f32_e32 v81, 1.0, v81
	v_rcp_f32_e32 v82, v81
	v_mul_f32_e32 v81, 0xbfb8aa3b, v77
	v_exp_f32_e32 v81, v81
	v_add_f32_e32 v80, 1.0, v80
	v_rcp_f32_e32 v80, v80
	v_add_f32_e32 v81, 1.0, v81
	v_rcp_f32_e32 v81, v81
	s_nop 0
	v_pk_mul_f32 v[76:77], v[76:77], v[80:81]
	s_nop 0
	v_pk_mul_f32 v[72:73], v[76:77], v[72:73]
	v_mul_f32_e32 v76, 0xbfb8aa3b, v69
	v_exp_f32_e32 v76, v76
	s_nop 0
	v_add_f32_e32 v76, 1.0, v76
	v_rcp_f32_e32 v83, v76
	s_nop 0
	v_pk_mul_f32 v[68:69], v[68:69], v[82:83]
	s_nop 0
	v_pk_mul_f32 v[68:69], v[68:69], v[64:65]
	v_mul_f32_e32 v65, 0xbfb8aa3b, v70
	v_exp_f32_e32 v65, v65
	v_mul_f32_e32 v64, 0xbfb8aa3b, v78
	v_exp_f32_e32 v64, v64
	v_add_f32_e32 v65, 1.0, v65
	v_rcp_f32_e32 v76, v65
	v_mul_f32_e32 v65, 0xbfb8aa3b, v79
	v_exp_f32_e32 v65, v65
	v_add_f32_e32 v64, 1.0, v64
	v_rcp_f32_e32 v64, v64
	v_add_f32_e32 v65, 1.0, v65
	v_rcp_f32_e32 v65, v65
	s_nop 0
	v_pk_mul_f32 v[64:65], v[78:79], v[64:65]
	s_nop 0
	v_pk_mul_f32 v[74:75], v[64:65], v[74:75]
	v_mul_f32_e32 v64, 0xbfb8aa3b, v71
	v_exp_f32_e32 v64, v64
	s_nop 0
	v_add_f32_e32 v64, 1.0, v64
	v_rcp_f32_e32 v77, v64
	s_nop 0
	v_pk_mul_f32 v[64:65], v[70:71], v[76:77]
	v_or_b32_e32 v76, 48, v143
	v_pk_mul_f32 v[70:71], v[64:65], v[66:67]
	v_cvt_pk_bf16_f32 v66, v68, v69
	v_mad_i64_i32 v[68:69], s[26:27], v76, s34, v[112:113]
	v_lshl_add_u64 v[68:69], v[68:69], 0, s[88:89]
	v_lshl_add_u64 v[68:69], v[68:69], 0, s[28:29]
	v_cvt_pk_bf16_f32 v64, v72, v73
	v_cvt_pk_bf16_f32 v65, v74, v75
	v_cvt_pk_bf16_f32 v67, v70, v71
	v_lshl_add_u64 v[68:69], v[68:69], 0, v[208:209]
	global_store_dwordx4 v[68:69], v[64:67], off
	v_add_u32_e32 v68, 0x80, v143
	s_nop 0
	v_mul_f32_e32 v65, 0xbfb8aa3b, v52
	v_exp_f32_e32 v65, v65
	v_mul_f32_e32 v64, 0xbfb8aa3b, v60
	v_exp_f32_e32 v64, v64
	v_add_f32_e32 v65, 1.0, v65
	v_rcp_f32_e32 v66, v65
	v_mul_f32_e32 v65, 0xbfb8aa3b, v61
	v_exp_f32_e32 v65, v65
	v_add_f32_e32 v64, 1.0, v64
	v_rcp_f32_e32 v64, v64
	v_add_f32_e32 v65, 1.0, v65
	v_rcp_f32_e32 v65, v65
	s_nop 0
	v_pk_mul_f32 v[60:61], v[60:61], v[64:65]
	s_nop 0
	v_pk_mul_f32 v[56:57], v[60:61], v[56:57]
	v_mul_f32_e32 v60, 0xbfb8aa3b, v53
	v_exp_f32_e32 v60, v60
	s_nop 0
	v_add_f32_e32 v60, 1.0, v60
	v_rcp_f32_e32 v67, v60
	s_nop 0
	v_pk_mul_f32 v[52:53], v[52:53], v[66:67]
	s_nop 0
	v_pk_mul_f32 v[52:53], v[52:53], v[48:49]
	v_mul_f32_e32 v49, 0xbfb8aa3b, v54
	v_exp_f32_e32 v49, v49
	v_mul_f32_e32 v48, 0xbfb8aa3b, v62
	v_exp_f32_e32 v48, v48
	v_add_f32_e32 v49, 1.0, v49
	v_rcp_f32_e32 v60, v49
	v_mul_f32_e32 v49, 0xbfb8aa3b, v63
	v_exp_f32_e32 v49, v49
	v_add_f32_e32 v48, 1.0, v48
	v_rcp_f32_e32 v48, v48
	v_add_f32_e32 v49, 1.0, v49
	v_rcp_f32_e32 v49, v49
	s_nop 0
	v_pk_mul_f32 v[48:49], v[62:63], v[48:49]
; __device__ __forceinline__ u32x4 pack8u(f32x4 a, f32x4 b) { u32x4 w = {cvt_pk_bf16(a[0], a[1]), cvt_pk_bf16(a[2], a[3]), cvt_pk_bf16(b[0], b[1]), cvt_pk_bf16(b[2], b[3])}; return w; }
; __device__ __forceinline__ float siluf_(float x) { return x * __builtin_amdgcn_rcpf(1.0f + __expf(-x)); }
; #define PG8_WAIT_V(n) asm volatile("s_waitcnt vmcnt(" #n ")" ::: "memory")
; #define PG8_BAR __builtin_amdgcn_s_barrier()
; template <class Epi>
; __device__ __forceinline__ void gemm_phase(LAS unsigned char* lds, const Gemm g, const Epi& E) {
;     ...
;         if (!has_next) break;
; #pragma unroll
;         for (int a = 0; a < 2; ++a)
; #pragma unroll
;             for (int b = 0; b < 2; ++b)
; #pragma unroll
;                 for (int m = 0; m < 4; ++m)
; #pragma unroll
;                     for (int n = 0; n < 2; ++n) acc[a][b][m][n] = (f32x4){0.f, 0.f, 0.f, 0.f};
;         cur = nxt; cA = nA; cB = nB; ++ui;
;     }
;     PG8_WAIT_V(0);
;     if (wr == 0) PG8_BAR;
;     __device__ __forceinline__ void operator()(const AccT& acc, const Unit& u, int wr, int wc, int fr, int fq) const {
;     ...
;         for (int ai = 0; ai < 2; ++ai)
; #pragma unroll
;             for (int m = 0; m < 4; ++m) {
;                 const int row = u.pm * 256 + ai * 128 + wr * 64 + m * 16 + fr;
;                 f32x4 o0, o1;
; #pragma unroll
;                 for (int j = 0; j < 4; ++j) { o0[j] = siluf_(acc[ai][0][m][0][j]) * acc[ai][1][m][0][j]; o1[j] = siluf_(acc[ai][0][m][1][j]) * acc[ai][1][m][1][j]; }
;                 *(u32x4*)(ACT + (size_t)row * DFF + u.pn * 128 + wc * 32 + fq * 8) = pack8u(o0, o1);
	s_nop 0
	v_pk_mul_f32 v[58:59], v[48:49], v[58:59]
	v_mul_f32_e32 v48, 0xbfb8aa3b, v55
	v_exp_f32_e32 v48, v48
	s_nop 0
	v_add_f32_e32 v48, 1.0, v48
	v_rcp_f32_e32 v61, v48
	s_nop 0
	v_pk_mul_f32 v[48:49], v[54:55], v[60:61]
	s_nop 0
	v_pk_mul_f32 v[54:55], v[48:49], v[50:51]
	v_cvt_pk_bf16_f32 v50, v52, v53
	v_mad_i64_i32 v[52:53], s[26:27], v68, s34, v[112:113]
	v_lshl_add_u64 v[52:53], v[52:53], 0, s[88:89]
	v_lshl_add_u64 v[52:53], v[52:53], 0, s[28:29]
	v_cvt_pk_bf16_f32 v48, v56, v57
	v_cvt_pk_bf16_f32 v49, v58, v59
	v_cvt_pk_bf16_f32 v51, v54, v55
	v_lshl_add_u64 v[52:53], v[52:53], 0, v[208:209]
	global_store_dwordx4 v[52:53], v[48:51], off
	s_nop 1
	v_mul_f32_e32 v49, 0xbfb8aa3b, v36
	v_exp_f32_e32 v49, v49
	v_mul_f32_e32 v48, 0xbfb8aa3b, v44
	v_exp_f32_e32 v48, v48
	v_add_f32_e32 v49, 1.0, v49
	v_rcp_f32_e32 v50, v49
	v_mul_f32_e32 v49, 0xbfb8aa3b, v45
	v_exp_f32_e32 v49, v49
	v_add_f32_e32 v48, 1.0, v48
	v_rcp_f32_e32 v48, v48
	v_add_f32_e32 v49, 1.0, v49
	v_rcp_f32_e32 v49, v49
	s_nop 0
	v_pk_mul_f32 v[44:45], v[44:45], v[48:49]
	s_nop 0
	v_pk_mul_f32 v[40:41], v[44:45], v[40:41]
	v_mul_f32_e32 v44, 0xbfb8aa3b, v37
	v_exp_f32_e32 v44, v44
	s_nop 0
	v_add_f32_e32 v44, 1.0, v44
	v_rcp_f32_e32 v51, v44
	s_nop 0
	v_pk_mul_f32 v[36:37], v[36:37], v[50:51]
	s_nop 0
	v_pk_mul_f32 v[36:37], v[36:37], v[32:33]
	v_mul_f32_e32 v33, 0xbfb8aa3b, v38
	v_exp_f32_e32 v33, v33
	v_mul_f32_e32 v32, 0xbfb8aa3b, v46
	v_exp_f32_e32 v32, v32
	v_add_f32_e32 v33, 1.0, v33
	v_rcp_f32_e32 v44, v33
	v_mul_f32_e32 v33, 0xbfb8aa3b, v47
	v_exp_f32_e32 v33, v33
	v_add_f32_e32 v32, 1.0, v32
	v_rcp_f32_e32 v32, v32
	v_add_f32_e32 v33, 1.0, v33
	v_rcp_f32_e32 v33, v33
	s_nop 0
	v_pk_mul_f32 v[32:33], v[46:47], v[32:33]
	s_nop 0
	v_pk_mul_f32 v[42:43], v[32:33], v[42:43]
	v_mul_f32_e32 v32, 0xbfb8aa3b, v39
	v_exp_f32_e32 v32, v32
	s_nop 0
	v_add_f32_e32 v32, 1.0, v32
	v_rcp_f32_e32 v45, v32
	s_nop 0
	v_pk_mul_f32 v[32:33], v[38:39], v[44:45]
	v_add_u32_e32 v44, 0x90, v143
	v_pk_mul_f32 v[38:39], v[32:33], v[34:35]
	v_cvt_pk_bf16_f32 v34, v36, v37
	v_mad_i64_i32 v[36:37], s[26:27], v44, s34, v[112:113]
	v_lshl_add_u64 v[36:37], v[36:37], 0, s[88:89]
	v_lshl_add_u64 v[36:37], v[36:37], 0, s[28:29]
	v_cvt_pk_bf16_f32 v32, v40, v41
	v_cvt_pk_bf16_f32 v33, v42, v43
	v_cvt_pk_bf16_f32 v35, v38, v39
	v_lshl_add_u64 v[36:37], v[36:37], 0, v[208:209]
	global_store_dwordx4 v[36:37], v[32:35], off
	s_nop 1
	v_mul_f32_e32 v33, 0xbfb8aa3b, v20
	v_exp_f32_e32 v33, v33
	v_mul_f32_e32 v32, 0xbfb8aa3b, v28
	v_exp_f32_e32 v32, v32
	v_add_f32_e32 v33, 1.0, v33
	v_rcp_f32_e32 v34, v33
	v_mul_f32_e32 v33, 0xbfb8aa3b, v29
	v_exp_f32_e32 v33, v33
	v_add_f32_e32 v32, 1.0, v32
	v_rcp_f32_e32 v32, v32
	v_add_f32_e32 v33, 1.0, v33
	v_rcp_f32_e32 v33, v33
	s_nop 0
	v_pk_mul_f32 v[28:29], v[28:29], v[32:33]
	s_nop 0
	v_pk_mul_f32 v[24:25], v[28:29], v[24:25]
	v_mul_f32_e32 v28, 0xbfb8aa3b, v21
	v_exp_f32_e32 v28, v28
	s_nop 0
	v_add_f32_e32 v28, 1.0, v28
	v_rcp_f32_e32 v35, v28
	s_nop 0
	v_pk_mul_f32 v[20:21], v[20:21], v[34:35]
	s_nop 0
	v_pk_mul_f32 v[20:21], v[20:21], v[16:17]
	v_mul_f32_e32 v17, 0xbfb8aa3b, v22
	v_exp_f32_e32 v17, v17
	v_mul_f32_e32 v16, 0xbfb8aa3b, v30
	v_exp_f32_e32 v16, v16
	v_add_f32_e32 v17, 1.0, v17
	v_rcp_f32_e32 v28, v17
	v_mul_f32_e32 v17, 0xbfb8aa3b, v31
	v_exp_f32_e32 v17, v17
	v_add_f32_e32 v16, 1.0, v16
	v_rcp_f32_e32 v16, v16
	v_add_f32_e32 v17, 1.0, v17
	v_rcp_f32_e32 v17, v17
	s_nop 0
	v_pk_mul_f32 v[16:17], v[30:31], v[16:17]
	s_nop 0
	v_pk_mul_f32 v[26:27], v[16:17], v[26:27]
	v_mul_f32_e32 v16, 0xbfb8aa3b, v23
	v_exp_f32_e32 v16, v16
	s_nop 0
	v_add_f32_e32 v16, 1.0, v16
	v_rcp_f32_e32 v29, v16
	s_nop 0
	v_pk_mul_f32 v[16:17], v[22:23], v[28:29]
	v_add_u32_e32 v28, 0xa0, v143
	v_pk_mul_f32 v[22:23], v[16:17], v[18:19]
	v_cvt_pk_bf16_f32 v18, v20, v21
	v_mad_i64_i32 v[20:21], s[26:27], v28, s34, v[112:113]
	v_lshl_add_u64 v[20:21], v[20:21], 0, s[88:89]
	v_lshl_add_u64 v[20:21], v[20:21], 0, s[28:29]
	v_cvt_pk_bf16_f32 v16, v24, v25
	v_cvt_pk_bf16_f32 v17, v26, v27
	v_cvt_pk_bf16_f32 v19, v22, v23
	v_lshl_add_u64 v[20:21], v[20:21], 0, v[208:209]
	global_store_dwordx4 v[20:21], v[16:19], off
	s_nop 1
	v_mul_f32_e32 v17, 0xbfb8aa3b, v4
	v_exp_f32_e32 v17, v17
	v_mul_f32_e32 v16, 0xbfb8aa3b, v12
	v_exp_f32_e32 v16, v16
	v_add_f32_e32 v17, 1.0, v17
	v_rcp_f32_e32 v18, v17
	v_mul_f32_e32 v17, 0xbfb8aa3b, v13
	v_exp_f32_e32 v17, v17
	v_add_f32_e32 v16, 1.0, v16
	v_rcp_f32_e32 v16, v16
	v_add_f32_e32 v17, 1.0, v17
	v_rcp_f32_e32 v17, v17
	s_nop 0
	v_pk_mul_f32 v[12:13], v[12:13], v[16:17]
	s_nop 0
	v_pk_mul_f32 v[8:9], v[12:13], v[8:9]
	v_mul_f32_e32 v12, 0xbfb8aa3b, v5
	v_exp_f32_e32 v12, v12
	s_nop 0
	v_add_f32_e32 v12, 1.0, v12
	v_rcp_f32_e32 v19, v12
	s_nop 0
	v_pk_mul_f32 v[4:5], v[4:5], v[18:19]
	s_nop 0
	v_pk_mul_f32 v[4:5], v[4:5], v[0:1]
	v_mul_f32_e32 v1, 0xbfb8aa3b, v6
	v_exp_f32_e32 v1, v1
	v_mul_f32_e32 v0, 0xbfb8aa3b, v14
	v_exp_f32_e32 v0, v0
	v_add_f32_e32 v1, 1.0, v1
	v_rcp_f32_e32 v12, v1
	v_mul_f32_e32 v1, 0xbfb8aa3b, v15
	v_exp_f32_e32 v1, v1
	v_add_f32_e32 v0, 1.0, v0
	v_rcp_f32_e32 v0, v0
	v_add_f32_e32 v1, 1.0, v1
	v_rcp_f32_e32 v1, v1
	s_nop 0
	v_pk_mul_f32 v[0:1], v[14:15], v[0:1]
	s_nop 0
	v_pk_mul_f32 v[10:11], v[0:1], v[10:11]
	v_mul_f32_e32 v0, 0xbfb8aa3b, v7
	v_exp_f32_e32 v0, v0
	s_nop 0
	v_add_f32_e32 v0, 1.0, v0
	v_rcp_f32_e32 v13, v0
	s_nop 0
	v_pk_mul_f32 v[0:1], v[6:7], v[12:13]
	v_add_u32_e32 v12, 0xb0, v143
	v_pk_mul_f32 v[6:7], v[0:1], v[2:3]
	v_cvt_pk_bf16_f32 v2, v4, v5
	v_mad_i64_i32 v[4:5], s[26:27], v12, s34, v[112:113]
	v_lshl_add_u64 v[4:5], v[4:5], 0, s[88:89]
	v_lshl_add_u64 v[4:5], v[4:5], 0, s[28:29]
	v_cvt_pk_bf16_f32 v0, v8, v9
	v_cvt_pk_bf16_f32 v1, v10, v11
	v_cvt_pk_bf16_f32 v3, v6, v7
	v_lshl_add_u64 v[4:5], v[4:5], 0, v[208:209]
	s_mov_b32 s88, s44
	s_mov_b64 s[28:29], s[64:65]
	s_mov_b64 s[26:27], s[48:49]
	global_store_dwordx4 v[4:5], v[0:3], off
	s_cbranch_vccz .LBB0_27
	s_waitcnt vmcnt(0)
	s_cmpk_gt_u32 s30, 0xff
	s_mov_b32 s89, 0xc000
	s_mov_b64 s[34:35], 0
	s_cbranch_scc1 .LBB0_34
	s_barrier

; #define PG8_STAGE(bufoff, gbase, voff) do { _Pragma("unroll") for (int _i = 0; _i < 2; ++_i) \
;         __builtin_amdgcn_global_load_lds((const unsigned*)((const char*)(gbase) + (voff)[_i]), (LAS unsigned*)(lds + (bufoff) + ldsw + _i * 8192), 16, 0, 0); } while (0)
; #define PG8_LDA(dst, b, h) do { _Pragma("unroll") for (int m = 0; m < 4; ++m) _Pragma("unroll") for (int k = 0; k < 2; ++k) dst[m][k] = *(const LAS bf16x8*)(lds + PG8_SA(b, h) + aoff + m * 2048 + k * 1024); } while (0)
; #define PG8_LDB(dst, b, h) do { _Pragma("unroll") for (int n = 0; n < 2; ++n) _Pragma("unroll") for (int k = 0; k < 2; ++k) dst[n][k] = *(const LAS bf16x8*)(lds + PG8_SB(b, h) + boff + n * 2048 + k * 1024); } while (0)
; #define PG8_MMA(ai, bj, At, Bt) do { __builtin_amdgcn_s_setprio(1); _Pragma("unroll") for (int m = 0; m < 4; ++m) _Pragma("unroll") for (int n = 0; n < 2; ++n) _Pragma("unroll") for (int k = 0; k < 2; ++k) \
;         acc[ai][bj][m][n] = __builtin_amdgcn_mfma_f32_16x16x32_bf16(Bt[n][k], At[m][k], acc[ai][bj][m][n], 0, 0, 0); __builtin_amdgcn_s_setprio(0); } while (0)
; template <class Epi>
; __device__ __forceinline__ void gemm_phase(LAS unsigned char* lds, const Gemm g, const Epi& E) {
;     ...
;         for (int t = 0; t < nt; t += 2) {
;             const bool last = (t == nt - 2);
;             const char* a1 = cA + (size_t)(t + 1) * kstep;
;             const char* a2 = last ? nA : cA + (size_t)(t + 2) * kstep; const char* b2 = last ? nB : cB + (size_t)(t + 2) * kstep;
;             const char* a3 = a2 + kstep; const char* b3 = b2 + kstep;
;             PG8_LDB(B0, 0, 0); PG8_SCHED; PG8_LDA(At, 0, 0); PG8_STAGE(PG8_SA(1, 1), a1 + hstep, voffA);
;             PG8_WAIT_L(8); PG8_BAR; PG8_WAIT_L(0); PG8_MMA(0, 0, At, B0); PG8_BAR; PG8_SCHED;
;             PG8_LDB(B1, 0, 1); PG8_STAGE(PG8_SB(0, 0), b2, voffB);
;             PG8_BAR; PG8_WAIT_L(0); PG8_MMA(0, 1, At, B1); PG8_BAR;
;             PG8_LDA(At, 0, 1); PG8_STAGE(PG8_SA(0, 0), a2, voffA);
;             PG8_BAR; PG8_WAIT_L(0); PG8_MMA(1, 0, At, B0); PG8_BAR; PG8_SCHED;
;             PG8_STAGE(PG8_SB(0, 1), b2 + hstep, voffB);
;             PG8_WAIT_V(6); PG8_BAR; PG8_MMA(1, 1, At, B1); PG8_BAR;
;             PG8_LDB(B0, 1, 0); PG8_SCHED; PG8_LDA(At, 1, 0); PG8_STAGE(PG8_SA(0, 1), a2 + hstep, voffA);
;             PG8_WAIT_L(8); PG8_BAR; PG8_WAIT_L(0); PG8_MMA(0, 0, At, B0); PG8_BAR; PG8_SCHED;
.LBB0_120:
	s_add_u32 s28, s26, 0xfff80080
	s_addc_u32 s29, s27, -1
	s_add_i32 s34, 0, 0x10000
	v_add_u32_e32 v92, s34, v174
	ds_read_b128 v[72:75], v92
	ds_read_b128 v[76:79], v92 offset:1024
	ds_read_b128 v[84:87], v92 offset:2048
	ds_read_b128 v[92:95], v92 offset:3072
	s_cmp_eq_u32 vcc_lo, 28
	s_cselect_b32 s37, s38, s29
	s_cselect_b32 s36, s39, s28
	s_cselect_b32 s29, s43, s97
	s_cselect_b32 s28, s49, s65
	s_add_i32 m0, s68, 0xc000
	ds_read_b128 v[144:147], v175
	ds_read_b128 v[148:151], v175 offset:1024
	ds_read_b128 v[164:167], v175 offset:2048
	ds_read_b128 v[168:171], v175 offset:3072
	ds_read_b128 v[178:181], v175 offset:4096
	ds_read_b128 v[182:185], v175 offset:5120
	ds_read_b128 v[186:189], v175 offset:6144
	ds_read_b128 v[190:193], v175 offset:7168
	global_load_lds_dwordx4 v160, s[26:27]
	s_add_i32 m0, s68, 0xe000
	s_nop 0
	global_load_lds_dwordx4 v162, s[26:27]
	s_waitcnt lgkmcnt(8)
	s_setprio 1
	s_barrier
	s_waitcnt lgkmcnt(0)
	v_mfma_f32_16x16x32_bf16 v[140:143], v[72:75], v[144:147], v[140:143]
	v_mfma_f32_16x16x32_bf16 v[136:139], v[84:87], v[144:147], v[136:139]
	v_mfma_f32_16x16x32_bf16 v[124:127], v[72:75], v[164:167], v[124:127]
	v_mfma_f32_16x16x32_bf16 v[120:123], v[84:87], v[164:167], v[120:123]
	v_mfma_f32_16x16x32_bf16 v[108:111], v[72:75], v[178:181], v[108:111]
	v_mfma_f32_16x16x32_bf16 v[104:107], v[84:87], v[178:181], v[104:107]
	v_mfma_f32_16x16x32_bf16 v[88:91], v[72:75], v[186:189], v[88:91]
	v_mfma_f32_16x16x32_bf16 v[80:83], v[84:87], v[186:189], v[80:83]
	v_mfma_f32_16x16x32_bf16 v[140:143], v[76:79], v[148:151], v[140:143]
	v_mfma_f32_16x16x32_bf16 v[136:139], v[92:95], v[148:151], v[136:139]
	v_mfma_f32_16x16x32_bf16 v[124:127], v[76:79], v[168:171], v[124:127]
	v_mfma_f32_16x16x32_bf16 v[120:123], v[92:95], v[168:171], v[120:123]
	v_mfma_f32_16x16x32_bf16 v[108:111], v[76:79], v[182:185], v[108:111]
	v_mfma_f32_16x16x32_bf16 v[104:107], v[92:95], v[182:185], v[104:107]
	v_mfma_f32_16x16x32_bf16 v[88:91], v[76:79], v[190:193], v[88:91]
	v_mfma_f32_16x16x32_bf16 v[80:83], v[92:95], v[190:193], v[80:83]
	s_setprio 0
	s_barrier
	s_add_i32 s46, 0, 0x14000
	v_add_u32_e32 v172, s46, v174
	s_add_i32 s34, s34, s31
	ds_read_b128 v[194:197], v172
	ds_read_b128 v[198:201], v172 offset:1024
	ds_read_b128 v[202:205], v172 offset:2048
	ds_read_b128 v[228:231], v172 offset:3072
	s_mov_b32 m0, s34
	s_nop 0
	global_load_lds_dwordx4 v208, s[28:29]
	s_add_i32 m0, s34, 0x2000
	s_nop 0
	global_load_lds_dwordx4 v156, s[28:29]
	s_setprio 1
	s_barrier
	s_waitcnt lgkmcnt(0)
	v_mfma_f32_16x16x32_bf16 v[132:135], v[194:197], v[144:147], v[132:135]
	v_mfma_f32_16x16x32_bf16 v[128:131], v[202:205], v[144:147], v[128:131]
	v_mfma_f32_16x16x32_bf16 v[116:119], v[194:197], v[164:167], v[116:119]
	v_mfma_f32_16x16x32_bf16 v[112:115], v[202:205], v[164:167], v[112:115]
	v_mfma_f32_16x16x32_bf16 v[100:103], v[194:197], v[178:181], v[100:103]
	v_mfma_f32_16x16x32_bf16 v[96:99], v[202:205], v[178:181], v[96:99]
	v_mfma_f32_16x16x32_bf16 v[68:71], v[194:197], v[186:189], v[68:71]
	v_mfma_f32_16x16x32_bf16 v[64:67], v[202:205], v[186:189], v[64:67]
	v_mfma_f32_16x16x32_bf16 v[132:135], v[198:201], v[148:151], v[132:135]
	v_mfma_f32_16x16x32_bf16 v[128:131], v[228:231], v[148:151], v[128:131]
	v_mfma_f32_16x16x32_bf16 v[116:119], v[198:201], v[168:171], v[116:119]
	v_mfma_f32_16x16x32_bf16 v[112:115], v[228:231], v[168:171], v[112:115]
	v_mfma_f32_16x16x32_bf16 v[100:103], v[198:201], v[182:185], v[100:103]
	v_mfma_f32_16x16x32_bf16 v[96:99], v[228:231], v[182:185], v[96:99]
	v_mfma_f32_16x16x32_bf16 v[68:71], v[198:201], v[190:193], v[68:71]
	v_mfma_f32_16x16x32_bf16 v[64:67], v[228:231], v[190:193], v[64:67]
	s_setprio 0
	s_mov_b32 m0, s68
	s_barrier
	ds_read_b128 v[144:147], v175 offset:16384
	ds_read_b128 v[148:151], v175 offset:17408
	ds_read_b128 v[164:167], v175 offset:18432
	ds_read_b128 v[168:171], v175 offset:19456
	ds_read_b128 v[178:181], v175 offset:20480
	ds_read_b128 v[182:185], v175 offset:21504
	ds_read_b128 v[186:189], v175 offset:22528
	ds_read_b128 v[190:193], v175 offset:23552
	global_load_lds_dwordx4 v152, s[36:37]
	s_mov_b32 m0, s69
	s_nop 0
	global_load_lds_dwordx4 v154, s[36:37]
	s_setprio 1
	s_barrier
	s_waitcnt lgkmcnt(0)
	v_mfma_f32_16x16x32_bf16 v[60:63], v[72:75], v[144:147], v[60:63]
	v_mfma_f32_16x16x32_bf16 v[56:59], v[84:87], v[144:147], v[56:59]
	v_mfma_f32_16x16x32_bf16 v[44:47], v[72:75], v[164:167], v[44:47]
	v_mfma_f32_16x16x32_bf16 v[40:43], v[84:87], v[164:167], v[40:43]
	v_mfma_f32_16x16x32_bf16 v[28:31], v[72:75], v[178:181], v[28:31]
	v_mfma_f32_16x16x32_bf16 v[24:27], v[84:87], v[178:181], v[24:27]
	v_mfma_f32_16x16x32_bf16 v[12:15], v[72:75], v[186:189], v[12:15]
	v_mfma_f32_16x16x32_bf16 v[8:11], v[84:87], v[186:189], v[8:11]
	v_mfma_f32_16x16x32_bf16 v[60:63], v[76:79], v[148:151], v[60:63]
	v_mfma_f32_16x16x32_bf16 v[56:59], v[92:95], v[148:151], v[56:59]
	v_mfma_f32_16x16x32_bf16 v[44:47], v[76:79], v[168:171], v[44:47]
	v_mfma_f32_16x16x32_bf16 v[40:43], v[92:95], v[168:171], v[40:43]
	v_mfma_f32_16x16x32_bf16 v[28:31], v[76:79], v[182:185], v[28:31]
	v_mfma_f32_16x16x32_bf16 v[24:27], v[92:95], v[182:185], v[24:27]
	v_mfma_f32_16x16x32_bf16 v[12:15], v[76:79], v[190:193], v[12:15]
	v_mfma_f32_16x16x32_bf16 v[8:11], v[92:95], v[190:193], v[8:11]
	s_setprio 0
	s_barrier
	s_add_u32 s34, s28, 0x80000
	s_addc_u32 s35, s29, 0
	s_add_i32 s46, s46, s31
	s_mov_b32 m0, s46
	s_nop 0
	global_load_lds_dwordx4 v208, s[34:35]
	s_add_i32 m0, s46, 0x2000
	s_nop 0
	global_load_lds_dwordx4 v156, s[34:35]
	s_waitcnt vmcnt(6)
	s_setprio 1
	s_barrier
; #define PG8_STAGE(bufoff, gbase, voff) do { _Pragma("unroll") for (int _i = 0; _i < 2; ++_i) \
;         __builtin_amdgcn_global_load_lds((const unsigned*)((const char*)(gbase) + (voff)[_i]), (LAS unsigned*)(lds + (bufoff) + ldsw + _i * 8192), 16, 0, 0); } while (0)
; #define PG8_LDA(dst, b, h) do { _Pragma("unroll") for (int m = 0; m < 4; ++m) _Pragma("unroll") for (int k = 0; k < 2; ++k) dst[m][k] = *(const LAS bf16x8*)(lds + PG8_SA(b, h) + aoff + m * 2048 + k * 1024); } while (0)
; #define PG8_LDB(dst, b, h) do { _Pragma("unroll") for (int n = 0; n < 2; ++n) _Pragma("unroll") for (int k = 0; k < 2; ++k) dst[n][k] = *(const LAS bf16x8*)(lds + PG8_SB(b, h) + boff + n * 2048 + k * 1024); } while (0)
; #define PG8_MMA(ai, bj, At, Bt) do { __builtin_amdgcn_s_setprio(1); _Pragma("unroll") for (int m = 0; m < 4; ++m) _Pragma("unroll") for (int n = 0; n < 2; ++n) _Pragma("unroll") for (int k = 0; k < 2; ++k) \
;         acc[ai][bj][m][n] = __builtin_amdgcn_mfma_f32_16x16x32_bf16(Bt[n][k], At[m][k], acc[ai][bj][m][n], 0, 0, 0); __builtin_amdgcn_s_setprio(0); } while (0)
; #define PG8_WAIT_V(n) asm volatile("s_waitcnt vmcnt(" #n ")" ::: "memory")
; #define PG8_WAIT_L(n) asm volatile("s_waitcnt lgkmcnt(" #n ")" ::: "memory")
; #define PG8_BAR __builtin_amdgcn_s_barrier()
; #define PG8_SCHED __builtin_amdgcn_sched_barrier(0)
; template <class Epi>
; __device__ __forceinline__ void gemm_phase(LAS unsigned char* lds, const Gemm g, const Epi& E) {
;     ...
;             PG8_WAIT_V(6); PG8_BAR; PG8_MMA(1, 1, At, B1); PG8_BAR;
;             PG8_LDB(B0, 1, 0); PG8_SCHED; PG8_LDA(At, 1, 0); PG8_STAGE(PG8_SA(0, 1), a2 + hstep, voffA);
;             PG8_WAIT_L(8); PG8_BAR; PG8_WAIT_L(0); PG8_MMA(0, 0, At, B0); PG8_BAR; PG8_SCHED;
;             PG8_LDB(B1, 1, 1); PG8_STAGE(PG8_SB(1, 0), b3, voffB);
;             PG8_BAR; PG8_WAIT_L(0); PG8_MMA(0, 1, At, B1); PG8_BAR;
;             PG8_LDA(At, 1, 1); PG8_STAGE(PG8_SA(1, 0), a3, voffA);
;             PG8_BAR; PG8_WAIT_L(0); PG8_MMA(1, 0, At, B0); PG8_BAR; PG8_SCHED;
;             PG8_STAGE(PG8_SB(1, 1), b3 + hstep, voffB);
;             PG8_WAIT_V(6); PG8_BAR; PG8_MMA(1, 1, At, B1); PG8_BAR;
	v_mfma_f32_16x16x32_bf16 v[52:55], v[194:197], v[144:147], v[52:55]
	v_mfma_f32_16x16x32_bf16 v[48:51], v[202:205], v[144:147], v[48:51]
	v_mfma_f32_16x16x32_bf16 v[36:39], v[194:197], v[164:167], v[36:39]
	v_mfma_f32_16x16x32_bf16 v[32:35], v[202:205], v[164:167], v[32:35]
	v_mfma_f32_16x16x32_bf16 v[20:23], v[194:197], v[178:181], v[20:23]
	v_mfma_f32_16x16x32_bf16 v[16:19], v[202:205], v[178:181], v[16:19]
	v_mfma_f32_16x16x32_bf16 v[4:7], v[194:197], v[186:189], v[4:7]
	v_mfma_f32_16x16x32_bf16 v[0:3], v[202:205], v[186:189], v[0:3]
	v_mfma_f32_16x16x32_bf16 v[52:55], v[198:201], v[148:151], v[52:55]
	v_mfma_f32_16x16x32_bf16 v[48:51], v[228:231], v[148:151], v[48:51]
	v_mfma_f32_16x16x32_bf16 v[36:39], v[198:201], v[168:171], v[36:39]
	v_mfma_f32_16x16x32_bf16 v[32:35], v[228:231], v[168:171], v[32:35]
	v_mfma_f32_16x16x32_bf16 v[20:23], v[198:201], v[182:185], v[20:23]
	v_mfma_f32_16x16x32_bf16 v[16:19], v[228:231], v[182:185], v[16:19]
	v_mfma_f32_16x16x32_bf16 v[4:7], v[198:201], v[190:193], v[4:7]
	v_mfma_f32_16x16x32_bf16 v[0:3], v[228:231], v[190:193], v[0:3]
	s_setprio 0
	s_add_i32 s46, 0, 0x18000
	v_add_u32_e32 v92, s46, v174
	s_barrier
	ds_read_b128 v[72:75], v92
	ds_read_b128 v[76:79], v92 offset:1024
	ds_read_b128 v[84:87], v92 offset:2048
	ds_read_b128 v[92:95], v92 offset:3072
	s_add_u32 s34, s36, 0x80000
	s_addc_u32 s35, s37, 0
	s_mov_b32 m0, s70
	ds_read_b128 v[144:147], v175 offset:32768
	ds_read_b128 v[148:151], v175 offset:33792
	ds_read_b128 v[164:167], v175 offset:34816
	ds_read_b128 v[168:171], v175 offset:35840
	ds_read_b128 v[178:181], v175 offset:36864
	ds_read_b128 v[182:185], v175 offset:37888
	ds_read_b128 v[186:189], v175 offset:38912
	ds_read_b128 v[190:193], v175 offset:39936
	global_load_lds_dwordx4 v152, s[34:35]
	s_mov_b32 m0, s71
	s_nop 0
	global_load_lds_dwordx4 v154, s[34:35]
	s_waitcnt lgkmcnt(8)
	s_setprio 1
	s_barrier
	s_waitcnt lgkmcnt(0)
	v_mfma_f32_16x16x32_bf16 v[140:143], v[72:75], v[144:147], v[140:143]
	v_mfma_f32_16x16x32_bf16 v[136:139], v[84:87], v[144:147], v[136:139]
	v_mfma_f32_16x16x32_bf16 v[124:127], v[72:75], v[164:167], v[124:127]
	v_mfma_f32_16x16x32_bf16 v[120:123], v[84:87], v[164:167], v[120:123]
	v_mfma_f32_16x16x32_bf16 v[108:111], v[72:75], v[178:181], v[108:111]
	v_mfma_f32_16x16x32_bf16 v[104:107], v[84:87], v[178:181], v[104:107]
	v_mfma_f32_16x16x32_bf16 v[88:91], v[72:75], v[186:189], v[88:91]
	v_mfma_f32_16x16x32_bf16 v[80:83], v[84:87], v[186:189], v[80:83]
	v_mfma_f32_16x16x32_bf16 v[140:143], v[76:79], v[148:151], v[140:143]
	v_mfma_f32_16x16x32_bf16 v[136:139], v[92:95], v[148:151], v[136:139]
	v_mfma_f32_16x16x32_bf16 v[124:127], v[76:79], v[168:171], v[124:127]
	v_mfma_f32_16x16x32_bf16 v[120:123], v[92:95], v[168:171], v[120:123]
	v_mfma_f32_16x16x32_bf16 v[108:111], v[76:79], v[182:185], v[108:111]
	v_mfma_f32_16x16x32_bf16 v[104:107], v[92:95], v[182:185], v[104:107]
	v_mfma_f32_16x16x32_bf16 v[88:91], v[76:79], v[190:193], v[88:91]
	v_mfma_f32_16x16x32_bf16 v[80:83], v[92:95], v[190:193], v[80:83]
	s_setprio 0
	s_barrier
	s_add_i32 s34, 0, 0x1c000
	s_add_i32 s35, s46, s31
	v_add_u32_e32 v177, s34, v174
	s_mov_b32 m0, s35
	ds_read_b128 v[194:197], v177
	ds_read_b128 v[198:201], v177 offset:1024
	ds_read_b128 v[202:205], v177 offset:2048
	ds_read_b128 v[228:231], v177 offset:3072
	s_add_u32 s98, s28, 0x80
	s_addc_u32 s99, s29, 0
	global_load_lds_dwordx4 v208, s[98:99]
	s_add_i32 m0, s35, 0x2000
	s_add_u32 s100, s28, 0x80
	s_addc_u32 s101, s29, 0
	global_load_lds_dwordx4 v156, s[100:101]
	s_setprio 1
	s_barrier
	s_waitcnt lgkmcnt(0)
	v_mfma_f32_16x16x32_bf16 v[132:135], v[194:197], v[144:147], v[132:135]
	v_mfma_f32_16x16x32_bf16 v[128:131], v[202:205], v[144:147], v[128:131]
	v_mfma_f32_16x16x32_bf16 v[116:119], v[194:197], v[164:167], v[116:119]
	v_mfma_f32_16x16x32_bf16 v[112:115], v[202:205], v[164:167], v[112:115]
	v_mfma_f32_16x16x32_bf16 v[100:103], v[194:197], v[178:181], v[100:103]
	v_mfma_f32_16x16x32_bf16 v[96:99], v[202:205], v[178:181], v[96:99]
	v_mfma_f32_16x16x32_bf16 v[68:71], v[194:197], v[186:189], v[68:71]
	v_mfma_f32_16x16x32_bf16 v[64:67], v[202:205], v[186:189], v[64:67]
	v_mfma_f32_16x16x32_bf16 v[132:135], v[198:201], v[148:151], v[132:135]
	v_mfma_f32_16x16x32_bf16 v[128:131], v[228:231], v[148:151], v[128:131]
	v_mfma_f32_16x16x32_bf16 v[116:119], v[198:201], v[168:171], v[116:119]
	v_mfma_f32_16x16x32_bf16 v[112:115], v[228:231], v[168:171], v[112:115]
	v_mfma_f32_16x16x32_bf16 v[100:103], v[198:201], v[182:185], v[100:103]
	v_mfma_f32_16x16x32_bf16 v[96:99], v[228:231], v[182:185], v[96:99]
	v_mfma_f32_16x16x32_bf16 v[68:71], v[198:201], v[190:193], v[68:71]
	v_mfma_f32_16x16x32_bf16 v[64:67], v[228:231], v[190:193], v[64:67]
	s_setprio 0
	s_mov_b32 m0, s78
	s_barrier
	ds_read_b128 v[144:147], v175 offset:49152
	ds_read_b128 v[148:151], v175 offset:50176
	ds_read_b128 v[164:167], v175 offset:51200
	ds_read_b128 v[168:171], v175 offset:52224
	ds_read_b128 v[178:181], v175 offset:53248
	ds_read_b128 v[182:185], v175 offset:54272
	ds_read_b128 v[186:189], v175 offset:55296
	ds_read_b128 v[190:193], v175 offset:56320
	s_add_u32 s98, s36, 0x80
	s_addc_u32 s99, s37, 0
	global_load_lds_dwordx4 v152, s[98:99]
	s_mov_b32 m0, s79
	s_add_u32 s100, s36, 0x80
	s_addc_u32 s101, s37, 0
	global_load_lds_dwordx4 v154, s[100:101]
	s_setprio 1
	s_barrier
; __device__ __forceinline__ float bflo(unsigned w) { return __uint_as_float(w << 16); }
; __device__ __forceinline__ float bfhi(unsigned w) { return __uint_as_float(w & 0xffff0000u); }
; __device__ __forceinline__ u32x4 pack8u(f32x4 a, f32x4 b) { u32x4 w = {cvt_pk_bf16(a[0], a[1]), cvt_pk_bf16(a[2], a[3]), cvt_pk_bf16(b[0], b[1]), cvt_pk_bf16(b[2], b[3])}; return w; }
; #define PG8_STAGE(bufoff, gbase, voff) do { _Pragma("unroll") for (int _i = 0; _i < 2; ++_i) \
;         __builtin_amdgcn_global_load_lds((const unsigned*)((const char*)(gbase) + (voff)[_i]), (LAS unsigned*)(lds + (bufoff) + ldsw + _i * 8192), 16, 0, 0); } while (0)
; template <class Epi>
; __device__ __forceinline__ void gemm_phase(LAS unsigned char* lds, const Gemm g, const Epi& E) {
;     ...
;             PG8_BAR; PG8_WAIT_L(0); PG8_MMA(0, 1, At, B1); PG8_BAR;
;             PG8_LDA(At, 1, 1); PG8_STAGE(PG8_SA(1, 0), a3, voffA);
;             PG8_BAR; PG8_WAIT_L(0); PG8_MMA(1, 0, At, B0); PG8_BAR; PG8_SCHED;
;             PG8_STAGE(PG8_SB(1, 1), b3 + hstep, voffB);
;             PG8_WAIT_V(6); PG8_BAR; PG8_MMA(1, 1, At, B1); PG8_BAR;
;     __device__ __forceinline__ void operator()(const AccT& acc, const Unit& u, int wr, int wc, int fr, int fq) const {
;         const int b = (u.pm * 256) / SEQ;
;         f32x4 gt[2][2];
; #pragma unroll
;         for (int bj = 0; bj < 2; ++bj)
; #pragma unroll
;             for (int n = 0; n < 2; ++n) gt[bj][n] = *(const f32x4*)(GT + (size_t)b * 6 * D + u.pn * 256 + bj * 128 + wc * 32 + fq * 8 + 4 * n);
; #pragma unroll
;         for (int ai = 0; ai < 2; ++ai)
; #pragma unroll
;             for (int m = 0; m < 4; ++m) {
;                 const int row = u.pm * 256 + ai * 128 + wr * 64 + m * 16 + fr;
; #pragma unroll
;                 for (int bj = 0; bj < 2; ++bj) {
;                     const size_t off = (size_t)row * D + u.pn * 256 + bj * 128 + wc * 32 + fq * 8;
;                     f32x4 x0, x1;
;                     if (XINF) { x0 = *(const f32x4*)(XINF + off); x1 = *(const f32x4*)(XINF + off + 4); }
;                     else { const u32x4 w = *(const u32x4*)(XIN16 + off); x0 = (f32x4){bflo(w[0]), bfhi(w[0]), bflo(w[1]), bfhi(w[1])}; x1 = (f32x4){bflo(w[2]), bfhi(w[2]), bflo(w[3]), bfhi(w[3])}; }
;                     *(u32x4*)(XOUT + off) = pack8u(x0 + gt[bj][0] * acc[ai][bj][m][0], x1 + gt[bj][1] * acc[ai][bj][m][1]);
	s_waitcnt lgkmcnt(0)
	v_mfma_f32_16x16x32_bf16 v[60:63], v[72:75], v[144:147], v[60:63]
	v_mfma_f32_16x16x32_bf16 v[56:59], v[84:87], v[144:147], v[56:59]
	v_mfma_f32_16x16x32_bf16 v[44:47], v[72:75], v[164:167], v[44:47]
	v_mfma_f32_16x16x32_bf16 v[40:43], v[84:87], v[164:167], v[40:43]
	v_mfma_f32_16x16x32_bf16 v[28:31], v[72:75], v[178:181], v[28:31]
	v_mfma_f32_16x16x32_bf16 v[24:27], v[84:87], v[178:181], v[24:27]
	v_mfma_f32_16x16x32_bf16 v[12:15], v[72:75], v[186:189], v[12:15]
	v_mfma_f32_16x16x32_bf16 v[8:11], v[84:87], v[186:189], v[8:11]
	v_mfma_f32_16x16x32_bf16 v[60:63], v[76:79], v[148:151], v[60:63]
	v_mfma_f32_16x16x32_bf16 v[56:59], v[92:95], v[148:151], v[56:59]
	v_mfma_f32_16x16x32_bf16 v[44:47], v[76:79], v[168:171], v[44:47]
	v_mfma_f32_16x16x32_bf16 v[40:43], v[92:95], v[168:171], v[40:43]
	v_mfma_f32_16x16x32_bf16 v[28:31], v[76:79], v[182:185], v[28:31]
	v_mfma_f32_16x16x32_bf16 v[24:27], v[92:95], v[182:185], v[24:27]
	v_mfma_f32_16x16x32_bf16 v[12:15], v[76:79], v[190:193], v[12:15]
	v_mfma_f32_16x16x32_bf16 v[8:11], v[92:95], v[190:193], v[8:11]
	s_setprio 0
	s_barrier
	s_add_u32 s28, s28, 0x80080
	s_addc_u32 s29, s29, 0
	s_add_i32 s34, s34, s31
	s_mov_b32 m0, s34
	s_nop 0
	global_load_lds_dwordx4 v208, s[28:29]
	s_add_i32 m0, s34, 0x2000
	s_nop 0
	global_load_lds_dwordx4 v156, s[28:29]
	s_waitcnt vmcnt(6)
	s_setprio 1
	s_barrier
	v_mfma_f32_16x16x32_bf16 v[52:55], v[194:197], v[144:147], v[52:55]
	v_mfma_f32_16x16x32_bf16 v[48:51], v[202:205], v[144:147], v[48:51]
	v_mfma_f32_16x16x32_bf16 v[36:39], v[194:197], v[164:167], v[36:39]
	v_mfma_f32_16x16x32_bf16 v[32:35], v[202:205], v[164:167], v[32:35]
	v_mfma_f32_16x16x32_bf16 v[20:23], v[194:197], v[178:181], v[20:23]
	v_mfma_f32_16x16x32_bf16 v[16:19], v[202:205], v[178:181], v[16:19]
	v_mfma_f32_16x16x32_bf16 v[4:7], v[194:197], v[186:189], v[4:7]
	v_mfma_f32_16x16x32_bf16 v[0:3], v[202:205], v[186:189], v[0:3]
	v_mfma_f32_16x16x32_bf16 v[52:55], v[198:201], v[148:151], v[52:55]
	v_mfma_f32_16x16x32_bf16 v[48:51], v[228:231], v[148:151], v[48:51]
	v_mfma_f32_16x16x32_bf16 v[36:39], v[198:201], v[168:171], v[36:39]
	v_mfma_f32_16x16x32_bf16 v[32:35], v[228:231], v[168:171], v[32:35]
	v_mfma_f32_16x16x32_bf16 v[20:23], v[198:201], v[182:185], v[20:23]
	v_mfma_f32_16x16x32_bf16 v[16:19], v[228:231], v[182:185], v[16:19]
	v_mfma_f32_16x16x32_bf16 v[4:7], v[198:201], v[190:193], v[4:7]
	v_mfma_f32_16x16x32_bf16 v[0:3], v[228:231], v[190:193], v[0:3]
	s_setprio 0
	s_add_i32 vcc_lo, vcc_lo, 2
	s_add_u32 s26, s26, 0x100
	s_addc_u32 s27, s27, 0
	s_add_u32 s65, s65, 0x100
	s_addc_u32 s97, s97, 0
	s_cmp_gt_u32 vcc_lo, 29
	s_barrier
	s_cbranch_scc0 .LBB0_120
	s_ashr_i32 s26, s42, 31
	s_lshr_b32 s26, s26, 29
	s_add_i32 s26, s42, s26
	s_ashr_i32 s26, s26, 3
	s_mul_i32 s26, s26, 6
	s_ashr_i32 s27, s26, 31
	s_lshl_b64 s[26:27], s[26:27], 13
	s_add_u32 s34, s74, s26
	s_addc_u32 s35, s76, s27
	s_lshl_b32 s26, s96, 8
	s_ashr_i32 s27, s26, 31
	s_lshl_b64 s[28:29], s[26:27], 2
	s_add_u32 s28, s34, s28
	s_addc_u32 s29, s35, s29
	s_add_u32 s28, s28, s83
	s_addc_u32 s29, s29, 0
	global_load_dwordx4 v[84:87], v176, s[28:29] offset:16
	global_load_dwordx4 v[92:95], v176, s[28:29]
	global_load_dwordx4 v[72:75], v176, s[28:29] offset:528
	global_load_dwordx4 v[76:79], v176, s[28:29] offset:512
	v_readlane_b32 s34, v255, 22
	v_readlane_b32 s35, v255, 23
	v_lshl_add_u32 v166, s42, 8, v159
	v_or_b32_e32 v167, s26, v158
	v_lshlrev_b32_e32 v164, 2, v167
	v_lshl_add_u32 v164, v166, 13, v164
	v_lshlrev_b32_e32 v165, 1, v167
	v_lshl_add_u32 v165, v166, 12, v165
	s_and_b64 vcc, exec, s[44:45]
	s_cbranch_vccnz .Lepr1_f32
	v_add_u32_e32 v166, 0x0, v165
	global_load_dwordx4 v[168:171], v166, s[34:35] offset:0
	v_add_u32_e32 v166, 0x0, v165
	global_load_dwordx4 v[178:181], v166, s[34:35] offset:256
	v_add_u32_e32 v166, 0x10000, v165
	global_load_dwordx4 v[182:185], v166, s[34:35] offset:0
	v_add_u32_e32 v166, 0x10000, v165
	global_load_dwordx4 v[186:189], v166, s[34:35] offset:256
	v_add_u32_e32 v166, 0x20000, v165
	global_load_dwordx4 v[190:193], v166, s[34:35] offset:0
	v_add_u32_e32 v166, 0x20000, v165
	global_load_dwordx4 v[194:197], v166, s[34:35] offset:256
	v_add_u32_e32 v166, 0x30000, v165
	global_load_dwordx4 v[198:201], v166, s[34:35] offset:0
	v_add_u32_e32 v166, 0x30000, v165
	global_load_dwordx4 v[202:205], v166, s[34:35] offset:256
	v_add_u32_e32 v166, 0x80000, v165
	global_load_dwordx4 v[228:231], v166, s[34:35] offset:0
	s_waitcnt vmcnt(8)
	v_lshlrev_b32_e32 v144, 16, v168
	v_and_b32_e32 v145, 0xffff0000, v168
	v_lshlrev_b32_e32 v146, 16, v169
	v_and_b32_e32 v147, 0xffff0000, v169
	v_lshlrev_b32_e32 v148, 16, v170
	v_and_b32_e32 v149, 0xffff0000, v170
	v_lshlrev_b32_e32 v150, 16, v171
	v_and_b32_e32 v151, 0xffff0000, v171
	v_pk_fma_f32 v[140:141], v[140:141], v[92:93], v[144:145]
	v_pk_fma_f32 v[142:143], v[142:143], v[94:95], v[146:147]
	v_pk_fma_f32 v[136:137], v[136:137], v[84:85], v[148:149]
	v_pk_fma_f32 v[138:139], v[138:139], v[86:87], v[150:151]
	v_cvt_pk_bf16_f32 v140, v140, v141
	v_cvt_pk_bf16_f32 v141, v142, v143
	v_cvt_pk_bf16_f32 v142, v136, v137
	v_cvt_pk_bf16_f32 v143, v138, v139
	v_add_u32_e32 v167, 0x0, v165
	global_store_dwordx4 v167, v[140:143], s[34:35] offset:0
	v_add_u32_e32 v166, 0x80000, v165
	global_load_dwordx4 v[168:171], v166, s[34:35] offset:256
	v_add_u32_e32 v166, 0x90000, v165
	global_load_dwordx4 v[136:139], v166, s[34:35] offset:0
	s_waitcnt vmcnt(10)
; __device__ __forceinline__ float bflo(unsigned w) { return __uint_as_float(w << 16); }
; __device__ __forceinline__ float bfhi(unsigned w) { return __uint_as_float(w & 0xffff0000u); }
; __device__ __forceinline__ u32x4 pack8u(f32x4 a, f32x4 b) { u32x4 w = {cvt_pk_bf16(a[0], a[1]), cvt_pk_bf16(a[2], a[3]), cvt_pk_bf16(b[0], b[1]), cvt_pk_bf16(b[2], b[3])}; return w; }
;     __device__ __forceinline__ void operator()(const AccT& acc, const Unit& u, int wr, int wc, int fr, int fq) const {
;     ...
;                 for (int bj = 0; bj < 2; ++bj) {
;                     const size_t off = (size_t)row * D + u.pn * 256 + bj * 128 + wc * 32 + fq * 8;
;                     f32x4 x0, x1;
;                     if (XINF) { x0 = *(const f32x4*)(XINF + off); x1 = *(const f32x4*)(XINF + off + 4); }
;                     else { const u32x4 w = *(const u32x4*)(XIN16 + off); x0 = (f32x4){bflo(w[0]), bfhi(w[0]), bflo(w[1]), bfhi(w[1])}; x1 = (f32x4){bflo(w[2]), bfhi(w[2]), bflo(w[3]), bfhi(w[3])}; }
;                     *(u32x4*)(XOUT + off) = pack8u(x0 + gt[bj][0] * acc[ai][bj][m][0], x1 + gt[bj][1] * acc[ai][bj][m][1]);
	v_lshlrev_b32_e32 v144, 16, v178
	v_and_b32_e32 v145, 0xffff0000, v178
	v_lshlrev_b32_e32 v146, 16, v179
	v_and_b32_e32 v147, 0xffff0000, v179
	v_lshlrev_b32_e32 v148, 16, v180
	v_and_b32_e32 v149, 0xffff0000, v180
	v_lshlrev_b32_e32 v150, 16, v181
	v_and_b32_e32 v151, 0xffff0000, v181
	v_pk_fma_f32 v[132:133], v[132:133], v[76:77], v[144:145]
	v_pk_fma_f32 v[134:135], v[134:135], v[78:79], v[146:147]
	v_pk_fma_f32 v[128:129], v[128:129], v[72:73], v[148:149]
	v_pk_fma_f32 v[130:131], v[130:131], v[74:75], v[150:151]
	v_cvt_pk_bf16_f32 v132, v132, v133
	v_cvt_pk_bf16_f32 v133, v134, v135
	v_cvt_pk_bf16_f32 v134, v128, v129
	v_cvt_pk_bf16_f32 v135, v130, v131
	v_add_u32_e32 v167, 0x0, v165
	global_store_dwordx4 v167, v[132:135], s[34:35] offset:256
	v_add_u32_e32 v166, 0x90000, v165
	global_load_dwordx4 v[178:181], v166, s[34:35] offset:256
	v_add_u32_e32 v166, 0xa0000, v165
	global_load_dwordx4 v[128:131], v166, s[34:35] offset:0
	s_waitcnt vmcnt(12)
	v_lshlrev_b32_e32 v144, 16, v182
	v_and_b32_e32 v145, 0xffff0000, v182
	v_lshlrev_b32_e32 v146, 16, v183
	v_and_b32_e32 v147, 0xffff0000, v183
	v_lshlrev_b32_e32 v148, 16, v184
	v_and_b32_e32 v149, 0xffff0000, v184
	v_lshlrev_b32_e32 v150, 16, v185
	v_and_b32_e32 v151, 0xffff0000, v185
	v_pk_fma_f32 v[124:125], v[124:125], v[92:93], v[144:145]
	v_pk_fma_f32 v[126:127], v[126:127], v[94:95], v[146:147]
	v_pk_fma_f32 v[120:121], v[120:121], v[84:85], v[148:149]
	v_pk_fma_f32 v[122:123], v[122:123], v[86:87], v[150:151]
	v_cvt_pk_bf16_f32 v124, v124, v125
	v_cvt_pk_bf16_f32 v125, v126, v127
	v_cvt_pk_bf16_f32 v126, v120, v121
	v_cvt_pk_bf16_f32 v127, v122, v123
	v_add_u32_e32 v167, 0x10000, v165
	global_store_dwordx4 v167, v[124:127], s[34:35] offset:0
	v_add_u32_e32 v166, 0xa0000, v165
	global_load_dwordx4 v[182:185], v166, s[34:35] offset:256
	v_add_u32_e32 v166, 0xb0000, v165
	global_load_dwordx4 v[120:123], v166, s[34:35] offset:0
	s_waitcnt vmcnt(14)
	v_lshlrev_b32_e32 v144, 16, v186
	v_and_b32_e32 v145, 0xffff0000, v186
	v_lshlrev_b32_e32 v146, 16, v187
	v_and_b32_e32 v147, 0xffff0000, v187
	v_lshlrev_b32_e32 v148, 16, v188
	v_and_b32_e32 v149, 0xffff0000, v188
	v_lshlrev_b32_e32 v150, 16, v189
	v_and_b32_e32 v151, 0xffff0000, v189
	v_pk_fma_f32 v[116:117], v[116:117], v[76:77], v[144:145]
	v_pk_fma_f32 v[118:119], v[118:119], v[78:79], v[146:147]
	v_pk_fma_f32 v[112:113], v[112:113], v[72:73], v[148:149]
	v_pk_fma_f32 v[114:115], v[114:115], v[74:75], v[150:151]
	v_cvt_pk_bf16_f32 v116, v116, v117
	v_cvt_pk_bf16_f32 v117, v118, v119
	v_cvt_pk_bf16_f32 v118, v112, v113
	v_cvt_pk_bf16_f32 v119, v114, v115
	v_add_u32_e32 v167, 0x10000, v165
	global_store_dwordx4 v167, v[116:119], s[34:35] offset:256
	v_add_u32_e32 v166, 0xb0000, v165
	global_load_dwordx4 v[186:189], v166, s[34:35] offset:256
	s_waitcnt vmcnt(15)
	v_lshlrev_b32_e32 v144, 16, v190
	v_and_b32_e32 v145, 0xffff0000, v190
	v_lshlrev_b32_e32 v146, 16, v191
	v_and_b32_e32 v147, 0xffff0000, v191
	v_lshlrev_b32_e32 v148, 16, v192
	v_and_b32_e32 v149, 0xffff0000, v192
	v_lshlrev_b32_e32 v150, 16, v193
	v_and_b32_e32 v151, 0xffff0000, v193
	v_pk_fma_f32 v[108:109], v[108:109], v[92:93], v[144:145]
	v_pk_fma_f32 v[110:111], v[110:111], v[94:95], v[146:147]
	v_pk_fma_f32 v[104:105], v[104:105], v[84:85], v[148:149]
	v_pk_fma_f32 v[106:107], v[106:107], v[86:87], v[150:151]
	v_cvt_pk_bf16_f32 v108, v108, v109
	v_cvt_pk_bf16_f32 v109, v110, v111
	v_cvt_pk_bf16_f32 v110, v104, v105
	v_cvt_pk_bf16_f32 v111, v106, v107
	v_add_u32_e32 v167, 0x20000, v165
	global_store_dwordx4 v167, v[108:111], s[34:35] offset:0
	s_waitcnt vmcnt(15)
	v_lshlrev_b32_e32 v144, 16, v194
	v_and_b32_e32 v145, 0xffff0000, v194
	v_lshlrev_b32_e32 v146, 16, v195
	v_and_b32_e32 v147, 0xffff0000, v195
	v_lshlrev_b32_e32 v148, 16, v196
	v_and_b32_e32 v149, 0xffff0000, v196
	v_lshlrev_b32_e32 v150, 16, v197
	v_and_b32_e32 v151, 0xffff0000, v197
	v_pk_fma_f32 v[100:101], v[100:101], v[76:77], v[144:145]
	v_pk_fma_f32 v[102:103], v[102:103], v[78:79], v[146:147]
	v_pk_fma_f32 v[96:97], v[96:97], v[72:73], v[148:149]
	v_pk_fma_f32 v[98:99], v[98:99], v[74:75], v[150:151]
	v_cvt_pk_bf16_f32 v100, v100, v101
	v_cvt_pk_bf16_f32 v101, v102, v103
	v_cvt_pk_bf16_f32 v102, v96, v97
	v_cvt_pk_bf16_f32 v103, v98, v99
	v_add_u32_e32 v167, 0x20000, v165
	global_store_dwordx4 v167, v[100:103], s[34:35] offset:256
	s_waitcnt vmcnt(15)
	v_lshlrev_b32_e32 v144, 16, v198
	v_and_b32_e32 v145, 0xffff0000, v198
	v_lshlrev_b32_e32 v146, 16, v199
	v_and_b32_e32 v147, 0xffff0000, v199
	v_lshlrev_b32_e32 v148, 16, v200
	v_and_b32_e32 v149, 0xffff0000, v200
	v_lshlrev_b32_e32 v150, 16, v201
	v_and_b32_e32 v151, 0xffff0000, v201
	v_pk_fma_f32 v[88:89], v[88:89], v[92:93], v[144:145]
	v_pk_fma_f32 v[90:91], v[90:91], v[94:95], v[146:147]
	v_pk_fma_f32 v[80:81], v[80:81], v[84:85], v[148:149]
	v_pk_fma_f32 v[82:83], v[82:83], v[86:87], v[150:151]
	v_cvt_pk_bf16_f32 v88, v88, v89
	v_cvt_pk_bf16_f32 v89, v90, v91
	v_cvt_pk_bf16_f32 v90, v80, v81
	v_cvt_pk_bf16_f32 v91, v82, v83
	v_add_u32_e32 v167, 0x30000, v165
	global_store_dwordx4 v167, v[88:91], s[34:35] offset:0
	s_waitcnt vmcnt(15)
	v_lshlrev_b32_e32 v144, 16, v202
	v_and_b32_e32 v145, 0xffff0000, v202
	v_lshlrev_b32_e32 v146, 16, v203
	v_and_b32_e32 v147, 0xffff0000, v203
	v_lshlrev_b32_e32 v148, 16, v204
	v_and_b32_e32 v149, 0xffff0000, v204
	v_lshlrev_b32_e32 v150, 16, v205
	v_and_b32_e32 v151, 0xffff0000, v205
	v_pk_fma_f32 v[68:69], v[68:69], v[76:77], v[144:145]
	v_pk_fma_f32 v[70:71], v[70:71], v[78:79], v[146:147]
	v_pk_fma_f32 v[64:65], v[64:65], v[72:73], v[148:149]
	v_pk_fma_f32 v[66:67], v[66:67], v[74:75], v[150:151]
	v_cvt_pk_bf16_f32 v68, v68, v69
	v_cvt_pk_bf16_f32 v69, v70, v71
	v_cvt_pk_bf16_f32 v70, v64, v65
	v_cvt_pk_bf16_f32 v71, v66, v67
	v_add_u32_e32 v167, 0x30000, v165
	global_store_dwordx4 v167, v[68:71], s[34:35] offset:256
	s_waitcnt vmcnt(15)
; __device__ __forceinline__ float bflo(unsigned w) { return __uint_as_float(w << 16); }
; __device__ __forceinline__ float bfhi(unsigned w) { return __uint_as_float(w & 0xffff0000u); }
; __device__ __forceinline__ u32x4 pack8u(f32x4 a, f32x4 b) { u32x4 w = {cvt_pk_bf16(a[0], a[1]), cvt_pk_bf16(a[2], a[3]), cvt_pk_bf16(b[0], b[1]), cvt_pk_bf16(b[2], b[3])}; return w; }
;     __device__ __forceinline__ void operator()(const AccT& acc, const Unit& u, int wr, int wc, int fr, int fq) const {
;     ...
;                 for (int bj = 0; bj < 2; ++bj) {
;                     const size_t off = (size_t)row * D + u.pn * 256 + bj * 128 + wc * 32 + fq * 8;
;                     f32x4 x0, x1;
;                     if (XINF) { x0 = *(const f32x4*)(XINF + off); x1 = *(const f32x4*)(XINF + off + 4); }
;                     else { const u32x4 w = *(const u32x4*)(XIN16 + off); x0 = (f32x4){bflo(w[0]), bfhi(w[0]), bflo(w[1]), bfhi(w[1])}; x1 = (f32x4){bflo(w[2]), bfhi(w[2]), bflo(w[3]), bfhi(w[3])}; }
;                     *(u32x4*)(XOUT + off) = pack8u(x0 + gt[bj][0] * acc[ai][bj][m][0], x1 + gt[bj][1] * acc[ai][bj][m][1]);
	v_lshlrev_b32_e32 v144, 16, v228
	v_and_b32_e32 v145, 0xffff0000, v228
	v_lshlrev_b32_e32 v146, 16, v229
	v_and_b32_e32 v147, 0xffff0000, v229
	v_lshlrev_b32_e32 v148, 16, v230
	v_and_b32_e32 v149, 0xffff0000, v230
	v_lshlrev_b32_e32 v150, 16, v231
	v_and_b32_e32 v151, 0xffff0000, v231
	v_pk_fma_f32 v[60:61], v[60:61], v[92:93], v[144:145]
	v_pk_fma_f32 v[62:63], v[62:63], v[94:95], v[146:147]
	v_pk_fma_f32 v[56:57], v[56:57], v[84:85], v[148:149]
	v_pk_fma_f32 v[58:59], v[58:59], v[86:87], v[150:151]
	v_cvt_pk_bf16_f32 v60, v60, v61
	v_cvt_pk_bf16_f32 v61, v62, v63
	v_cvt_pk_bf16_f32 v62, v56, v57
	v_cvt_pk_bf16_f32 v63, v58, v59
	v_add_u32_e32 v167, 0x80000, v165
	global_store_dwordx4 v167, v[60:63], s[34:35] offset:0
	s_waitcnt vmcnt(14)
	v_lshlrev_b32_e32 v144, 16, v168
	v_and_b32_e32 v145, 0xffff0000, v168
	v_lshlrev_b32_e32 v146, 16, v169
	v_and_b32_e32 v147, 0xffff0000, v169
	v_lshlrev_b32_e32 v148, 16, v170
	v_and_b32_e32 v149, 0xffff0000, v170
	v_lshlrev_b32_e32 v150, 16, v171
	v_and_b32_e32 v151, 0xffff0000, v171
	v_pk_fma_f32 v[52:53], v[52:53], v[76:77], v[144:145]
	v_pk_fma_f32 v[54:55], v[54:55], v[78:79], v[146:147]
	v_pk_fma_f32 v[48:49], v[48:49], v[72:73], v[148:149]
	v_pk_fma_f32 v[50:51], v[50:51], v[74:75], v[150:151]
	v_cvt_pk_bf16_f32 v52, v52, v53
	v_cvt_pk_bf16_f32 v53, v54, v55
	v_cvt_pk_bf16_f32 v54, v48, v49
	v_cvt_pk_bf16_f32 v55, v50, v51
	v_add_u32_e32 v167, 0x80000, v165
	global_store_dwordx4 v167, v[52:55], s[34:35] offset:256
	s_waitcnt vmcnt(14)
	v_lshlrev_b32_e32 v144, 16, v136
	v_and_b32_e32 v145, 0xffff0000, v136
	v_lshlrev_b32_e32 v146, 16, v137
	v_and_b32_e32 v147, 0xffff0000, v137
	v_lshlrev_b32_e32 v148, 16, v138
	v_and_b32_e32 v149, 0xffff0000, v138
	v_lshlrev_b32_e32 v150, 16, v139
	v_and_b32_e32 v151, 0xffff0000, v139
	v_pk_fma_f32 v[44:45], v[44:45], v[92:93], v[144:145]
	v_pk_fma_f32 v[46:47], v[46:47], v[94:95], v[146:147]
	v_pk_fma_f32 v[40:41], v[40:41], v[84:85], v[148:149]
	v_pk_fma_f32 v[42:43], v[42:43], v[86:87], v[150:151]
	v_cvt_pk_bf16_f32 v44, v44, v45
	v_cvt_pk_bf16_f32 v45, v46, v47
	v_cvt_pk_bf16_f32 v46, v40, v41
	v_cvt_pk_bf16_f32 v47, v42, v43
	v_add_u32_e32 v167, 0x90000, v165
	global_store_dwordx4 v167, v[44:47], s[34:35] offset:0
	s_waitcnt vmcnt(13)
	v_lshlrev_b32_e32 v144, 16, v178
	v_and_b32_e32 v145, 0xffff0000, v178
	v_lshlrev_b32_e32 v146, 16, v179
	v_and_b32_e32 v147, 0xffff0000, v179
	v_lshlrev_b32_e32 v148, 16, v180
	v_and_b32_e32 v149, 0xffff0000, v180
	v_lshlrev_b32_e32 v150, 16, v181
	v_and_b32_e32 v151, 0xffff0000, v181
	v_pk_fma_f32 v[36:37], v[36:37], v[76:77], v[144:145]
	v_pk_fma_f32 v[38:39], v[38:39], v[78:79], v[146:147]
	v_pk_fma_f32 v[32:33], v[32:33], v[72:73], v[148:149]
	v_pk_fma_f32 v[34:35], v[34:35], v[74:75], v[150:151]
	v_cvt_pk_bf16_f32 v36, v36, v37
	v_cvt_pk_bf16_f32 v37, v38, v39
	v_cvt_pk_bf16_f32 v38, v32, v33
	v_cvt_pk_bf16_f32 v39, v34, v35
	v_add_u32_e32 v167, 0x90000, v165
	global_store_dwordx4 v167, v[36:39], s[34:35] offset:256
	s_waitcnt vmcnt(13)
	v_lshlrev_b32_e32 v144, 16, v128
	v_and_b32_e32 v145, 0xffff0000, v128
	v_lshlrev_b32_e32 v146, 16, v129
	v_and_b32_e32 v147, 0xffff0000, v129
	v_lshlrev_b32_e32 v148, 16, v130
	v_and_b32_e32 v149, 0xffff0000, v130
	v_lshlrev_b32_e32 v150, 16, v131
	v_and_b32_e32 v151, 0xffff0000, v131
	v_pk_fma_f32 v[28:29], v[28:29], v[92:93], v[144:145]
	v_pk_fma_f32 v[30:31], v[30:31], v[94:95], v[146:147]
	v_pk_fma_f32 v[24:25], v[24:25], v[84:85], v[148:149]
	v_pk_fma_f32 v[26:27], v[26:27], v[86:87], v[150:151]
	v_cvt_pk_bf16_f32 v28, v28, v29
	v_cvt_pk_bf16_f32 v29, v30, v31
	v_cvt_pk_bf16_f32 v30, v24, v25
	v_cvt_pk_bf16_f32 v31, v26, v27
	v_add_u32_e32 v167, 0xa0000, v165
	global_store_dwordx4 v167, v[28:31], s[34:35] offset:0
	s_waitcnt vmcnt(12)
	v_lshlrev_b32_e32 v144, 16, v182
	v_and_b32_e32 v145, 0xffff0000, v182
	v_lshlrev_b32_e32 v146, 16, v183
	v_and_b32_e32 v147, 0xffff0000, v183
	v_lshlrev_b32_e32 v148, 16, v184
	v_and_b32_e32 v149, 0xffff0000, v184
	v_lshlrev_b32_e32 v150, 16, v185
	v_and_b32_e32 v151, 0xffff0000, v185
	v_pk_fma_f32 v[20:21], v[20:21], v[76:77], v[144:145]
	v_pk_fma_f32 v[22:23], v[22:23], v[78:79], v[146:147]
	v_pk_fma_f32 v[16:17], v[16:17], v[72:73], v[148:149]
	v_pk_fma_f32 v[18:19], v[18:19], v[74:75], v[150:151]
	v_cvt_pk_bf16_f32 v20, v20, v21
	v_cvt_pk_bf16_f32 v21, v22, v23
	v_cvt_pk_bf16_f32 v22, v16, v17
	v_cvt_pk_bf16_f32 v23, v18, v19
	v_add_u32_e32 v167, 0xa0000, v165
	global_store_dwordx4 v167, v[20:23], s[34:35] offset:256
	s_waitcnt vmcnt(12)
	v_lshlrev_b32_e32 v144, 16, v120
	v_and_b32_e32 v145, 0xffff0000, v120
	v_lshlrev_b32_e32 v146, 16, v121
	v_and_b32_e32 v147, 0xffff0000, v121
	v_lshlrev_b32_e32 v148, 16, v122
	v_and_b32_e32 v149, 0xffff0000, v122
	v_lshlrev_b32_e32 v150, 16, v123
	v_and_b32_e32 v151, 0xffff0000, v123
	v_pk_fma_f32 v[12:13], v[12:13], v[92:93], v[144:145]
	v_pk_fma_f32 v[14:15], v[14:15], v[94:95], v[146:147]
	v_pk_fma_f32 v[8:9], v[8:9], v[84:85], v[148:149]
	v_pk_fma_f32 v[10:11], v[10:11], v[86:87], v[150:151]
	v_cvt_pk_bf16_f32 v12, v12, v13
	v_cvt_pk_bf16_f32 v13, v14, v15
	v_cvt_pk_bf16_f32 v14, v8, v9
	v_cvt_pk_bf16_f32 v15, v10, v11
	v_add_u32_e32 v167, 0xb0000, v165
	global_store_dwordx4 v167, v[12:15], s[34:35] offset:0
	s_waitcnt vmcnt(11)
	v_lshlrev_b32_e32 v144, 16, v186
	v_and_b32_e32 v145, 0xffff0000, v186
	v_lshlrev_b32_e32 v146, 16, v187
	v_and_b32_e32 v147, 0xffff0000, v187
	v_lshlrev_b32_e32 v148, 16, v188
	v_and_b32_e32 v149, 0xffff0000, v188
	v_lshlrev_b32_e32 v150, 16, v189
	v_and_b32_e32 v151, 0xffff0000, v189
	v_pk_fma_f32 v[4:5], v[4:5], v[76:77], v[144:145]
	v_pk_fma_f32 v[6:7], v[6:7], v[78:79], v[146:147]
	v_pk_fma_f32 v[0:1], v[0:1], v[72:73], v[148:149]
	v_pk_fma_f32 v[2:3], v[2:3], v[74:75], v[150:151]
	v_cvt_pk_bf16_f32 v4, v4, v5
	v_cvt_pk_bf16_f32 v5, v6, v7
	v_cvt_pk_bf16_f32 v6, v0, v1
	v_cvt_pk_bf16_f32 v7, v2, v3
	v_add_u32_e32 v167, 0xb0000, v165
	global_store_dwordx4 v167, v[4:7], s[34:35] offset:256
	s_mov_b64 s[42:43], exec
	s_branch .Lepr1_latch

; #define PG8_STAGE(bufoff, gbase, voff) do { _Pragma("unroll") for (int _i = 0; _i < 2; ++_i) \
;         __builtin_amdgcn_global_load_lds((const unsigned*)((const char*)(gbase) + (voff)[_i]), (LAS unsigned*)(lds + (bufoff) + ldsw + _i * 8192), 16, 0, 0); } while (0)
; #define PG8_LDA(dst, b, h) do { _Pragma("unroll") for (int m = 0; m < 4; ++m) _Pragma("unroll") for (int k = 0; k < 2; ++k) dst[m][k] = *(const LAS bf16x8*)(lds + PG8_SA(b, h) + aoff + m * 2048 + k * 1024); } while (0)
; #define PG8_LDB(dst, b, h) do { _Pragma("unroll") for (int n = 0; n < 2; ++n) _Pragma("unroll") for (int k = 0; k < 2; ++k) dst[n][k] = *(const LAS bf16x8*)(lds + PG8_SB(b, h) + boff + n * 2048 + k * 1024); } while (0)
; #define PG8_WAIT_V(n) asm volatile("s_waitcnt vmcnt(" #n ")" ::: "memory")
; #define PG8_WAIT_L(n) asm volatile("s_waitcnt lgkmcnt(" #n ")" ::: "memory")
; #define PG8_BAR __builtin_amdgcn_s_barrier()
; template <class Epi>
; __device__ __forceinline__ void gemm_phase(LAS unsigned char* lds, const Gemm g, const Epi& E) {
;     ...
;         for (int t = 0; t < nt; t += 2) {
;             const bool last = (t == nt - 2);
;             const char* a1 = cA + (size_t)(t + 1) * kstep;
;             const char* a2 = last ? nA : cA + (size_t)(t + 2) * kstep; const char* b2 = last ? nB : cB + (size_t)(t + 2) * kstep;
;             const char* a3 = a2 + kstep; const char* b3 = b2 + kstep;
;             PG8_LDB(B0, 0, 0); PG8_SCHED; PG8_LDA(At, 0, 0); PG8_STAGE(PG8_SA(1, 1), a1 + hstep, voffA);
;             PG8_WAIT_L(8); PG8_BAR; PG8_WAIT_L(0); PG8_MMA(0, 0, At, B0); PG8_BAR; PG8_SCHED;
;             PG8_LDB(B1, 0, 1); PG8_STAGE(PG8_SB(0, 0), b2, voffB);
;             PG8_BAR; PG8_WAIT_L(0); PG8_MMA(0, 1, At, B1); PG8_BAR;
;             PG8_LDA(At, 0, 1); PG8_STAGE(PG8_SA(0, 0), a2, voffA);
;             PG8_BAR; PG8_WAIT_L(0); PG8_MMA(1, 0, At, B0); PG8_BAR; PG8_SCHED;
;             PG8_STAGE(PG8_SB(0, 1), b2 + hstep, voffB);
;             PG8_WAIT_V(6); PG8_BAR; PG8_MMA(1, 1, At, B1); PG8_BAR;
;             PG8_LDB(B0, 1, 0); PG8_SCHED; PG8_LDA(At, 1, 0); PG8_STAGE(PG8_SA(0, 1), a2 + hstep, voffA);
;             PG8_WAIT_L(8); PG8_BAR; PG8_WAIT_L(0); PG8_MMA(0, 0, At, B0); PG8_BAR; PG8_SCHED;
;             PG8_LDB(B1, 1, 1); PG8_STAGE(PG8_SB(1, 0), b3, voffB);
;             PG8_BAR; PG8_WAIT_L(0); PG8_MMA(0, 1, At, B1); PG8_BAR;
.LBB0_211:
	s_add_u32 s28, s26, 0xfffc0080
	s_addc_u32 s29, s27, -1
	s_add_i32 s34, 0, 0x10000
	v_add_u32_e32 v150, s34, v159
	ds_read_b128 v[138:141], v150
	ds_read_b128 v[142:145], v150 offset:1024
	ds_read_b128 v[146:149], v150 offset:2048
	ds_read_b128 v[150:153], v150 offset:3072
	s_cmp_eq_u32 vcc_hi, 12
	s_cselect_b32 s37, s38, s29
	s_cselect_b32 s36, s39, s28
	s_cselect_b32 s29, s43, vcc_lo
	s_cselect_b32 s28, s49, s65
	s_add_i32 m0, s74, 0xc000
	ds_read_b128 v[154:157], v161
	ds_read_b128 v[162:165], v161 offset:1024
	ds_read_b128 v[166:169], v161 offset:2048
	ds_read_b128 v[170:173], v161 offset:3072
	ds_read_b128 v[174:177], v161 offset:4096
	ds_read_b128 v[178:181], v161 offset:5120
	ds_read_b128 v[182:185], v161 offset:6144
	ds_read_b128 v[186:189], v161 offset:7168
	global_load_lds_dwordx4 v134, s[26:27]
	s_add_i32 m0, s74, 0xe000
	s_nop 0
	global_load_lds_dwordx4 v136, s[26:27]
	s_waitcnt lgkmcnt(8)
	s_setprio 1
	s_barrier
	s_waitcnt lgkmcnt(0)
	v_mfma_f32_16x16x32_bf16 v[124:127], v[138:141], v[154:157], v[124:127]
	v_mfma_f32_16x16x32_bf16 v[120:123], v[146:149], v[154:157], v[120:123]
	v_mfma_f32_16x16x32_bf16 v[108:111], v[138:141], v[166:169], v[108:111]
	v_mfma_f32_16x16x32_bf16 v[104:107], v[146:149], v[166:169], v[104:107]
	v_mfma_f32_16x16x32_bf16 v[92:95], v[138:141], v[174:177], v[92:95]
	v_mfma_f32_16x16x32_bf16 v[88:91], v[146:149], v[174:177], v[88:91]
	v_mfma_f32_16x16x32_bf16 v[76:79], v[138:141], v[182:185], v[76:79]
	v_mfma_f32_16x16x32_bf16 v[72:75], v[146:149], v[182:185], v[72:75]
	v_mfma_f32_16x16x32_bf16 v[124:127], v[142:145], v[162:165], v[124:127]
	v_mfma_f32_16x16x32_bf16 v[120:123], v[150:153], v[162:165], v[120:123]
	v_mfma_f32_16x16x32_bf16 v[108:111], v[142:145], v[170:173], v[108:111]
	v_mfma_f32_16x16x32_bf16 v[104:107], v[150:153], v[170:173], v[104:107]
	v_mfma_f32_16x16x32_bf16 v[92:95], v[142:145], v[178:181], v[92:95]
	v_mfma_f32_16x16x32_bf16 v[88:91], v[150:153], v[178:181], v[88:91]
	v_mfma_f32_16x16x32_bf16 v[76:79], v[142:145], v[186:189], v[76:79]
	v_mfma_f32_16x16x32_bf16 v[72:75], v[150:153], v[186:189], v[72:75]
	s_setprio 0
	s_barrier
	s_add_i32 s46, 0, 0x14000
	s_add_i32 s34, s34, s71
	v_add_u32_e32 v202, s46, v159
	s_mov_b32 m0, s34
	ds_read_b128 v[190:193], v202
	ds_read_b128 v[194:197], v202 offset:1024
	ds_read_b128 v[198:201], v202 offset:2048
	ds_read_b128 v[202:205], v202 offset:3072
	global_load_lds_dwordx4 v208, s[28:29]
	s_add_i32 m0, s34, 0x2000
	s_nop 0
	global_load_lds_dwordx4 v132, s[28:29]
	s_setprio 1
	s_barrier
	s_waitcnt lgkmcnt(0)
	v_mfma_f32_16x16x32_bf16 v[116:119], v[190:193], v[154:157], v[116:119]
	v_mfma_f32_16x16x32_bf16 v[112:115], v[198:201], v[154:157], v[112:115]
	v_mfma_f32_16x16x32_bf16 v[100:103], v[190:193], v[166:169], v[100:103]
	v_mfma_f32_16x16x32_bf16 v[96:99], v[198:201], v[166:169], v[96:99]
	v_mfma_f32_16x16x32_bf16 v[84:87], v[190:193], v[174:177], v[84:87]
	v_mfma_f32_16x16x32_bf16 v[80:83], v[198:201], v[174:177], v[80:83]
	v_mfma_f32_16x16x32_bf16 v[68:71], v[190:193], v[182:185], v[68:71]
	v_mfma_f32_16x16x32_bf16 v[64:67], v[198:201], v[182:185], v[64:67]
	v_mfma_f32_16x16x32_bf16 v[116:119], v[194:197], v[162:165], v[116:119]
	v_mfma_f32_16x16x32_bf16 v[112:115], v[202:205], v[162:165], v[112:115]
	v_mfma_f32_16x16x32_bf16 v[100:103], v[194:197], v[170:173], v[100:103]
	v_mfma_f32_16x16x32_bf16 v[96:99], v[202:205], v[170:173], v[96:99]
	v_mfma_f32_16x16x32_bf16 v[84:87], v[194:197], v[178:181], v[84:87]
	v_mfma_f32_16x16x32_bf16 v[80:83], v[202:205], v[178:181], v[80:83]
	v_mfma_f32_16x16x32_bf16 v[68:71], v[194:197], v[186:189], v[68:71]
	v_mfma_f32_16x16x32_bf16 v[64:67], v[202:205], v[186:189], v[64:67]
	s_setprio 0
	s_mov_b32 m0, s74
	s_barrier
	ds_read_b128 v[154:157], v161 offset:16384
	ds_read_b128 v[162:165], v161 offset:17408
	ds_read_b128 v[166:169], v161 offset:18432
	ds_read_b128 v[170:173], v161 offset:19456
	ds_read_b128 v[174:177], v161 offset:20480
	ds_read_b128 v[178:181], v161 offset:21504
	ds_read_b128 v[182:185], v161 offset:22528
	ds_read_b128 v[186:189], v161 offset:23552
	global_load_lds_dwordx4 v128, s[36:37]
	s_mov_b32 m0, s76
	s_nop 0
	global_load_lds_dwordx4 v130, s[36:37]
	s_setprio 1
	s_barrier
	s_waitcnt lgkmcnt(0)
	v_mfma_f32_16x16x32_bf16 v[60:63], v[138:141], v[154:157], v[60:63]
	v_mfma_f32_16x16x32_bf16 v[56:59], v[146:149], v[154:157], v[56:59]
	v_mfma_f32_16x16x32_bf16 v[44:47], v[138:141], v[166:169], v[44:47]
	v_mfma_f32_16x16x32_bf16 v[40:43], v[146:149], v[166:169], v[40:43]
	v_mfma_f32_16x16x32_bf16 v[28:31], v[138:141], v[174:177], v[28:31]
	v_mfma_f32_16x16x32_bf16 v[24:27], v[146:149], v[174:177], v[24:27]
	v_mfma_f32_16x16x32_bf16 v[12:15], v[138:141], v[182:185], v[12:15]
	v_mfma_f32_16x16x32_bf16 v[8:11], v[146:149], v[182:185], v[8:11]
	v_mfma_f32_16x16x32_bf16 v[60:63], v[142:145], v[162:165], v[60:63]
	v_mfma_f32_16x16x32_bf16 v[56:59], v[150:153], v[162:165], v[56:59]
	v_mfma_f32_16x16x32_bf16 v[44:47], v[142:145], v[170:173], v[44:47]
	v_mfma_f32_16x16x32_bf16 v[40:43], v[150:153], v[170:173], v[40:43]
	v_mfma_f32_16x16x32_bf16 v[28:31], v[142:145], v[178:181], v[28:31]
	v_mfma_f32_16x16x32_bf16 v[24:27], v[150:153], v[178:181], v[24:27]
	v_mfma_f32_16x16x32_bf16 v[12:15], v[142:145], v[186:189], v[12:15]
	v_mfma_f32_16x16x32_bf16 v[8:11], v[150:153], v[186:189], v[8:11]
	s_setprio 0
	s_barrier
	s_add_u32 s34, s28, 0x40000
	s_addc_u32 s35, s29, 0
	s_add_i32 s46, s46, s71
	s_mov_b32 m0, s46
	s_nop 0
	global_load_lds_dwordx4 v208, s[34:35]
	s_add_i32 m0, s46, 0x2000
	s_nop 0
	global_load_lds_dwordx4 v132, s[34:35]
	s_waitcnt vmcnt(6)
	s_setprio 1
	s_barrier
; #define PG8_STAGE(bufoff, gbase, voff) do { _Pragma("unroll") for (int _i = 0; _i < 2; ++_i) \
;         __builtin_amdgcn_global_load_lds((const unsigned*)((const char*)(gbase) + (voff)[_i]), (LAS unsigned*)(lds + (bufoff) + ldsw + _i * 8192), 16, 0, 0); } while (0)
; #define PG8_LDA(dst, b, h) do { _Pragma("unroll") for (int m = 0; m < 4; ++m) _Pragma("unroll") for (int k = 0; k < 2; ++k) dst[m][k] = *(const LAS bf16x8*)(lds + PG8_SA(b, h) + aoff + m * 2048 + k * 1024); } while (0)
; #define PG8_LDB(dst, b, h) do { _Pragma("unroll") for (int n = 0; n < 2; ++n) _Pragma("unroll") for (int k = 0; k < 2; ++k) dst[n][k] = *(const LAS bf16x8*)(lds + PG8_SB(b, h) + boff + n * 2048 + k * 1024); } while (0)
; #define PG8_MMA(ai, bj, At, Bt) do { __builtin_amdgcn_s_setprio(1); _Pragma("unroll") for (int m = 0; m < 4; ++m) _Pragma("unroll") for (int n = 0; n < 2; ++n) _Pragma("unroll") for (int k = 0; k < 2; ++k) \
;         acc[ai][bj][m][n] = __builtin_amdgcn_mfma_f32_16x16x32_bf16(Bt[n][k], At[m][k], acc[ai][bj][m][n], 0, 0, 0); __builtin_amdgcn_s_setprio(0); } while (0)
; #define PG8_WAIT_V(n) asm volatile("s_waitcnt vmcnt(" #n ")" ::: "memory")
; #define PG8_WAIT_L(n) asm volatile("s_waitcnt lgkmcnt(" #n ")" ::: "memory")
; #define PG8_BAR __builtin_amdgcn_s_barrier()
; #define PG8_SCHED __builtin_amdgcn_sched_barrier(0)
; template <class Epi>
; __device__ __forceinline__ void gemm_phase(LAS unsigned char* lds, const Gemm g, const Epi& E) {
;     ...
;             PG8_BAR; PG8_WAIT_L(0); PG8_MMA(1, 0, At, B0); PG8_BAR; PG8_SCHED;
;             PG8_STAGE(PG8_SB(0, 1), b2 + hstep, voffB);
;             PG8_WAIT_V(6); PG8_BAR; PG8_MMA(1, 1, At, B1); PG8_BAR;
;             PG8_LDB(B0, 1, 0); PG8_SCHED; PG8_LDA(At, 1, 0); PG8_STAGE(PG8_SA(0, 1), a2 + hstep, voffA);
;             PG8_WAIT_L(8); PG8_BAR; PG8_WAIT_L(0); PG8_MMA(0, 0, At, B0); PG8_BAR; PG8_SCHED;
;             PG8_LDB(B1, 1, 1); PG8_STAGE(PG8_SB(1, 0), b3, voffB);
;             PG8_BAR; PG8_WAIT_L(0); PG8_MMA(0, 1, At, B1); PG8_BAR;
;             PG8_LDA(At, 1, 1); PG8_STAGE(PG8_SA(1, 0), a3, voffA);
;             PG8_BAR; PG8_WAIT_L(0); PG8_MMA(1, 0, At, B0); PG8_BAR; PG8_SCHED;
	v_mfma_f32_16x16x32_bf16 v[52:55], v[190:193], v[154:157], v[52:55]
	v_mfma_f32_16x16x32_bf16 v[48:51], v[198:201], v[154:157], v[48:51]
	v_mfma_f32_16x16x32_bf16 v[36:39], v[190:193], v[166:169], v[36:39]
	v_mfma_f32_16x16x32_bf16 v[32:35], v[198:201], v[166:169], v[32:35]
	v_mfma_f32_16x16x32_bf16 v[20:23], v[190:193], v[174:177], v[20:23]
	v_mfma_f32_16x16x32_bf16 v[16:19], v[198:201], v[174:177], v[16:19]
	v_mfma_f32_16x16x32_bf16 v[4:7], v[190:193], v[182:185], v[4:7]
	v_mfma_f32_16x16x32_bf16 v[0:3], v[198:201], v[182:185], v[0:3]
	v_mfma_f32_16x16x32_bf16 v[52:55], v[194:197], v[162:165], v[52:55]
	v_mfma_f32_16x16x32_bf16 v[48:51], v[202:205], v[162:165], v[48:51]
	v_mfma_f32_16x16x32_bf16 v[36:39], v[194:197], v[170:173], v[36:39]
	v_mfma_f32_16x16x32_bf16 v[32:35], v[202:205], v[170:173], v[32:35]
	v_mfma_f32_16x16x32_bf16 v[20:23], v[194:197], v[178:181], v[20:23]
	v_mfma_f32_16x16x32_bf16 v[16:19], v[202:205], v[178:181], v[16:19]
	v_mfma_f32_16x16x32_bf16 v[4:7], v[194:197], v[186:189], v[4:7]
	v_mfma_f32_16x16x32_bf16 v[0:3], v[202:205], v[186:189], v[0:3]
	s_setprio 0
	s_add_i32 s46, 0, 0x18000
	v_add_u32_e32 v150, s46, v159
	s_barrier
	ds_read_b128 v[138:141], v150
	ds_read_b128 v[142:145], v150 offset:1024
	ds_read_b128 v[146:149], v150 offset:2048
	ds_read_b128 v[150:153], v150 offset:3072
	s_add_u32 s34, s36, 0x40000
	s_addc_u32 s35, s37, 0
	s_mov_b32 m0, s78
	ds_read_b128 v[154:157], v161 offset:32768
	ds_read_b128 v[162:165], v161 offset:33792
	ds_read_b128 v[166:169], v161 offset:34816
	ds_read_b128 v[170:173], v161 offset:35840
	ds_read_b128 v[174:177], v161 offset:36864
	ds_read_b128 v[178:181], v161 offset:37888
	ds_read_b128 v[182:185], v161 offset:38912
	ds_read_b128 v[186:189], v161 offset:39936
	global_load_lds_dwordx4 v128, s[34:35]
	s_mov_b32 m0, s79
	s_nop 0
	global_load_lds_dwordx4 v130, s[34:35]
	s_waitcnt lgkmcnt(8)
	s_setprio 1
	s_barrier
	s_waitcnt lgkmcnt(0)
	v_mfma_f32_16x16x32_bf16 v[124:127], v[138:141], v[154:157], v[124:127]
	v_mfma_f32_16x16x32_bf16 v[120:123], v[146:149], v[154:157], v[120:123]
	v_mfma_f32_16x16x32_bf16 v[108:111], v[138:141], v[166:169], v[108:111]
	v_mfma_f32_16x16x32_bf16 v[104:107], v[146:149], v[166:169], v[104:107]
	v_mfma_f32_16x16x32_bf16 v[92:95], v[138:141], v[174:177], v[92:95]
	v_mfma_f32_16x16x32_bf16 v[88:91], v[146:149], v[174:177], v[88:91]
	v_mfma_f32_16x16x32_bf16 v[76:79], v[138:141], v[182:185], v[76:79]
	v_mfma_f32_16x16x32_bf16 v[72:75], v[146:149], v[182:185], v[72:75]
	v_mfma_f32_16x16x32_bf16 v[124:127], v[142:145], v[162:165], v[124:127]
	v_mfma_f32_16x16x32_bf16 v[120:123], v[150:153], v[162:165], v[120:123]
	v_mfma_f32_16x16x32_bf16 v[108:111], v[142:145], v[170:173], v[108:111]
	v_mfma_f32_16x16x32_bf16 v[104:107], v[150:153], v[170:173], v[104:107]
	v_mfma_f32_16x16x32_bf16 v[92:95], v[142:145], v[178:181], v[92:95]
	v_mfma_f32_16x16x32_bf16 v[88:91], v[150:153], v[178:181], v[88:91]
	v_mfma_f32_16x16x32_bf16 v[76:79], v[142:145], v[186:189], v[76:79]
	v_mfma_f32_16x16x32_bf16 v[72:75], v[150:153], v[186:189], v[72:75]
	s_setprio 0
	s_barrier
	s_add_i32 s34, 0, 0x1c000
	s_add_i32 s35, s46, s71
	v_add_u32_e32 v202, s34, v159
	s_mov_b32 m0, s35
	ds_read_b128 v[190:193], v202
	ds_read_b128 v[194:197], v202 offset:1024
	ds_read_b128 v[198:201], v202 offset:2048
	ds_read_b128 v[202:205], v202 offset:3072
	s_add_u32 s98, s28, 0x80
	s_addc_u32 s99, s29, 0
	global_load_lds_dwordx4 v208, s[98:99]
	s_add_i32 m0, s35, 0x2000
	s_add_u32 s100, s28, 0x80
	s_addc_u32 s101, s29, 0
	global_load_lds_dwordx4 v132, s[100:101]
	s_setprio 1
	s_barrier
	s_waitcnt lgkmcnt(0)
	v_mfma_f32_16x16x32_bf16 v[116:119], v[190:193], v[154:157], v[116:119]
	v_mfma_f32_16x16x32_bf16 v[112:115], v[198:201], v[154:157], v[112:115]
	v_mfma_f32_16x16x32_bf16 v[100:103], v[190:193], v[166:169], v[100:103]
	v_mfma_f32_16x16x32_bf16 v[96:99], v[198:201], v[166:169], v[96:99]
	v_mfma_f32_16x16x32_bf16 v[84:87], v[190:193], v[174:177], v[84:87]
	v_mfma_f32_16x16x32_bf16 v[80:83], v[198:201], v[174:177], v[80:83]
	v_mfma_f32_16x16x32_bf16 v[68:71], v[190:193], v[182:185], v[68:71]
	v_mfma_f32_16x16x32_bf16 v[64:67], v[198:201], v[182:185], v[64:67]
	v_mfma_f32_16x16x32_bf16 v[116:119], v[194:197], v[162:165], v[116:119]
	v_mfma_f32_16x16x32_bf16 v[112:115], v[202:205], v[162:165], v[112:115]
	v_mfma_f32_16x16x32_bf16 v[100:103], v[194:197], v[170:173], v[100:103]
	v_mfma_f32_16x16x32_bf16 v[96:99], v[202:205], v[170:173], v[96:99]
	v_mfma_f32_16x16x32_bf16 v[84:87], v[194:197], v[178:181], v[84:87]
	v_mfma_f32_16x16x32_bf16 v[80:83], v[202:205], v[178:181], v[80:83]
	v_mfma_f32_16x16x32_bf16 v[68:71], v[194:197], v[186:189], v[68:71]
	v_mfma_f32_16x16x32_bf16 v[64:67], v[202:205], v[186:189], v[64:67]
	s_setprio 0
	s_mov_b32 m0, s82
	s_barrier
	ds_read_b128 v[154:157], v161 offset:49152
	ds_read_b128 v[162:165], v161 offset:50176
	ds_read_b128 v[166:169], v161 offset:51200
	ds_read_b128 v[170:173], v161 offset:52224
	ds_read_b128 v[174:177], v161 offset:53248
	ds_read_b128 v[178:181], v161 offset:54272
	ds_read_b128 v[182:185], v161 offset:55296
	ds_read_b128 v[186:189], v161 offset:56320
	s_add_u32 s98, s36, 0x80
	s_addc_u32 s99, s37, 0
	global_load_lds_dwordx4 v128, s[98:99]
	s_mov_b32 m0, s83
	s_add_u32 s100, s36, 0x80
	s_addc_u32 s101, s37, 0
	global_load_lds_dwordx4 v130, s[100:101]
	s_setprio 1
	s_barrier
; __device__ __forceinline__ float bflo(unsigned w) { return __uint_as_float(w << 16); }
; __device__ __forceinline__ float bfhi(unsigned w) { return __uint_as_float(w & 0xffff0000u); }
; __device__ __forceinline__ u32x4 pack8u(f32x4 a, f32x4 b) { u32x4 w = {cvt_pk_bf16(a[0], a[1]), cvt_pk_bf16(a[2], a[3]), cvt_pk_bf16(b[0], b[1]), cvt_pk_bf16(b[2], b[3])}; return w; }
; #define PG8_STAGE(bufoff, gbase, voff) do { _Pragma("unroll") for (int _i = 0; _i < 2; ++_i) \
;         __builtin_amdgcn_global_load_lds((const unsigned*)((const char*)(gbase) + (voff)[_i]), (LAS unsigned*)(lds + (bufoff) + ldsw + _i * 8192), 16, 0, 0); } while (0)
; #define PG8_LDA(dst, b, h) do { _Pragma("unroll") for (int m = 0; m < 4; ++m) _Pragma("unroll") for (int k = 0; k < 2; ++k) dst[m][k] = *(const LAS bf16x8*)(lds + PG8_SA(b, h) + aoff + m * 2048 + k * 1024); } while (0)
; #define PG8_WAIT_V(n) asm volatile("s_waitcnt vmcnt(" #n ")" ::: "memory")
; #define PG8_WAIT_L(n) asm volatile("s_waitcnt lgkmcnt(" #n ")" ::: "memory")
; #define PG8_BAR __builtin_amdgcn_s_barrier()
; #define PG8_SCHED __builtin_amdgcn_sched_barrier(0)
; template <class Epi>
; __device__ __forceinline__ void gemm_phase(LAS unsigned char* lds, const Gemm g, const Epi& E) {
;     ...
;             PG8_BAR; PG8_WAIT_L(0); PG8_MMA(0, 1, At, B1); PG8_BAR;
;             PG8_LDA(At, 1, 1); PG8_STAGE(PG8_SA(1, 0), a3, voffA);
;             PG8_BAR; PG8_WAIT_L(0); PG8_MMA(1, 0, At, B0); PG8_BAR; PG8_SCHED;
;             PG8_STAGE(PG8_SB(1, 1), b3 + hstep, voffB);
;             PG8_WAIT_V(6); PG8_BAR; PG8_MMA(1, 1, At, B1); PG8_BAR;
;     __device__ __forceinline__ void operator()(const AccT& acc, const Unit& u, int wr, int wc, int fr, int fq) const {
;     ...
;                 const int row = u.pm * 256 + ai * 128 + wr * 64 + m * 16 + fr;
; #pragma unroll
;                 for (int bj = 0; bj < 2; ++bj) {
;                     const int c8 = u.pn * 256 + bj * 128 + wc * 32 + fq * 8;
;                     const u32x4 gw = *(const u32x4*)(GATE + (size_t)row * 4096 + SECOND * 2048 + c8);
;                     const f32x4 g0 = {bflo(gw[0]), bfhi(gw[0]), bflo(gw[1]), bfhi(gw[1])}, g1 = {bflo(gw[2]), bfhi(gw[2]), bflo(gw[3]), bfhi(gw[3])};
;                     bf16_t* tp = (bf16_t*)TMP + (size_t)row * 2048 + c8;
;                     if (SECOND == 0) { *(u32x4*)tp = pack8u(g0 * acc[ai][bj][m][0], g1 * acc[ai][bj][m][1]); }
	s_waitcnt lgkmcnt(0)
	v_mfma_f32_16x16x32_bf16 v[60:63], v[138:141], v[154:157], v[60:63]
	v_mfma_f32_16x16x32_bf16 v[56:59], v[146:149], v[154:157], v[56:59]
	v_mfma_f32_16x16x32_bf16 v[44:47], v[138:141], v[166:169], v[44:47]
	v_mfma_f32_16x16x32_bf16 v[40:43], v[146:149], v[166:169], v[40:43]
	v_mfma_f32_16x16x32_bf16 v[28:31], v[138:141], v[174:177], v[28:31]
	v_mfma_f32_16x16x32_bf16 v[24:27], v[146:149], v[174:177], v[24:27]
	v_mfma_f32_16x16x32_bf16 v[12:15], v[138:141], v[182:185], v[12:15]
	v_mfma_f32_16x16x32_bf16 v[8:11], v[146:149], v[182:185], v[8:11]
	v_mfma_f32_16x16x32_bf16 v[60:63], v[142:145], v[162:165], v[60:63]
	v_mfma_f32_16x16x32_bf16 v[56:59], v[150:153], v[162:165], v[56:59]
	v_mfma_f32_16x16x32_bf16 v[44:47], v[142:145], v[170:173], v[44:47]
	v_mfma_f32_16x16x32_bf16 v[40:43], v[150:153], v[170:173], v[40:43]
	v_mfma_f32_16x16x32_bf16 v[28:31], v[142:145], v[178:181], v[28:31]
	v_mfma_f32_16x16x32_bf16 v[24:27], v[150:153], v[178:181], v[24:27]
	v_mfma_f32_16x16x32_bf16 v[12:15], v[142:145], v[186:189], v[12:15]
	v_mfma_f32_16x16x32_bf16 v[8:11], v[150:153], v[186:189], v[8:11]
	s_setprio 0
	s_barrier
	s_add_u32 s28, s28, 0x40080
	s_addc_u32 s29, s29, 0
	s_add_i32 s34, s34, s71
	s_mov_b32 m0, s34
	s_nop 0
	global_load_lds_dwordx4 v208, s[28:29]
	s_add_i32 m0, s34, 0x2000
	s_nop 0
	global_load_lds_dwordx4 v132, s[28:29]
	s_waitcnt vmcnt(6)
	s_setprio 1
	s_barrier
	v_mfma_f32_16x16x32_bf16 v[52:55], v[190:193], v[154:157], v[52:55]
	v_mfma_f32_16x16x32_bf16 v[48:51], v[198:201], v[154:157], v[48:51]
	v_mfma_f32_16x16x32_bf16 v[36:39], v[190:193], v[166:169], v[36:39]
	v_mfma_f32_16x16x32_bf16 v[32:35], v[198:201], v[166:169], v[32:35]
	v_mfma_f32_16x16x32_bf16 v[20:23], v[190:193], v[174:177], v[20:23]
	v_mfma_f32_16x16x32_bf16 v[16:19], v[198:201], v[174:177], v[16:19]
	v_mfma_f32_16x16x32_bf16 v[4:7], v[190:193], v[182:185], v[4:7]
	v_mfma_f32_16x16x32_bf16 v[0:3], v[198:201], v[182:185], v[0:3]
	v_mfma_f32_16x16x32_bf16 v[52:55], v[194:197], v[162:165], v[52:55]
	v_mfma_f32_16x16x32_bf16 v[48:51], v[202:205], v[162:165], v[48:51]
	v_mfma_f32_16x16x32_bf16 v[36:39], v[194:197], v[170:173], v[36:39]
	v_mfma_f32_16x16x32_bf16 v[32:35], v[202:205], v[170:173], v[32:35]
	v_mfma_f32_16x16x32_bf16 v[20:23], v[194:197], v[178:181], v[20:23]
	v_mfma_f32_16x16x32_bf16 v[16:19], v[202:205], v[178:181], v[16:19]
	v_mfma_f32_16x16x32_bf16 v[4:7], v[194:197], v[186:189], v[4:7]
	v_mfma_f32_16x16x32_bf16 v[0:3], v[202:205], v[186:189], v[0:3]
	s_setprio 0
	s_add_i32 vcc_hi, vcc_hi, 2
	s_add_u32 s26, s26, 0x100
	s_addc_u32 s27, s27, 0
	s_add_u32 s65, s65, 0x100
	s_addc_u32 vcc_lo, vcc_lo, 0
	s_cmp_gt_u32 vcc_hi, 13
	s_barrier
	s_cbranch_scc0 .LBB0_211
	v_lshl_add_u32 v140, s42, 8, v158
	v_lshl_or_b32 v141, s96, 8, v160
	v_lshlrev_b32_e32 v141, 1, v141
	v_lshl_add_u32 v138, v140, 13, v141
	v_lshl_add_u32 v139, v140, 12, v141
	s_and_b64 vcc, exec, s[0:1]
	s_cbranch_vccnz .Lepo_second
	v_add_u32_e32 v140, 0x0, v138
	global_load_dwordx4 v[162:165], v140, s[44:45]
	v_add_u32_e32 v140, 0x0, v138
	global_load_dwordx4 v[166:169], v140, s[44:45] offset:256
	v_add_u32_e32 v140, 0x20000, v138
	global_load_dwordx4 v[170:173], v140, s[44:45]
	v_add_u32_e32 v140, 0x20000, v138
	global_load_dwordx4 v[174:177], v140, s[44:45] offset:256
	v_add_u32_e32 v140, 0x40000, v138
	global_load_dwordx4 v[178:181], v140, s[44:45]
	v_add_u32_e32 v140, 0x40000, v138
	global_load_dwordx4 v[182:185], v140, s[44:45] offset:256
	v_add_u32_e32 v140, 0x60000, v138
	global_load_dwordx4 v[186:189], v140, s[44:45]
	v_add_u32_e32 v140, 0x60000, v138
	global_load_dwordx4 v[190:193], v140, s[44:45] offset:256
	v_add_u32_e32 v140, 0x100000, v138
	global_load_dwordx4 v[194:197], v140, s[44:45]
	v_add_u32_e32 v140, 0x100000, v138
	global_load_dwordx4 v[198:201], v140, s[44:45] offset:256
	v_add_u32_e32 v140, 0x120000, v138
	global_load_dwordx4 v[202:205], v140, s[44:45]
	v_add_u32_e32 v140, 0x120000, v138
	global_load_dwordx4 v[228:231], v140, s[44:45] offset:256
	s_waitcnt vmcnt(11)
	v_lshlrev_b32_e32 v142, 16, v162
	v_and_b32_e32 v143, 0xffff0000, v162
	v_lshlrev_b32_e32 v144, 16, v163
	v_and_b32_e32 v145, 0xffff0000, v163
	v_lshlrev_b32_e32 v146, 16, v164
	v_and_b32_e32 v147, 0xffff0000, v164
	v_lshlrev_b32_e32 v148, 16, v165
	v_and_b32_e32 v149, 0xffff0000, v165
	v_pk_mul_f32 v[124:125], v[124:125], v[142:143]
	v_pk_mul_f32 v[126:127], v[126:127], v[144:145]
	v_pk_mul_f32 v[120:121], v[120:121], v[146:147]
	v_pk_mul_f32 v[122:123], v[122:123], v[148:149]
	v_cvt_pk_bf16_f32 v124, v124, v125
	v_cvt_pk_bf16_f32 v125, v126, v127
	v_cvt_pk_bf16_f32 v126, v120, v121
	v_cvt_pk_bf16_f32 v127, v122, v123
	v_add_u32_e32 v141, 0x0, v139
	global_store_dwordx4 v141, v[124:127], s[92:93]
	v_add_u32_e32 v140, 0x140000, v138
	global_load_dwordx4 v[162:165], v140, s[44:45]
	v_add_u32_e32 v140, 0x140000, v138
	global_load_dwordx4 v[120:123], v140, s[44:45] offset:256
	s_waitcnt vmcnt(13)
	v_lshlrev_b32_e32 v142, 16, v166
	v_and_b32_e32 v143, 0xffff0000, v166
	v_lshlrev_b32_e32 v144, 16, v167
	v_and_b32_e32 v145, 0xffff0000, v167
	v_lshlrev_b32_e32 v146, 16, v168
	v_and_b32_e32 v147, 0xffff0000, v168
	v_lshlrev_b32_e32 v148, 16, v169
	v_and_b32_e32 v149, 0xffff0000, v169
	v_pk_mul_f32 v[116:117], v[116:117], v[142:143]
	v_pk_mul_f32 v[118:119], v[118:119], v[144:145]
	v_pk_mul_f32 v[112:113], v[112:113], v[146:147]
	v_pk_mul_f32 v[114:115], v[114:115], v[148:149]
	v_cvt_pk_bf16_f32 v116, v116, v117
	v_cvt_pk_bf16_f32 v117, v118, v119
	v_cvt_pk_bf16_f32 v118, v112, v113
	v_cvt_pk_bf16_f32 v119, v114, v115
	v_add_u32_e32 v141, 0x0, v139
	global_store_dwordx4 v141, v[116:119], s[92:93] offset:256
	v_add_u32_e32 v140, 0x160000, v138
	global_load_dwordx4 v[166:169], v140, s[44:45]
	v_add_u32_e32 v140, 0x160000, v138
	global_load_dwordx4 v[112:115], v140, s[44:45] offset:256
	s_waitcnt vmcnt(15)
; __device__ __forceinline__ float bflo(unsigned w) { return __uint_as_float(w << 16); }
; __device__ __forceinline__ float bfhi(unsigned w) { return __uint_as_float(w & 0xffff0000u); }
; __device__ __forceinline__ u32x4 pack8u(f32x4 a, f32x4 b) { u32x4 w = {cvt_pk_bf16(a[0], a[1]), cvt_pk_bf16(a[2], a[3]), cvt_pk_bf16(b[0], b[1]), cvt_pk_bf16(b[2], b[3])}; return w; }
;     __device__ __forceinline__ void operator()(const AccT& acc, const Unit& u, int wr, int wc, int fr, int fq) const {
;     ...
;                 const int row = u.pm * 256 + ai * 128 + wr * 64 + m * 16 + fr;
; #pragma unroll
;                 for (int bj = 0; bj < 2; ++bj) {
;                     const int c8 = u.pn * 256 + bj * 128 + wc * 32 + fq * 8;
;                     const u32x4 gw = *(const u32x4*)(GATE + (size_t)row * 4096 + SECOND * 2048 + c8);
;                     const f32x4 g0 = {bflo(gw[0]), bfhi(gw[0]), bflo(gw[1]), bfhi(gw[1])}, g1 = {bflo(gw[2]), bfhi(gw[2]), bflo(gw[3]), bfhi(gw[3])};
;                     bf16_t* tp = (bf16_t*)TMP + (size_t)row * 2048 + c8;
;                     if (SECOND == 0) { *(u32x4*)tp = pack8u(g0 * acc[ai][bj][m][0], g1 * acc[ai][bj][m][1]); }
	v_lshlrev_b32_e32 v142, 16, v170
	v_and_b32_e32 v143, 0xffff0000, v170
	v_lshlrev_b32_e32 v144, 16, v171
	v_and_b32_e32 v145, 0xffff0000, v171
	v_lshlrev_b32_e32 v146, 16, v172
	v_and_b32_e32 v147, 0xffff0000, v172
	v_lshlrev_b32_e32 v148, 16, v173
	v_and_b32_e32 v149, 0xffff0000, v173
	v_pk_mul_f32 v[108:109], v[108:109], v[142:143]
	v_pk_mul_f32 v[110:111], v[110:111], v[144:145]
	v_pk_mul_f32 v[104:105], v[104:105], v[146:147]
	v_pk_mul_f32 v[106:107], v[106:107], v[148:149]
	v_cvt_pk_bf16_f32 v108, v108, v109
	v_cvt_pk_bf16_f32 v109, v110, v111
	v_cvt_pk_bf16_f32 v110, v104, v105
	v_cvt_pk_bf16_f32 v111, v106, v107
	v_add_u32_e32 v141, 0x10000, v139
	global_store_dwordx4 v141, v[108:111], s[92:93]
	s_waitcnt vmcnt(15)
	v_lshlrev_b32_e32 v142, 16, v174
	v_and_b32_e32 v143, 0xffff0000, v174
	v_lshlrev_b32_e32 v144, 16, v175
	v_and_b32_e32 v145, 0xffff0000, v175
	v_lshlrev_b32_e32 v146, 16, v176
	v_and_b32_e32 v147, 0xffff0000, v176
	v_lshlrev_b32_e32 v148, 16, v177
	v_and_b32_e32 v149, 0xffff0000, v177
	v_pk_mul_f32 v[100:101], v[100:101], v[142:143]
	v_pk_mul_f32 v[102:103], v[102:103], v[144:145]
	v_pk_mul_f32 v[96:97], v[96:97], v[146:147]
	v_pk_mul_f32 v[98:99], v[98:99], v[148:149]
	v_cvt_pk_bf16_f32 v100, v100, v101
	v_cvt_pk_bf16_f32 v101, v102, v103
	v_cvt_pk_bf16_f32 v102, v96, v97
	v_cvt_pk_bf16_f32 v103, v98, v99
	v_add_u32_e32 v141, 0x10000, v139
	global_store_dwordx4 v141, v[100:103], s[92:93] offset:256
	s_waitcnt vmcnt(15)
	v_lshlrev_b32_e32 v142, 16, v178
	v_and_b32_e32 v143, 0xffff0000, v178
	v_lshlrev_b32_e32 v144, 16, v179
	v_and_b32_e32 v145, 0xffff0000, v179
	v_lshlrev_b32_e32 v146, 16, v180
	v_and_b32_e32 v147, 0xffff0000, v180
	v_lshlrev_b32_e32 v148, 16, v181
	v_and_b32_e32 v149, 0xffff0000, v181
	v_pk_mul_f32 v[92:93], v[92:93], v[142:143]
	v_pk_mul_f32 v[94:95], v[94:95], v[144:145]
	v_pk_mul_f32 v[88:89], v[88:89], v[146:147]
	v_pk_mul_f32 v[90:91], v[90:91], v[148:149]
	v_cvt_pk_bf16_f32 v92, v92, v93
	v_cvt_pk_bf16_f32 v93, v94, v95
	v_cvt_pk_bf16_f32 v94, v88, v89
	v_cvt_pk_bf16_f32 v95, v90, v91
	v_add_u32_e32 v141, 0x20000, v139
	global_store_dwordx4 v141, v[92:95], s[92:93]
	s_waitcnt vmcnt(15)
	v_lshlrev_b32_e32 v142, 16, v182
	v_and_b32_e32 v143, 0xffff0000, v182
	v_lshlrev_b32_e32 v144, 16, v183
	v_and_b32_e32 v145, 0xffff0000, v183
	v_lshlrev_b32_e32 v146, 16, v184
	v_and_b32_e32 v147, 0xffff0000, v184
	v_lshlrev_b32_e32 v148, 16, v185
	v_and_b32_e32 v149, 0xffff0000, v185
	v_pk_mul_f32 v[84:85], v[84:85], v[142:143]
	v_pk_mul_f32 v[86:87], v[86:87], v[144:145]
	v_pk_mul_f32 v[80:81], v[80:81], v[146:147]
	v_pk_mul_f32 v[82:83], v[82:83], v[148:149]
	v_cvt_pk_bf16_f32 v84, v84, v85
	v_cvt_pk_bf16_f32 v85, v86, v87
	v_cvt_pk_bf16_f32 v86, v80, v81
	v_cvt_pk_bf16_f32 v87, v82, v83
	v_add_u32_e32 v141, 0x20000, v139
	global_store_dwordx4 v141, v[84:87], s[92:93] offset:256
	s_waitcnt vmcnt(15)
	v_lshlrev_b32_e32 v142, 16, v186
	v_and_b32_e32 v143, 0xffff0000, v186
	v_lshlrev_b32_e32 v144, 16, v187
	v_and_b32_e32 v145, 0xffff0000, v187
	v_lshlrev_b32_e32 v146, 16, v188
	v_and_b32_e32 v147, 0xffff0000, v188
	v_lshlrev_b32_e32 v148, 16, v189
	v_and_b32_e32 v149, 0xffff0000, v189
	v_pk_mul_f32 v[76:77], v[76:77], v[142:143]
	v_pk_mul_f32 v[78:79], v[78:79], v[144:145]
	v_pk_mul_f32 v[72:73], v[72:73], v[146:147]
	v_pk_mul_f32 v[74:75], v[74:75], v[148:149]
	v_cvt_pk_bf16_f32 v76, v76, v77
	v_cvt_pk_bf16_f32 v77, v78, v79
	v_cvt_pk_bf16_f32 v78, v72, v73
	v_cvt_pk_bf16_f32 v79, v74, v75
	v_add_u32_e32 v141, 0x30000, v139
	global_store_dwordx4 v141, v[76:79], s[92:93]
	s_waitcnt vmcnt(15)
	v_lshlrev_b32_e32 v142, 16, v190
	v_and_b32_e32 v143, 0xffff0000, v190
	v_lshlrev_b32_e32 v144, 16, v191
	v_and_b32_e32 v145, 0xffff0000, v191
	v_lshlrev_b32_e32 v146, 16, v192
	v_and_b32_e32 v147, 0xffff0000, v192
	v_lshlrev_b32_e32 v148, 16, v193
	v_and_b32_e32 v149, 0xffff0000, v193
	v_pk_mul_f32 v[68:69], v[68:69], v[142:143]
	v_pk_mul_f32 v[70:71], v[70:71], v[144:145]
	v_pk_mul_f32 v[64:65], v[64:65], v[146:147]
	v_pk_mul_f32 v[66:67], v[66:67], v[148:149]
	v_cvt_pk_bf16_f32 v68, v68, v69
	v_cvt_pk_bf16_f32 v69, v70, v71
	v_cvt_pk_bf16_f32 v70, v64, v65
	v_cvt_pk_bf16_f32 v71, v66, v67
	v_add_u32_e32 v141, 0x30000, v139
	global_store_dwordx4 v141, v[68:71], s[92:93] offset:256
	s_waitcnt vmcnt(15)
	v_lshlrev_b32_e32 v142, 16, v194
	v_and_b32_e32 v143, 0xffff0000, v194
	v_lshlrev_b32_e32 v144, 16, v195
	v_and_b32_e32 v145, 0xffff0000, v195
	v_lshlrev_b32_e32 v146, 16, v196
	v_and_b32_e32 v147, 0xffff0000, v196
	v_lshlrev_b32_e32 v148, 16, v197
	v_and_b32_e32 v149, 0xffff0000, v197
	v_pk_mul_f32 v[60:61], v[60:61], v[142:143]
	v_pk_mul_f32 v[62:63], v[62:63], v[144:145]
	v_pk_mul_f32 v[56:57], v[56:57], v[146:147]
	v_pk_mul_f32 v[58:59], v[58:59], v[148:149]
	v_cvt_pk_bf16_f32 v60, v60, v61
	v_cvt_pk_bf16_f32 v61, v62, v63
	v_cvt_pk_bf16_f32 v62, v56, v57
	v_cvt_pk_bf16_f32 v63, v58, v59
	v_add_u32_e32 v141, 0x80000, v139
	global_store_dwordx4 v141, v[60:63], s[92:93]
	s_waitcnt vmcnt(15)
; __device__ __forceinline__ float bflo(unsigned w) { return __uint_as_float(w << 16); }
; __device__ __forceinline__ float bfhi(unsigned w) { return __uint_as_float(w & 0xffff0000u); }
; __device__ __forceinline__ u32x4 pack8u(f32x4 a, f32x4 b) { u32x4 w = {cvt_pk_bf16(a[0], a[1]), cvt_pk_bf16(a[2], a[3]), cvt_pk_bf16(b[0], b[1]), cvt_pk_bf16(b[2], b[3])}; return w; }
;     __device__ __forceinline__ void operator()(const AccT& acc, const Unit& u, int wr, int wc, int fr, int fq) const {
;     ...
;                 const int row = u.pm * 256 + ai * 128 + wr * 64 + m * 16 + fr;
; #pragma unroll
;                 for (int bj = 0; bj < 2; ++bj) {
;                     const int c8 = u.pn * 256 + bj * 128 + wc * 32 + fq * 8;
;                     const u32x4 gw = *(const u32x4*)(GATE + (size_t)row * 4096 + SECOND * 2048 + c8);
;                     const f32x4 g0 = {bflo(gw[0]), bfhi(gw[0]), bflo(gw[1]), bfhi(gw[1])}, g1 = {bflo(gw[2]), bfhi(gw[2]), bflo(gw[3]), bfhi(gw[3])};
;                     bf16_t* tp = (bf16_t*)TMP + (size_t)row * 2048 + c8;
;                     if (SECOND == 0) { *(u32x4*)tp = pack8u(g0 * acc[ai][bj][m][0], g1 * acc[ai][bj][m][1]); }
	v_lshlrev_b32_e32 v142, 16, v198
	v_and_b32_e32 v143, 0xffff0000, v198
	v_lshlrev_b32_e32 v144, 16, v199
	v_and_b32_e32 v145, 0xffff0000, v199
	v_lshlrev_b32_e32 v146, 16, v200
	v_and_b32_e32 v147, 0xffff0000, v200
	v_lshlrev_b32_e32 v148, 16, v201
	v_and_b32_e32 v149, 0xffff0000, v201
	v_pk_mul_f32 v[52:53], v[52:53], v[142:143]
	v_pk_mul_f32 v[54:55], v[54:55], v[144:145]
	v_pk_mul_f32 v[48:49], v[48:49], v[146:147]
	v_pk_mul_f32 v[50:51], v[50:51], v[148:149]
	v_cvt_pk_bf16_f32 v52, v52, v53
	v_cvt_pk_bf16_f32 v53, v54, v55
	v_cvt_pk_bf16_f32 v54, v48, v49
	v_cvt_pk_bf16_f32 v55, v50, v51
	v_add_u32_e32 v141, 0x80000, v139
	global_store_dwordx4 v141, v[52:55], s[92:93] offset:256
	s_waitcnt vmcnt(15)
	v_lshlrev_b32_e32 v142, 16, v202
	v_and_b32_e32 v143, 0xffff0000, v202
	v_lshlrev_b32_e32 v144, 16, v203
	v_and_b32_e32 v145, 0xffff0000, v203
	v_lshlrev_b32_e32 v146, 16, v204
	v_and_b32_e32 v147, 0xffff0000, v204
	v_lshlrev_b32_e32 v148, 16, v205
	v_and_b32_e32 v149, 0xffff0000, v205
	v_pk_mul_f32 v[44:45], v[44:45], v[142:143]
	v_pk_mul_f32 v[46:47], v[46:47], v[144:145]
	v_pk_mul_f32 v[40:41], v[40:41], v[146:147]
	v_pk_mul_f32 v[42:43], v[42:43], v[148:149]
	v_cvt_pk_bf16_f32 v44, v44, v45
	v_cvt_pk_bf16_f32 v45, v46, v47
	v_cvt_pk_bf16_f32 v46, v40, v41
	v_cvt_pk_bf16_f32 v47, v42, v43
	v_add_u32_e32 v141, 0x90000, v139
	global_store_dwordx4 v141, v[44:47], s[92:93]
	s_waitcnt vmcnt(15)
	v_lshlrev_b32_e32 v142, 16, v228
	v_and_b32_e32 v143, 0xffff0000, v228
	v_lshlrev_b32_e32 v144, 16, v229
	v_and_b32_e32 v145, 0xffff0000, v229
	v_lshlrev_b32_e32 v146, 16, v230
	v_and_b32_e32 v147, 0xffff0000, v230
	v_lshlrev_b32_e32 v148, 16, v231
	v_and_b32_e32 v149, 0xffff0000, v231
	v_pk_mul_f32 v[36:37], v[36:37], v[142:143]
	v_pk_mul_f32 v[38:39], v[38:39], v[144:145]
	v_pk_mul_f32 v[32:33], v[32:33], v[146:147]
	v_pk_mul_f32 v[34:35], v[34:35], v[148:149]
	v_cvt_pk_bf16_f32 v36, v36, v37
	v_cvt_pk_bf16_f32 v37, v38, v39
	v_cvt_pk_bf16_f32 v38, v32, v33
	v_cvt_pk_bf16_f32 v39, v34, v35
	v_add_u32_e32 v141, 0x90000, v139
	global_store_dwordx4 v141, v[36:39], s[92:93] offset:256
	s_waitcnt vmcnt(14)
	v_lshlrev_b32_e32 v142, 16, v162
	v_and_b32_e32 v143, 0xffff0000, v162
	v_lshlrev_b32_e32 v144, 16, v163
	v_and_b32_e32 v145, 0xffff0000, v163
	v_lshlrev_b32_e32 v146, 16, v164
	v_and_b32_e32 v147, 0xffff0000, v164
	v_lshlrev_b32_e32 v148, 16, v165
	v_and_b32_e32 v149, 0xffff0000, v165
	v_pk_mul_f32 v[28:29], v[28:29], v[142:143]
	v_pk_mul_f32 v[30:31], v[30:31], v[144:145]
	v_pk_mul_f32 v[24:25], v[24:25], v[146:147]
	v_pk_mul_f32 v[26:27], v[26:27], v[148:149]
	v_cvt_pk_bf16_f32 v28, v28, v29
	v_cvt_pk_bf16_f32 v29, v30, v31
	v_cvt_pk_bf16_f32 v30, v24, v25
	v_cvt_pk_bf16_f32 v31, v26, v27
	v_add_u32_e32 v141, 0xa0000, v139
	global_store_dwordx4 v141, v[28:31], s[92:93]
	s_waitcnt vmcnt(14)
	v_lshlrev_b32_e32 v142, 16, v120
	v_and_b32_e32 v143, 0xffff0000, v120
	v_lshlrev_b32_e32 v144, 16, v121
	v_and_b32_e32 v145, 0xffff0000, v121
	v_lshlrev_b32_e32 v146, 16, v122
	v_and_b32_e32 v147, 0xffff0000, v122
	v_lshlrev_b32_e32 v148, 16, v123
	v_and_b32_e32 v149, 0xffff0000, v123
	v_pk_mul_f32 v[20:21], v[20:21], v[142:143]
	v_pk_mul_f32 v[22:23], v[22:23], v[144:145]
	v_pk_mul_f32 v[16:17], v[16:17], v[146:147]
	v_pk_mul_f32 v[18:19], v[18:19], v[148:149]
	v_cvt_pk_bf16_f32 v20, v20, v21
	v_cvt_pk_bf16_f32 v21, v22, v23
	v_cvt_pk_bf16_f32 v22, v16, v17
	v_cvt_pk_bf16_f32 v23, v18, v19
	v_add_u32_e32 v141, 0xa0000, v139
	global_store_dwordx4 v141, v[20:23], s[92:93] offset:256
	s_waitcnt vmcnt(13)
	v_lshlrev_b32_e32 v142, 16, v166
	v_and_b32_e32 v143, 0xffff0000, v166
	v_lshlrev_b32_e32 v144, 16, v167
	v_and_b32_e32 v145, 0xffff0000, v167
	v_lshlrev_b32_e32 v146, 16, v168
	v_and_b32_e32 v147, 0xffff0000, v168
	v_lshlrev_b32_e32 v148, 16, v169
	v_and_b32_e32 v149, 0xffff0000, v169
	v_pk_mul_f32 v[12:13], v[12:13], v[142:143]
	v_pk_mul_f32 v[14:15], v[14:15], v[144:145]
	v_pk_mul_f32 v[8:9], v[8:9], v[146:147]
	v_pk_mul_f32 v[10:11], v[10:11], v[148:149]
	v_cvt_pk_bf16_f32 v12, v12, v13
	v_cvt_pk_bf16_f32 v13, v14, v15
	v_cvt_pk_bf16_f32 v14, v8, v9
	v_cvt_pk_bf16_f32 v15, v10, v11
	v_add_u32_e32 v141, 0xb0000, v139
	global_store_dwordx4 v141, v[12:15], s[92:93]
	s_waitcnt vmcnt(13)
	v_lshlrev_b32_e32 v142, 16, v112
	v_and_b32_e32 v143, 0xffff0000, v112
	v_lshlrev_b32_e32 v144, 16, v113
	v_and_b32_e32 v145, 0xffff0000, v113
	v_lshlrev_b32_e32 v146, 16, v114
	v_and_b32_e32 v147, 0xffff0000, v114
	v_lshlrev_b32_e32 v148, 16, v115
	v_and_b32_e32 v149, 0xffff0000, v115
	v_pk_mul_f32 v[4:5], v[4:5], v[142:143]
	v_pk_mul_f32 v[6:7], v[6:7], v[144:145]
	v_pk_mul_f32 v[0:1], v[0:1], v[146:147]
	v_pk_mul_f32 v[2:3], v[2:3], v[148:149]
	v_cvt_pk_bf16_f32 v4, v4, v5
	v_cvt_pk_bf16_f32 v5, v6, v7
	v_cvt_pk_bf16_f32 v6, v0, v1
	v_cvt_pk_bf16_f32 v7, v2, v3
	v_add_u32_e32 v141, 0xb0000, v139
	global_store_dwordx4 v141, v[4:7], s[92:93] offset:256
	s_mov_b64 s[26:27], -1
	s_mov_b64 s[42:43], exec
	s_mov_b64 vcc, 0
	s_branch .LBB0_203

; #define PG8_STAGE(bufoff, gbase, voff) do { _Pragma("unroll") for (int _i = 0; _i < 2; ++_i) \
;         __builtin_amdgcn_global_load_lds((const unsigned*)((const char*)(gbase) + (voff)[_i]), (LAS unsigned*)(lds + (bufoff) + ldsw + _i * 8192), 16, 0, 0); } while (0)
; #define PG8_LDA(dst, b, h) do { _Pragma("unroll") for (int m = 0; m < 4; ++m) _Pragma("unroll") for (int k = 0; k < 2; ++k) dst[m][k] = *(const LAS bf16x8*)(lds + PG8_SA(b, h) + aoff + m * 2048 + k * 1024); } while (0)
; #define PG8_LDB(dst, b, h) do { _Pragma("unroll") for (int n = 0; n < 2; ++n) _Pragma("unroll") for (int k = 0; k < 2; ++k) dst[n][k] = *(const LAS bf16x8*)(lds + PG8_SB(b, h) + boff + n * 2048 + k * 1024); } while (0)
; #define PG8_WAIT_V(n) asm volatile("s_waitcnt vmcnt(" #n ")" ::: "memory")
; #define PG8_WAIT_L(n) asm volatile("s_waitcnt lgkmcnt(" #n ")" ::: "memory")
; #define PG8_BAR __builtin_amdgcn_s_barrier()
; template <class Epi>
; __device__ __forceinline__ void gemm_phase(LAS unsigned char* lds, const Gemm g, const Epi& E) {
;     ...
;         for (int t = 0; t < nt; t += 2) {
;             const bool last = (t == nt - 2);
;             const char* a1 = cA + (size_t)(t + 1) * kstep;
;             const char* a2 = last ? nA : cA + (size_t)(t + 2) * kstep; const char* b2 = last ? nB : cB + (size_t)(t + 2) * kstep;
;             const char* a3 = a2 + kstep; const char* b3 = b2 + kstep;
;             PG8_LDB(B0, 0, 0); PG8_SCHED; PG8_LDA(At, 0, 0); PG8_STAGE(PG8_SA(1, 1), a1 + hstep, voffA);
;             PG8_WAIT_L(8); PG8_BAR; PG8_WAIT_L(0); PG8_MMA(0, 0, At, B0); PG8_BAR; PG8_SCHED;
;             PG8_LDB(B1, 0, 1); PG8_STAGE(PG8_SB(0, 0), b2, voffB);
;             PG8_BAR; PG8_WAIT_L(0); PG8_MMA(0, 1, At, B1); PG8_BAR;
;             PG8_LDA(At, 0, 1); PG8_STAGE(PG8_SA(0, 0), a2, voffA);
;             PG8_BAR; PG8_WAIT_L(0); PG8_MMA(1, 0, At, B0); PG8_BAR; PG8_SCHED;
;             PG8_STAGE(PG8_SB(0, 1), b2 + hstep, voffB);
;             PG8_WAIT_V(6); PG8_BAR; PG8_MMA(1, 1, At, B1); PG8_BAR;
;             PG8_LDB(B0, 1, 0); PG8_SCHED; PG8_LDA(At, 1, 0); PG8_STAGE(PG8_SA(0, 1), a2 + hstep, voffA);
;             PG8_WAIT_L(8); PG8_BAR; PG8_WAIT_L(0); PG8_MMA(0, 0, At, B0); PG8_BAR; PG8_SCHED;
;             PG8_LDB(B1, 1, 1); PG8_STAGE(PG8_SB(1, 0), b3, voffB);
;             PG8_BAR; PG8_WAIT_L(0); PG8_MMA(0, 1, At, B1); PG8_BAR;
.LBB0_499:
	s_add_u32 s28, s26, 0xfffe0080
	s_addc_u32 s29, s27, -1
	s_add_i32 s34, 0, 0x10000
	v_add_u32_e32 v156, s34, v159
	ds_read_b128 v[144:147], v156
	ds_read_b128 v[148:151], v156 offset:1024
	ds_read_b128 v[152:155], v156 offset:2048
	ds_read_b128 v[162:165], v156 offset:3072
	s_cmp_eq_u32 vcc_lo, 4
	s_cselect_b32 s37, s1, s29
	s_cselect_b32 s36, s31, s28
	s_cselect_b32 s29, s42, s65
	s_cselect_b32 s28, s43, s45
	s_add_i32 m0, s95, 0xc000
	ds_read_b128 v[166:169], v161
	ds_read_b128 v[170:173], v161 offset:1024
	ds_read_b128 v[174:177], v161 offset:2048
	ds_read_b128 v[178:181], v161 offset:3072
	ds_read_b128 v[182:185], v161 offset:4096
	ds_read_b128 v[186:189], v161 offset:5120
	ds_read_b128 v[190:193], v161 offset:6144
	ds_read_b128 v[194:197], v161 offset:7168
	global_load_lds_dwordx4 v140, s[26:27]
	s_add_i32 m0, s95, 0xe000
	s_nop 0
	global_load_lds_dwordx4 v142, s[26:27]
	s_waitcnt lgkmcnt(8)
	s_setprio 1
	s_barrier
	s_waitcnt lgkmcnt(0)
	v_mfma_f32_16x16x32_bf16 v[124:127], v[144:147], v[166:169], v[124:127]
	v_mfma_f32_16x16x32_bf16 v[120:123], v[152:155], v[166:169], v[120:123]
	v_mfma_f32_16x16x32_bf16 v[108:111], v[144:147], v[174:177], v[108:111]
	v_mfma_f32_16x16x32_bf16 v[104:107], v[152:155], v[174:177], v[104:107]
	v_mfma_f32_16x16x32_bf16 v[92:95], v[144:147], v[182:185], v[92:95]
	v_mfma_f32_16x16x32_bf16 v[88:91], v[152:155], v[182:185], v[88:91]
	v_mfma_f32_16x16x32_bf16 v[76:79], v[144:147], v[190:193], v[76:79]
	v_mfma_f32_16x16x32_bf16 v[72:75], v[152:155], v[190:193], v[72:75]
	v_mfma_f32_16x16x32_bf16 v[124:127], v[148:151], v[170:173], v[124:127]
	v_mfma_f32_16x16x32_bf16 v[120:123], v[162:165], v[170:173], v[120:123]
	v_mfma_f32_16x16x32_bf16 v[108:111], v[148:151], v[178:181], v[108:111]
	v_mfma_f32_16x16x32_bf16 v[104:107], v[162:165], v[178:181], v[104:107]
	v_mfma_f32_16x16x32_bf16 v[92:95], v[148:151], v[186:189], v[92:95]
	v_mfma_f32_16x16x32_bf16 v[88:91], v[162:165], v[186:189], v[88:91]
	v_mfma_f32_16x16x32_bf16 v[76:79], v[148:151], v[194:197], v[76:79]
	v_mfma_f32_16x16x32_bf16 v[72:75], v[162:165], v[194:197], v[72:75]
	s_setprio 0
	s_barrier
	s_add_i32 vcc_hi, 0, 0x14000
	v_add_u32_e32 v156, vcc_hi, v159
	s_add_i32 s34, s34, s83
	ds_read_b128 v[198:201], v156
	ds_read_b128 v[202:205], v156 offset:1024
	ds_read_b128 v[238:241], v156 offset:2048
	ds_read_b128 v[242:245], v156 offset:3072
	s_mov_b32 m0, s34
	s_nop 0
	global_load_lds_dwordx4 v130, s[28:29]
	s_add_i32 m0, s34, 0x2000
	s_nop 0
	global_load_lds_dwordx4 v134, s[28:29]
	s_setprio 1
	s_barrier
	s_waitcnt lgkmcnt(0)
	v_mfma_f32_16x16x32_bf16 v[116:119], v[198:201], v[166:169], v[116:119]
	v_mfma_f32_16x16x32_bf16 v[112:115], v[238:241], v[166:169], v[112:115]
	v_mfma_f32_16x16x32_bf16 v[100:103], v[198:201], v[174:177], v[100:103]
	v_mfma_f32_16x16x32_bf16 v[96:99], v[238:241], v[174:177], v[96:99]
	v_mfma_f32_16x16x32_bf16 v[84:87], v[198:201], v[182:185], v[84:87]
	v_mfma_f32_16x16x32_bf16 v[80:83], v[238:241], v[182:185], v[80:83]
	v_mfma_f32_16x16x32_bf16 v[68:71], v[198:201], v[190:193], v[68:71]
	v_mfma_f32_16x16x32_bf16 v[64:67], v[238:241], v[190:193], v[64:67]
	v_mfma_f32_16x16x32_bf16 v[116:119], v[202:205], v[170:173], v[116:119]
	v_mfma_f32_16x16x32_bf16 v[112:115], v[242:245], v[170:173], v[112:115]
	v_mfma_f32_16x16x32_bf16 v[100:103], v[202:205], v[178:181], v[100:103]
	v_mfma_f32_16x16x32_bf16 v[96:99], v[242:245], v[178:181], v[96:99]
	v_mfma_f32_16x16x32_bf16 v[84:87], v[202:205], v[186:189], v[84:87]
	v_mfma_f32_16x16x32_bf16 v[80:83], v[242:245], v[186:189], v[80:83]
	v_mfma_f32_16x16x32_bf16 v[68:71], v[202:205], v[194:197], v[68:71]
	v_mfma_f32_16x16x32_bf16 v[64:67], v[242:245], v[194:197], v[64:67]
	s_setprio 0
	s_mov_b32 m0, s95
	s_barrier
	ds_read_b128 v[166:169], v161 offset:16384
	ds_read_b128 v[170:173], v161 offset:17408
	ds_read_b128 v[174:177], v161 offset:18432
	ds_read_b128 v[178:181], v161 offset:19456
	ds_read_b128 v[182:185], v161 offset:20480
	ds_read_b128 v[186:189], v161 offset:21504
	ds_read_b128 v[190:193], v161 offset:22528
	ds_read_b128 v[194:197], v161 offset:23552
	global_load_lds_dwordx4 v128, s[36:37]
	s_mov_b32 m0, s82
	s_nop 0
	global_load_lds_dwordx4 v132, s[36:37]
	s_setprio 1
	s_barrier
	s_waitcnt lgkmcnt(0)
	v_mfma_f32_16x16x32_bf16 v[60:63], v[144:147], v[166:169], v[60:63]
	v_mfma_f32_16x16x32_bf16 v[56:59], v[152:155], v[166:169], v[56:59]
	v_mfma_f32_16x16x32_bf16 v[44:47], v[144:147], v[174:177], v[44:47]
	v_mfma_f32_16x16x32_bf16 v[40:43], v[152:155], v[174:177], v[40:43]
	v_mfma_f32_16x16x32_bf16 v[28:31], v[144:147], v[182:185], v[28:31]
	v_mfma_f32_16x16x32_bf16 v[24:27], v[152:155], v[182:185], v[24:27]
	v_mfma_f32_16x16x32_bf16 v[12:15], v[144:147], v[190:193], v[12:15]
	v_mfma_f32_16x16x32_bf16 v[8:11], v[152:155], v[190:193], v[8:11]
	v_mfma_f32_16x16x32_bf16 v[60:63], v[148:151], v[170:173], v[60:63]
	v_mfma_f32_16x16x32_bf16 v[56:59], v[162:165], v[170:173], v[56:59]
	v_mfma_f32_16x16x32_bf16 v[44:47], v[148:151], v[178:181], v[44:47]
	v_mfma_f32_16x16x32_bf16 v[40:43], v[162:165], v[178:181], v[40:43]
	v_mfma_f32_16x16x32_bf16 v[28:31], v[148:151], v[186:189], v[28:31]
	v_mfma_f32_16x16x32_bf16 v[24:27], v[162:165], v[186:189], v[24:27]
	v_mfma_f32_16x16x32_bf16 v[12:15], v[148:151], v[194:197], v[12:15]
	v_mfma_f32_16x16x32_bf16 v[8:11], v[162:165], v[194:197], v[8:11]
	s_setprio 0
	s_barrier
	s_add_u32 s34, s28, 0x20000
	s_addc_u32 s35, s29, 0
	s_add_i32 vcc_hi, vcc_hi, s83
	s_mov_b32 m0, vcc_hi
	s_nop 0
	global_load_lds_dwordx4 v130, s[34:35]
	s_add_i32 m0, vcc_hi, 0x2000
	s_nop 0
	global_load_lds_dwordx4 v134, s[34:35]
	s_waitcnt vmcnt(6)
	s_setprio 1
	s_barrier
; #define PG8_STAGE(bufoff, gbase, voff) do { _Pragma("unroll") for (int _i = 0; _i < 2; ++_i) \
;         __builtin_amdgcn_global_load_lds((const unsigned*)((const char*)(gbase) + (voff)[_i]), (LAS unsigned*)(lds + (bufoff) + ldsw + _i * 8192), 16, 0, 0); } while (0)
; #define PG8_LDA(dst, b, h) do { _Pragma("unroll") for (int m = 0; m < 4; ++m) _Pragma("unroll") for (int k = 0; k < 2; ++k) dst[m][k] = *(const LAS bf16x8*)(lds + PG8_SA(b, h) + aoff + m * 2048 + k * 1024); } while (0)
; #define PG8_LDB(dst, b, h) do { _Pragma("unroll") for (int n = 0; n < 2; ++n) _Pragma("unroll") for (int k = 0; k < 2; ++k) dst[n][k] = *(const LAS bf16x8*)(lds + PG8_SB(b, h) + boff + n * 2048 + k * 1024); } while (0)
; #define PG8_MMA(ai, bj, At, Bt) do { __builtin_amdgcn_s_setprio(1); _Pragma("unroll") for (int m = 0; m < 4; ++m) _Pragma("unroll") for (int n = 0; n < 2; ++n) _Pragma("unroll") for (int k = 0; k < 2; ++k) \
;         acc[ai][bj][m][n] = __builtin_amdgcn_mfma_f32_16x16x32_bf16(Bt[n][k], At[m][k], acc[ai][bj][m][n], 0, 0, 0); __builtin_amdgcn_s_setprio(0); } while (0)
; #define PG8_WAIT_V(n) asm volatile("s_waitcnt vmcnt(" #n ")" ::: "memory")
; #define PG8_WAIT_L(n) asm volatile("s_waitcnt lgkmcnt(" #n ")" ::: "memory")
; #define PG8_BAR __builtin_amdgcn_s_barrier()
; #define PG8_SCHED __builtin_amdgcn_sched_barrier(0)
; template <class Epi>
; __device__ __forceinline__ void gemm_phase(LAS unsigned char* lds, const Gemm g, const Epi& E) {
;     ...
;             PG8_BAR; PG8_WAIT_L(0); PG8_MMA(1, 0, At, B0); PG8_BAR; PG8_SCHED;
;             PG8_STAGE(PG8_SB(0, 1), b2 + hstep, voffB);
;             PG8_WAIT_V(6); PG8_BAR; PG8_MMA(1, 1, At, B1); PG8_BAR;
;             PG8_LDB(B0, 1, 0); PG8_SCHED; PG8_LDA(At, 1, 0); PG8_STAGE(PG8_SA(0, 1), a2 + hstep, voffA);
;             PG8_WAIT_L(8); PG8_BAR; PG8_WAIT_L(0); PG8_MMA(0, 0, At, B0); PG8_BAR; PG8_SCHED;
;             PG8_LDB(B1, 1, 1); PG8_STAGE(PG8_SB(1, 0), b3, voffB);
;             PG8_BAR; PG8_WAIT_L(0); PG8_MMA(0, 1, At, B1); PG8_BAR;
;             PG8_LDA(At, 1, 1); PG8_STAGE(PG8_SA(1, 0), a3, voffA);
;             PG8_BAR; PG8_WAIT_L(0); PG8_MMA(1, 0, At, B0); PG8_BAR; PG8_SCHED;
	v_mfma_f32_16x16x32_bf16 v[52:55], v[198:201], v[166:169], v[52:55]
	v_mfma_f32_16x16x32_bf16 v[48:51], v[238:241], v[166:169], v[48:51]
	v_mfma_f32_16x16x32_bf16 v[36:39], v[198:201], v[174:177], v[36:39]
	v_mfma_f32_16x16x32_bf16 v[32:35], v[238:241], v[174:177], v[32:35]
	v_mfma_f32_16x16x32_bf16 v[20:23], v[198:201], v[182:185], v[20:23]
	v_mfma_f32_16x16x32_bf16 v[16:19], v[238:241], v[182:185], v[16:19]
	v_mfma_f32_16x16x32_bf16 v[4:7], v[198:201], v[190:193], v[4:7]
	v_mfma_f32_16x16x32_bf16 v[0:3], v[238:241], v[190:193], v[0:3]
	v_mfma_f32_16x16x32_bf16 v[52:55], v[202:205], v[170:173], v[52:55]
	v_mfma_f32_16x16x32_bf16 v[48:51], v[242:245], v[170:173], v[48:51]
	v_mfma_f32_16x16x32_bf16 v[36:39], v[202:205], v[178:181], v[36:39]
	v_mfma_f32_16x16x32_bf16 v[32:35], v[242:245], v[178:181], v[32:35]
	v_mfma_f32_16x16x32_bf16 v[20:23], v[202:205], v[186:189], v[20:23]
	v_mfma_f32_16x16x32_bf16 v[16:19], v[242:245], v[186:189], v[16:19]
	v_mfma_f32_16x16x32_bf16 v[4:7], v[202:205], v[194:197], v[4:7]
	v_mfma_f32_16x16x32_bf16 v[0:3], v[242:245], v[194:197], v[0:3]
	s_setprio 0
	s_add_i32 vcc_hi, 0, 0x18000
	v_add_u32_e32 v162, vcc_hi, v159
	s_barrier
	ds_read_b128 v[144:147], v162
	ds_read_b128 v[148:151], v162 offset:1024
	ds_read_b128 v[152:155], v162 offset:2048
	ds_read_b128 v[162:165], v162 offset:3072
	s_add_u32 s34, s36, 0x20000
	s_addc_u32 s35, s37, 0
	s_mov_b32 m0, s78
	ds_read_b128 v[166:169], v161 offset:32768
	ds_read_b128 v[170:173], v161 offset:33792
	ds_read_b128 v[174:177], v161 offset:34816
	ds_read_b128 v[178:181], v161 offset:35840
	ds_read_b128 v[182:185], v161 offset:36864
	ds_read_b128 v[186:189], v161 offset:37888
	ds_read_b128 v[190:193], v161 offset:38912
	ds_read_b128 v[194:197], v161 offset:39936
	global_load_lds_dwordx4 v128, s[34:35]
	s_mov_b32 m0, s76
	s_nop 0
	global_load_lds_dwordx4 v132, s[34:35]
	s_waitcnt lgkmcnt(8)
	s_setprio 1
	s_barrier
	s_waitcnt lgkmcnt(0)
	v_mfma_f32_16x16x32_bf16 v[124:127], v[144:147], v[166:169], v[124:127]
	v_mfma_f32_16x16x32_bf16 v[120:123], v[152:155], v[166:169], v[120:123]
	v_mfma_f32_16x16x32_bf16 v[108:111], v[144:147], v[174:177], v[108:111]
	v_mfma_f32_16x16x32_bf16 v[104:107], v[152:155], v[174:177], v[104:107]
	v_mfma_f32_16x16x32_bf16 v[92:95], v[144:147], v[182:185], v[92:95]
	v_mfma_f32_16x16x32_bf16 v[88:91], v[152:155], v[182:185], v[88:91]
	v_mfma_f32_16x16x32_bf16 v[76:79], v[144:147], v[190:193], v[76:79]
	v_mfma_f32_16x16x32_bf16 v[72:75], v[152:155], v[190:193], v[72:75]
	v_mfma_f32_16x16x32_bf16 v[124:127], v[148:151], v[170:173], v[124:127]
	v_mfma_f32_16x16x32_bf16 v[120:123], v[162:165], v[170:173], v[120:123]
	v_mfma_f32_16x16x32_bf16 v[108:111], v[148:151], v[178:181], v[108:111]
	v_mfma_f32_16x16x32_bf16 v[104:107], v[162:165], v[178:181], v[104:107]
	v_mfma_f32_16x16x32_bf16 v[92:95], v[148:151], v[186:189], v[92:95]
	v_mfma_f32_16x16x32_bf16 v[88:91], v[162:165], v[186:189], v[88:91]
	v_mfma_f32_16x16x32_bf16 v[76:79], v[148:151], v[194:197], v[76:79]
	v_mfma_f32_16x16x32_bf16 v[72:75], v[162:165], v[194:197], v[72:75]
	s_setprio 0
	s_barrier
	s_add_i32 s34, 0, 0x1c000
	s_add_i32 s35, vcc_hi, s83
	v_add_u32_e32 v208, s34, v159
	s_mov_b32 m0, s35
	ds_read_b128 v[198:201], v208
	ds_read_b128 v[202:205], v208 offset:1024
	ds_read_b128 v[238:241], v208 offset:2048
	ds_read_b128 v[242:245], v208 offset:3072
	s_add_u32 s98, s28, 0x80
	s_addc_u32 s99, s29, 0
	global_load_lds_dwordx4 v130, s[98:99]
	s_add_i32 m0, s35, 0x2000
	s_add_u32 s100, s28, 0x80
	s_addc_u32 s101, s29, 0
	global_load_lds_dwordx4 v134, s[100:101]
	s_setprio 1
	s_barrier
	s_waitcnt lgkmcnt(0)
	v_mfma_f32_16x16x32_bf16 v[116:119], v[198:201], v[166:169], v[116:119]
	v_mfma_f32_16x16x32_bf16 v[112:115], v[238:241], v[166:169], v[112:115]
	v_mfma_f32_16x16x32_bf16 v[100:103], v[198:201], v[174:177], v[100:103]
	v_mfma_f32_16x16x32_bf16 v[96:99], v[238:241], v[174:177], v[96:99]
	v_mfma_f32_16x16x32_bf16 v[84:87], v[198:201], v[182:185], v[84:87]
	v_mfma_f32_16x16x32_bf16 v[80:83], v[238:241], v[182:185], v[80:83]
	v_mfma_f32_16x16x32_bf16 v[68:71], v[198:201], v[190:193], v[68:71]
	v_mfma_f32_16x16x32_bf16 v[64:67], v[238:241], v[190:193], v[64:67]
	v_mfma_f32_16x16x32_bf16 v[116:119], v[202:205], v[170:173], v[116:119]
	v_mfma_f32_16x16x32_bf16 v[112:115], v[242:245], v[170:173], v[112:115]
	v_mfma_f32_16x16x32_bf16 v[100:103], v[202:205], v[178:181], v[100:103]
	v_mfma_f32_16x16x32_bf16 v[96:99], v[242:245], v[178:181], v[96:99]
	v_mfma_f32_16x16x32_bf16 v[84:87], v[202:205], v[186:189], v[84:87]
	v_mfma_f32_16x16x32_bf16 v[80:83], v[242:245], v[186:189], v[80:83]
	v_mfma_f32_16x16x32_bf16 v[68:71], v[202:205], v[194:197], v[68:71]
	v_mfma_f32_16x16x32_bf16 v[64:67], v[242:245], v[194:197], v[64:67]
	s_setprio 0
	s_mov_b32 m0, s68
	s_barrier
	ds_read_b128 v[166:169], v161 offset:49152
	ds_read_b128 v[170:173], v161 offset:50176
	ds_read_b128 v[174:177], v161 offset:51200
	ds_read_b128 v[178:181], v161 offset:52224
	ds_read_b128 v[182:185], v161 offset:53248
	ds_read_b128 v[186:189], v161 offset:54272
	ds_read_b128 v[190:193], v161 offset:55296
	ds_read_b128 v[194:197], v161 offset:56320
	s_add_u32 s98, s36, 0x80
	s_addc_u32 s99, s37, 0
	global_load_lds_dwordx4 v128, s[98:99]
	s_mov_b32 m0, s74
	s_add_u32 s100, s36, 0x80
	s_addc_u32 s101, s37, 0
	global_load_lds_dwordx4 v132, s[100:101]
	s_setprio 1
	s_barrier
; __device__ __forceinline__ u32x4 pack8u(f32x4 a, f32x4 b) { u32x4 w = {cvt_pk_bf16(a[0], a[1]), cvt_pk_bf16(a[2], a[3]), cvt_pk_bf16(b[0], b[1]), cvt_pk_bf16(b[2], b[3])}; return w; }
; #define PG8_STAGE(bufoff, gbase, voff) do { _Pragma("unroll") for (int _i = 0; _i < 2; ++_i) \
;         __builtin_amdgcn_global_load_lds((const unsigned*)((const char*)(gbase) + (voff)[_i]), (LAS unsigned*)(lds + (bufoff) + ldsw + _i * 8192), 16, 0, 0); } while (0)
; #define PG8_LDA(dst, b, h) do { _Pragma("unroll") for (int m = 0; m < 4; ++m) _Pragma("unroll") for (int k = 0; k < 2; ++k) dst[m][k] = *(const LAS bf16x8*)(lds + PG8_SA(b, h) + aoff + m * 2048 + k * 1024); } while (0)
; #define PG8_WAIT_V(n) asm volatile("s_waitcnt vmcnt(" #n ")" ::: "memory")
; #define PG8_WAIT_L(n) asm volatile("s_waitcnt lgkmcnt(" #n ")" ::: "memory")
; #define PG8_BAR __builtin_amdgcn_s_barrier()
; #define PG8_SCHED __builtin_amdgcn_sched_barrier(0)
; template <class Epi>
; __device__ __forceinline__ void gemm_phase(LAS unsigned char* lds, const Gemm g, const Epi& E) {
;     ...
;             PG8_BAR; PG8_WAIT_L(0); PG8_MMA(0, 1, At, B1); PG8_BAR;
;             PG8_LDA(At, 1, 1); PG8_STAGE(PG8_SA(1, 0), a3, voffA);
;             PG8_BAR; PG8_WAIT_L(0); PG8_MMA(1, 0, At, B0); PG8_BAR; PG8_SCHED;
;             PG8_STAGE(PG8_SB(1, 1), b3 + hstep, voffB);
;             PG8_WAIT_V(6); PG8_BAR; PG8_MMA(1, 1, At, B1); PG8_BAR;
;     __device__ __forceinline__ void operator()(const AccT& acc, const Unit& u, int wr, int wc, int fr, int fq) const {
;     ...
;                 const int row = u.pm * 256 + ai * 128 + wr * 64 + m * 16 + fr; const int b = row / SEQ, t = row % SEQ;
;                 const f32x4 s0 = *(const f32x4*)(SSQ + (size_t)row * 16 + mode * 8), s1 = *(const f32x4*)(SSQ + (size_t)row * 16 + mode * 8 + 4);
;                 const float ssq = (s0[0] + s0[1]) + (s0[2] + s0[3]) + (s1[0] + s1[1]) + (s1[2] + s1[3]);
;                 float rs = rsqrtf(ssq * (1.0f / 512.0f) + EPS);
;     ...
;                     const size_t bh = (size_t)(b * NH + u.pn) * SEQ + t; const int d = wc * 32 + fq * 8;
;                     *(u32x4*)(Kb + bh * DQK + d) = pack8u(acc[ai][0][m][0] * rs, acc[ai][0][m][1] * rs);
;                     *(u32x4*)(Vb + bh * 128 + d) = pack8u(acc[ai][1][m][0] * rs, acc[ai][1][m][1] * rs);
	s_waitcnt lgkmcnt(0)
	v_mfma_f32_16x16x32_bf16 v[60:63], v[144:147], v[166:169], v[60:63]
	v_mfma_f32_16x16x32_bf16 v[56:59], v[152:155], v[166:169], v[56:59]
	v_mfma_f32_16x16x32_bf16 v[44:47], v[144:147], v[174:177], v[44:47]
	v_mfma_f32_16x16x32_bf16 v[40:43], v[152:155], v[174:177], v[40:43]
	v_mfma_f32_16x16x32_bf16 v[28:31], v[144:147], v[182:185], v[28:31]
	v_mfma_f32_16x16x32_bf16 v[24:27], v[152:155], v[182:185], v[24:27]
	v_mfma_f32_16x16x32_bf16 v[12:15], v[144:147], v[190:193], v[12:15]
	v_mfma_f32_16x16x32_bf16 v[8:11], v[152:155], v[190:193], v[8:11]
	v_mfma_f32_16x16x32_bf16 v[60:63], v[148:151], v[170:173], v[60:63]
	v_mfma_f32_16x16x32_bf16 v[56:59], v[162:165], v[170:173], v[56:59]
	v_mfma_f32_16x16x32_bf16 v[44:47], v[148:151], v[178:181], v[44:47]
	v_mfma_f32_16x16x32_bf16 v[40:43], v[162:165], v[178:181], v[40:43]
	v_mfma_f32_16x16x32_bf16 v[28:31], v[148:151], v[186:189], v[28:31]
	v_mfma_f32_16x16x32_bf16 v[24:27], v[162:165], v[186:189], v[24:27]
	v_mfma_f32_16x16x32_bf16 v[12:15], v[148:151], v[194:197], v[12:15]
	v_mfma_f32_16x16x32_bf16 v[8:11], v[162:165], v[194:197], v[8:11]
	s_setprio 0
	s_barrier
	s_add_u32 s28, s28, 0x20080
	s_addc_u32 s29, s29, 0
	s_add_i32 s34, s34, s83
	s_mov_b32 m0, s34
	s_nop 0
	global_load_lds_dwordx4 v130, s[28:29]
	s_add_i32 m0, s34, 0x2000
	s_nop 0
	global_load_lds_dwordx4 v134, s[28:29]
	s_waitcnt vmcnt(6)
	s_setprio 1
	s_barrier
	v_mfma_f32_16x16x32_bf16 v[52:55], v[198:201], v[166:169], v[52:55]
	v_mfma_f32_16x16x32_bf16 v[48:51], v[238:241], v[166:169], v[48:51]
	v_mfma_f32_16x16x32_bf16 v[36:39], v[198:201], v[174:177], v[36:39]
	v_mfma_f32_16x16x32_bf16 v[32:35], v[238:241], v[174:177], v[32:35]
	v_mfma_f32_16x16x32_bf16 v[20:23], v[198:201], v[182:185], v[20:23]
	v_mfma_f32_16x16x32_bf16 v[16:19], v[238:241], v[182:185], v[16:19]
	v_mfma_f32_16x16x32_bf16 v[4:7], v[198:201], v[190:193], v[4:7]
	v_mfma_f32_16x16x32_bf16 v[0:3], v[238:241], v[190:193], v[0:3]
	v_mfma_f32_16x16x32_bf16 v[52:55], v[202:205], v[170:173], v[52:55]
	v_mfma_f32_16x16x32_bf16 v[48:51], v[242:245], v[170:173], v[48:51]
	v_mfma_f32_16x16x32_bf16 v[36:39], v[202:205], v[178:181], v[36:39]
	v_mfma_f32_16x16x32_bf16 v[32:35], v[242:245], v[178:181], v[32:35]
	v_mfma_f32_16x16x32_bf16 v[20:23], v[202:205], v[186:189], v[20:23]
	v_mfma_f32_16x16x32_bf16 v[16:19], v[242:245], v[186:189], v[16:19]
	v_mfma_f32_16x16x32_bf16 v[4:7], v[202:205], v[194:197], v[4:7]
	v_mfma_f32_16x16x32_bf16 v[0:3], v[242:245], v[194:197], v[0:3]
	s_setprio 0
	s_add_i32 vcc_lo, vcc_lo, 2
	s_add_u32 s26, s26, 0x100
	s_addc_u32 s27, s27, 0
	s_add_u32 s45, s45, 0x100
	s_addc_u32 s65, s65, 0
	s_cmp_gt_u32 vcc_lo, 5
	s_barrier
	s_cbranch_scc0 .LBB0_499
	v_lshl_add_u32 v144, s0, 8, v158
	v_lshlrev_b32_e32 v220, 6, v144
	v_add_u32_e32 v221, 0x2000, v220
	global_load_dwordx4 v[176:179], v220, s[48:49] offset:16
	global_load_dwordx4 v[180:183], v220, s[48:49]
	global_load_dwordx4 v[184:187], v220, s[48:49] offset:1040
	global_load_dwordx4 v[188:191], v220, s[48:49] offset:1024
	global_load_dwordx4 v[192:195], v220, s[48:49] offset:2064
	global_load_dwordx4 v[196:199], v220, s[48:49] offset:2048
	global_load_dwordx4 v[200:203], v220, s[48:49] offset:3088
	global_load_dwordx4 v[204:207], v220, s[48:49] offset:3072
	v_ashrrev_i32_e32 v145, 31, v144
	v_lshlrev_b64 v[150:151], 6, v[144:145]
	v_lshl_add_u64 v[154:155], s[48:49], 0, v[150:151]
	s_waitcnt vmcnt(6)
	v_mov_b32_e32 v150, v176
	v_mov_b32_e32 v151, v177
	v_mov_b32_e32 v152, v178
	v_mov_b32_e32 v153, v179
	s_nop 0
	v_mov_b32_e32 v154, v180
	v_mov_b32_e32 v155, v181
	v_mov_b32_e32 v156, v182
	v_mov_b32_e32 v157, v183
	global_load_dwordx4 v[176:179], v221, s[48:49] offset:16
	global_load_dwordx4 v[180:183], v221, s[48:49]
	v_lshrrev_b32_e32 v146, 21, v145
	v_add_u32_e32 v146, v144, v146
	v_ashrrev_i32_e32 v149, 11, v146
	v_mul_i32_i24_e32 v146, 0x800, v149
	v_sub_u32_e32 v146, v144, v146
	s_mov_b64 s[0:1], -1
	s_nop 0
	v_mov_b32_e32 v162, v155
	v_mov_b32_e32 v163, v156
	v_mov_b32_e32 v155, v157
	v_pk_add_f32 v[154:155], v[162:163], v[154:155]
	v_mov_b32_e32 v156, v152
	v_mov_b32_e32 v157, v150
	v_mov_b32_e32 v150, v153
	v_pk_add_f32 v[150:151], v[156:157], v[150:151]
	v_add_f32_e32 v147, v154, v155
	v_add_f32_e32 v147, v147, v151
	v_add_f32_e32 v147, v150, v147
	v_fmamk_f32 v147, v147, 0x3b000000, v223
	v_cmp_gt_f32_e32 vcc, s60, v147
	v_mul_f32_e32 v148, 0x4b800000, v147
	s_nop 0
	v_cndmask_b32_e32 v147, v147, v148, vcc
	v_rsq_f32_e32 v147, v147
	s_nop 0
	v_mul_f32_e32 v148, 0x45800000, v147
	v_cndmask_b32_e32 v148, v147, v148, vcc
	s_and_b64 vcc, exec, s[46:47]
	v_ashrrev_i32_e32 v147, 31, v146
	s_cbranch_vccz .LBB0_502
	v_lshl_add_u32 v150, v149, 3, s94
	v_ashrrev_i32_e32 v151, 31, v150
	v_lshlrev_b64 v[150:151], 11, v[150:151]
	v_lshl_add_u64 v[154:155], v[150:151], 0, v[146:147]
	v_pk_mul_f32 v[152:153], v[126:127], v[148:149] op_sel_hi:[1,0]
	v_pk_mul_f32 v[150:151], v[124:125], v[148:149] op_sel_hi:[1,0]
	v_pk_mul_f32 v[156:157], v[122:123], v[148:149] op_sel_hi:[1,0]
	v_pk_mul_f32 v[162:163], v[120:121], v[148:149] op_sel_hi:[1,0]
	v_cvt_pk_bf16_f32 v150, v150, v151
	v_cvt_pk_bf16_f32 v151, v152, v153
	v_cvt_pk_bf16_f32 v153, v156, v157
	v_mad_u64_u32 v[156:157], s[0:1], v154, s33, v[136:137]
	v_cvt_pk_bf16_f32 v152, v162, v163
	v_mad_i32_i24 v157, v155, s33, v157
	global_store_dwordx4 v[156:157], v[150:153], off
	v_pk_mul_f32 v[156:157], v[114:115], v[148:149] op_sel_hi:[1,0]
	v_pk_mul_f32 v[162:163], v[112:113], v[148:149] op_sel_hi:[1,0]
	v_pk_mul_f32 v[152:153], v[118:119], v[148:149] op_sel_hi:[1,0]
	v_pk_mul_f32 v[150:151], v[116:117], v[148:149] op_sel_hi:[1,0]
	v_lshlrev_b64 v[154:155], 8, v[154:155]
	v_cvt_pk_bf16_f32 v150, v150, v151
	v_cvt_pk_bf16_f32 v151, v152, v153
	v_cvt_pk_bf16_f32 v152, v162, v163
	v_cvt_pk_bf16_f32 v153, v156, v157
	v_lshl_add_u64 v[154:155], v[138:139], 0, v[154:155]
	global_store_dwordx4 v[154:155], v[150:153], off
	s_mov_b64 s[0:1], 0

; #define LAS __attribute__((address_space(3)))
; __device__ __forceinline__ void prep_unit(LAS unsigned char* lds, const Params& p, int l, int unit) {
;     ...
;     const int b = unit / (NH * NCH), h = (unit / NCH) % NH, n = unit % NCH;
;     const int row0 = b * SEQ + n * CHK;
;     LAS float* Xq = (LAS float*)(lds + OFF_XQ); LAS float* Xk = (LAS float*)(lds + OFF_XK); LAS float* Xv = (LAS float*)(lds + OFF_XV);
;     LAS float* Lm = (LAS float*)(lds + OFF_LM); LAS float* beta = (LAS float*)(lds + OFF_BETA); LAS float* Gc = (LAS float*)(lds + OFF_G); LAS float* eG = (LAS float*)(lds + OFF_EG);
;     const bf16_t* QKVG = (const bf16_t*)(p.ws + AR_QKVG); const float* BA = (const float*)(p.ws + WS_BA);
;     float* U = (float*)(p.ws + WS_H); bf16_t* Wg = (bf16_t*)(p.ws + AR_WG); bf16_t* QG = (bf16_t*)(p.ws + AR_QG); bf16_t* KDT = (bf16_t*)(p.ws + AR_KDT); bf16_t* ATT = (bf16_t*)(p.ws + AR_ATT);
;     float* EGL = (float*)(p.ws + WS_EGL);
;     ...
;     for (int rpc = 0; rpc < (PROBE_SEL == 7 ? 2 : 1); ++rpc)
;     if (tid < 384) {
;         const int cgp = tid % 48, rg = tid / 48, mat = cgp / 16, c8 = (cgp % 16) * 8, col = mat * 1024 + h * 128 + c8;
;         float wj[4][8];
; #pragma unroll
;         for (int j = 0; j < 4; ++j) { const float* wp = p.conv_w + ((size_t)l * 4 + j) * 3072 + col; const f32x4 a = *(const f32x4*)wp, c = *(const f32x4*)(wp + 4);
;             wj[j][0] = a[0]; wj[j][1] = a[1]; wj[j][2] = a[2]; wj[j][3] = a[3]; wj[j][4] = c[0]; wj[j][5] = c[1]; wj[j][6] = c[2]; wj[j][7] = c[3]; }
;         float u[11][8];
; #pragma unroll
;         for (int k = 0; k < 11; ++k) { const int tt = n * CHK + rg * 8 - 3 + k;
;             u32x4 w = {0u, 0u, 0u, 0u};
;             if (tt >= 0) w = *(const u32x4*)(QKVG + (size_t)(b * SEQ + tt) * 3072 + col);
;     ...
;         const float bl = BA[(size_t)(row0 + lane) * 16 + h], al = BA[(size_t)(row0 + lane) * 16 + 8 + h];
;         const float xx = al + p.dt_bias[l * NH + h];
;         const float sp = fmaxf(xx, 0.f) + log1pf(__expf(-fabsf(xx)));
;         const float g0 = -__expf(p.A_log[l * NH + h]) * sp;
.LBB0_600:
	s_ashr_i32 s43, s42, 31
	s_lshr_b32 s1, s43, 27
	s_add_i32 s1, s42, s1
	s_ashr_i32 s3, s1, 5
	s_lshr_b32 s0, s43, 24
	s_lshr_b32 s26, s3, 29
	s_add_i32 s0, s42, s0
	s_add_i32 s26, s3, s26
	s_and_b32 s1, s1, 0x3ffffe0
	v_mov_b32_e32 v110, v222
	s_and_b32 s26, s26, -8
	s_sub_i32 s1, s42, s1
	s_lshl_b32 s0, s0, 3
	s_sub_i32 s44, s3, s26
	s_and_b32 s3, s0, 0xfffff800
	s_lshl_b32 s28, s1, 6
	v_cmp_gt_u32_e32 vcc, 64, v110
	s_and_saveexec_b64 s[98:99], vcc
	s_cbranch_execz .Lprep_ba_skip
	s_add_i32 s100, s3, s28
	v_or_b32_e32 v200, s100, v110
	v_ashrrev_i32_e32 v201, 31, v200
	v_readlane_b32 s100, v253, 15
	v_lshlrev_b64 v[200:201], 6, v[200:201]
	v_readlane_b32 s101, v253, 16
	v_lshlrev_b32_e64 v202, 2, s44
	v_mov_b32_e32 v203, 0
	s_nop 1
	v_lshl_add_u64 v[200:201], s[100:101], 0, v[200:201]
	v_lshl_add_u64 v[200:201], v[200:201], 0, v[202:203]
	global_load_dword v204, v[200:201], off offset:32
	global_load_dword v205, v[200:201], off
	s_add_i32 s100, s44, s2
	s_lshl_b32 s100, s100, 2
	v_mov_b32_e32 v202, s100
	global_load_dword v206, v202, s[18:19]
	global_load_dword v207, v202, s[16:17]
.Lprep_ba_skip:
	s_or_b64 exec, exec, s[98:99]
	v_cmp_gt_i32_e32 vcc, s33, v110
	s_and_saveexec_b64 s[46:47], vcc
	s_cbranch_execz .LBB0_624
	v_mul_hi_i32 v0, v110, s80
	v_lshrrev_b32_e32 v1, 31, v0
	v_ashrrev_i32_e32 v0, 3, v0
	v_add_u32_e32 v111, v0, v1
	v_mul_lo_u32 v0, v111, 48
	v_sub_u32_e32 v113, v110, v0
	v_mov_b32_e32 v0, 11
	v_lshrrev_b16_sdwa v0, v0, sext(v113) dst_sel:DWORD dst_unused:UNUSED_PAD src0_sel:DWORD src1_sel:BYTE_0
	v_and_b32_e32 v0, 15, v0
	v_add_u16_e32 v0, v113, v0
	v_mov_b32_e32 v1, 4
	v_ashrrev_i16_sdwa v1, v1, sext(v0) dst_sel:DWORD dst_unused:UNUSED_PAD src0_sel:DWORD src1_sel:BYTE_0
	v_and_b32_e32 v0, 0xf0, v0
	v_sub_u16_e32 v0, v113, v0
	v_mov_b32_e32 v2, 3
	v_lshlrev_b32_sdwa v112, v2, sext(v0) dst_sel:DWORD dst_unused:UNUSED_PAD src0_sel:DWORD src1_sel:BYTE_0
	v_mov_b32_e32 v0, 10
	v_lshlrev_b32_sdwa v0, v0, sext(v1) dst_sel:DWORD dst_unused:UNUSED_PAD src0_sel:DWORD src1_sel:WORD_0
	s_lshl_b32 s0, s44, 7
	v_add3_u32 v34, v0, s0, v112
	v_ashrrev_i32_e32 v35, 31, v34
	v_lshl_add_u64 v[12:13], v[34:35], 2, s[40:41]
	v_add_co_u32_e32 v6, vcc, 0x3000, v12
	s_mov_b64 s[0:1], 0x3000
	s_nop 0
	v_addc_co_u32_e32 v7, vcc, 0, v13, vcc
	v_add_co_u32_e32 v10, vcc, 0x6000, v12
	v_lshl_add_u64 v[4:5], v[12:13], 0, s[0:1]
	s_nop 0
	v_addc_co_u32_e32 v11, vcc, 0, v13, vcc
	s_mov_b64 s[0:1], 0x9000
	global_load_dwordx4 v[0:3], v[12:13], off offset:16
	global_load_dwordx4 v[16:19], v[12:13], off
	v_lshl_add_u64 v[8:9], v[12:13], 0, s[56:57]
	v_lshl_add_u64 v[14:15], v[12:13], 0, s[0:1]
	v_add_co_u32_e32 v12, vcc, 0x9000, v12
	global_load_dwordx4 v[20:23], v[6:7], off
	s_nop 0
	global_load_dwordx4 v[4:7], v[4:5], off offset:16
	v_addc_co_u32_e32 v13, vcc, 0, v13, vcc
	global_load_dwordx4 v[24:27], v[10:11], off
	s_nop 0
	global_load_dwordx4 v[8:11], v[8:9], off offset:16
	s_nop 0
	global_load_dwordx4 v[28:31], v[12:13], off
	s_nop 0
	global_load_dwordx4 v[12:15], v[14:15], off offset:16
	v_lshl_add_u32 v32, v111, 3, s28
	v_readlane_b32 s0, v252, 37
	v_add_u32_e32 v78, -3, v32
	v_readlane_b32 s1, v252, 38
	v_cmp_lt_i32_e32 vcc, 2, v32
	v_mov_b32_e32 v40, 0
	v_lshl_add_u64 v[76:77], v[34:35], 1, s[0:1]
	v_add_u32_e32 v33, s3, v78
	v_mov_b32_e32 v36, 0
	v_mov_b32_e32 v37, 0
	v_mov_b32_e32 v38, 0
	v_mov_b32_e32 v39, 0
	s_and_saveexec_b64 s[0:1], vcc
	s_cbranch_execz .LBB0_603
	s_movk_i32 s26, 0x1800
	v_mad_i64_i32 v[34:35], s[26:27], v33, s26, v[76:77]
	global_load_dwordx4 v[36:39], v[34:35], off

; #define LAS __attribute__((address_space(3)))
; __device__ __forceinline__ float siluf_(float x) { return x * __builtin_amdgcn_rcpf(1.0f + __expf(-x)); }
; template <int M> __device__ __forceinline__ float swz(float v) { return __int_as_float(__builtin_amdgcn_ds_swizzle(__float_as_int(v), (M << 10) | 0x1F)); }
; #define LDS_BAR() do { asm volatile("s_waitcnt lgkmcnt(0)" ::: "memory"); __builtin_amdgcn_s_barrier(); asm volatile("" ::: "memory"); } while (0)
; __device__ __forceinline__ void prep_unit(LAS unsigned char* lds, const Params& p, int l, int unit) {
;     ...
;         for (int i = 0; i < 8; ++i) { f32x4 y0, y1;
; #pragma unroll
;             for (int c = 0; c < 8; ++c) { float y = wj[0][c] * u[i][c] + wj[1][c] * u[i + 1][c] + wj[2][c] * u[i + 2][c] + wj[3][c] * u[i + 3][c]; y = siluf_(y); if (c < 4) y0[c] = y; else y1[c - 4] = y; }
;             *(LAS f32x4*)(X + (rg * 8 + i) * XS + c8) = y0; *(LAS f32x4*)(X + (rg * 8 + i) * XS + c8 + 4) = y1; }
;     }
;     ...
;     LDS_BAR();
; #pragma unroll
;     for (int mat = 0; mat < 2; ++mat) { LAS float* X = (mat ? Xk : Xq) + (tid >> 3) * XS + (tid & 7) * 16;
;         f32x4 v[4]; float s = 0.f;
; #pragma unroll
;         for (int j = 0; j < 4; ++j) { v[j] = *(const LAS f32x4*)(X + 4 * j); s += (v[j][0] * v[j][0] + v[j][1] * v[j][1]) + (v[j][2] * v[j][2] + v[j][3] * v[j][3]); }
;         s += swz<1>(s); s += swz<2>(s); s += swz<4>(s);
;         const float sc = rsqrtf(s + EPS) * (mat ? 1.0f : 0.08838834764831845f);
; #pragma unroll
;         for (int j = 0; j < 4; ++j) *(LAS f32x4*)(X + 4 * j) = v[j] * sc; }
;     if (wid == 0) {
.LBB0_624:
	s_or_b64 exec, exec, s[46:47]
	v_lshrrev_b32_e32 v0, 3, v110
	s_movk_i32 s0, 0x210
	v_lshlrev_b32_e32 v1, 6, v110
	v_mul_lo_u32 v0, v0, s0
	v_and_b32_e32 v1, 0x1c0, v1
	s_waitcnt lgkmcnt(0)
	s_barrier
	v_add3_u32 v42, 0, v0, v1
	ds_read_b128 v[2:5], v42
	ds_read_b128 v[6:9], v42 offset:16
	ds_read_b128 v[10:13], v42 offset:32
	ds_read_b128 v[14:17], v42 offset:48
	s_mov_b32 s0, 0x358637bd
	s_waitcnt lgkmcnt(3)
	v_pk_mul_f32 v[0:1], v[4:5], v[4:5]
	v_pk_mul_f32 v[18:19], v[2:3], v[2:3]
	s_waitcnt lgkmcnt(0)
	v_mul_f32_e32 v24, v16, v16
	v_pk_mov_b32 v[20:21], v[18:19], v[0:1] op_sel:[1,0]
	v_mov_b32_e32 v19, v1
	v_pk_add_f32 v[0:1], v[20:21], v[18:19]
	v_pk_mul_f32 v[18:19], v[8:9], v[8:9]
	v_pk_mul_f32 v[20:21], v[6:7], v[6:7]
	v_pk_add_f32 v[0:1], v[0:1], v[0:1] op_sel:[0,1] op_sel_hi:[1,0]
	v_pk_mov_b32 v[22:23], v[20:21], v[18:19] op_sel:[1,0]
	v_mov_b32_e32 v21, v19
	v_pk_add_f32 v[18:19], v[22:23], v[20:21]
	v_mul_f32_e32 v20, v14, v14
	v_mul_f32_e32 v21, v15, v15
	v_pk_add_f32 v[18:19], v[18:19], v[18:19] op_sel:[0,1] op_sel_hi:[1,0]
	v_mov_b32_e32 v1, v20
	v_mov_b32_e32 v19, v21
	v_pk_add_f32 v[0:1], v[0:1], v[18:19]
	v_mul_f32_e32 v18, v11, v11
	v_pk_fma_f32 v[22:23], v[10:11], v[10:11], v[18:19] op_sel_hi:[1,1,0]
	v_mul_f32_e32 v18, v13, v13
	v_mov_b32_e32 v23, v24
	v_pk_fma_f32 v[24:25], v[12:13], v[12:13], v[18:19] op_sel_hi:[1,1,0]
	ds_read_b128 v[18:21], v42 offset:33792
	v_mul_f32_e32 v26, v17, v17
	v_mov_b32_e32 v25, v26
	v_pk_add_f32 v[22:23], v[22:23], v[24:25]
	s_nop 0
	v_pk_add_f32 v[0:1], v[0:1], v[22:23]
	ds_read_b128 v[22:25], v42 offset:33808
	s_waitcnt lgkmcnt(1)
	v_pk_mul_f32 v[26:27], v[20:21], v[20:21]
	v_pk_mul_f32 v[28:29], v[18:19], v[18:19]
	s_waitcnt lgkmcnt(0)
	v_pk_mul_f32 v[36:37], v[24:25], v[24:25]
	v_pk_mov_b32 v[30:31], v[28:29], v[26:27] op_sel:[1,0]
	v_mov_b32_e32 v29, v27
	v_pk_add_f32 v[34:35], v[30:31], v[28:29]
	ds_read_b128 v[26:29], v42 offset:33824
	ds_read_b128 v[30:33], v42 offset:33840
	v_pk_mul_f32 v[38:39], v[22:23], v[22:23]
	v_pk_add_f32 v[34:35], v[34:35], v[34:35] op_sel:[0,1] op_sel_hi:[1,0]
	v_pk_mov_b32 v[40:41], v[38:39], v[36:37] op_sel:[1,0]
	v_mov_b32_e32 v39, v37
	v_pk_add_f32 v[36:37], v[40:41], v[38:39]
	s_waitcnt lgkmcnt(0)
	v_mul_f32_e32 v38, v30, v30
	v_mul_f32_e32 v39, v31, v31
	v_pk_add_f32 v[36:37], v[36:37], v[36:37] op_sel:[0,1] op_sel_hi:[1,0]
	v_mov_b32_e32 v35, v38
	v_mov_b32_e32 v37, v39
	v_pk_add_f32 v[34:35], v[34:35], v[36:37]
	v_mul_f32_e32 v36, v27, v27
	v_mul_f32_e32 v38, v29, v29
	v_mul_f32_e32 v40, v32, v32
	v_mul_f32_e32 v41, v33, v33
	v_pk_fma_f32 v[36:37], v[26:27], v[26:27], v[36:37] op_sel_hi:[1,1,0]
	v_pk_fma_f32 v[38:39], v[28:29], v[28:29], v[38:39] op_sel_hi:[1,1,0]
	v_mov_b32_e32 v37, v40
	v_mov_b32_e32 v39, v41
	v_pk_add_f32 v[36:37], v[36:37], v[38:39]
	s_nop 0
	v_pk_add_f32 v[34:35], v[34:35], v[36:37]
	v_mov_b32_e32 v37, v0
	v_mov_b32_e32 v36, v34
	v_mov_b32_e32 v0, v35
	v_pk_add_f32 v[0:1], v[36:37], v[0:1]
	ds_swizzle_b32 v35, v1 offset:swizzle(SWAP,1)
	ds_swizzle_b32 v34, v0 offset:swizzle(SWAP,1)
	s_waitcnt lgkmcnt(0)
	v_pk_add_f32 v[0:1], v[0:1], v[34:35]
	ds_swizzle_b32 v35, v1 offset:swizzle(SWAP,2)
	ds_swizzle_b32 v34, v0 offset:swizzle(SWAP,2)
	s_waitcnt lgkmcnt(0)
	v_pk_add_f32 v[0:1], v[0:1], v[34:35]
	ds_swizzle_b32 v35, v1 offset:swizzle(SWAP,4)
	ds_swizzle_b32 v34, v0 offset:swizzle(SWAP,4)
	s_waitcnt lgkmcnt(0)
	v_pk_add_f32 v[0:1], v[0:1], v[34:35]
	s_nop 0
	v_pk_add_f32 v[34:35], v[0:1], s[0:1] op_sel_hi:[1,0]
	s_nop 0
	v_mul_f32_e32 v0, 0x4b800000, v35
	v_cmp_gt_f32_e32 vcc, s60, v35
	s_nop 1
	v_cndmask_b32_e32 v0, v35, v0, vcc
	v_rsq_f32_e32 v1, v0
	v_and_b32_e32 v0, 63, v110
	v_mul_f32_e32 v35, 0x45800000, v1
	v_cndmask_b32_e32 v1, v1, v35, vcc
	v_mul_f32_e32 v36, 0x3db504f3, v1
	v_mul_f32_e32 v1, 0x4b800000, v34
	v_cmp_gt_f32_e32 vcc, s60, v34
	v_pk_mul_f32 v[4:5], v[4:5], v[36:37] op_sel_hi:[1,0]
	v_pk_mul_f32 v[2:3], v[2:3], v[36:37] op_sel_hi:[1,0]
	v_cndmask_b32_e32 v1, v34, v1, vcc
	v_rsq_f32_e32 v1, v1
	ds_write_b128 v42, v[2:5]
	v_pk_mul_f32 v[4:5], v[8:9], v[36:37] op_sel_hi:[1,0]
	v_pk_mul_f32 v[2:3], v[6:7], v[36:37] op_sel_hi:[1,0]
	ds_write_b128 v42, v[2:5] offset:16
	v_pk_mul_f32 v[4:5], v[12:13], v[36:37] op_sel_hi:[1,0]
	v_pk_mul_f32 v[2:3], v[10:11], v[36:37] op_sel_hi:[1,0]
	ds_write_b128 v42, v[2:5] offset:32
	v_pk_mul_f32 v[4:5], v[16:17], v[36:37] op_sel_hi:[1,0]
	v_pk_mul_f32 v[2:3], v[14:15], v[36:37] op_sel_hi:[1,0]
	ds_write_b128 v42, v[2:5] offset:48
	v_mul_f32_e32 v2, 0x45800000, v1
	v_cndmask_b32_e32 v6, v1, v2, vcc
	v_pk_mul_f32 v[4:5], v[20:21], v[6:7] op_sel_hi:[1,0]
	v_pk_mul_f32 v[2:3], v[18:19], v[6:7] op_sel_hi:[1,0]
	ds_write_b128 v42, v[2:5] offset:33792
	v_pk_mul_f32 v[4:5], v[24:25], v[6:7] op_sel_hi:[1,0]
	v_pk_mul_f32 v[2:3], v[22:23], v[6:7] op_sel_hi:[1,0]
	ds_write_b128 v42, v[2:5] offset:33808
	v_pk_mul_f32 v[4:5], v[28:29], v[6:7] op_sel_hi:[1,0]
	v_pk_mul_f32 v[2:3], v[26:27], v[6:7] op_sel_hi:[1,0]
	ds_write_b128 v42, v[2:5] offset:33824
	v_pk_mul_f32 v[4:5], v[32:33], v[6:7] op_sel_hi:[1,0]
	v_pk_mul_f32 v[2:3], v[30:31], v[6:7] op_sel_hi:[1,0]
	v_cmp_gt_u32_e32 vcc, 64, v110
	ds_write_b128 v42, v[2:5] offset:33840
	s_and_saveexec_b64 s[0:1], vcc
	s_cbranch_execz .LBB0_629
; __device__ __forceinline__ void prep_unit(LAS unsigned char* lds, const Params& p, int l, int unit) {
;     ...
;     if (wid == 0) {
;         const float bl = BA[(size_t)(row0 + lane) * 16 + h], al = BA[(size_t)(row0 + lane) * 16 + 8 + h];
;         const float xx = al + p.dt_bias[l * NH + h];
;         const float sp = fmaxf(xx, 0.f) + log1pf(__expf(-fabsf(xx)));
;         const float g0 = -__expf(p.A_log[l * NH + h]) * sp;
;         Gc[lane] = g0; asm volatile("s_waitcnt lgkmcnt(0)" ::: "memory");
	s_add_i32 s3, s3, s28
	v_or_b32_e32 v2, s3, v110
	v_ashrrev_i32_e32 v3, 31, v2
	v_readlane_b32 s26, v253, 15
	v_lshlrev_b64 v[2:3], 6, v[2:3]
	v_readlane_b32 s27, v253, 16
	s_ashr_i32 s45, s44, 31
	s_mov_b32 s3, 0
	v_lshl_add_u64 v[2:3], s[26:27], 0, v[2:3]
	s_add_i32 s26, s44, s2
	s_ashr_i32 s27, s26, 31
	s_lshl_b64 s[26:27], s[26:27], 2
	s_add_u32 s28, s18, s26
	v_lshl_add_u64 v[4:5], s[44:45], 2, v[2:3]
	s_addc_u32 s29, s19, s27
	v_mov_b32_e32 v3, v204
	v_mov_b32_e32 v1, v205
	v_mov_b32_e32 v6, v206
	s_add_u32 s26, s16, s26
	s_addc_u32 s27, s17, s27
	v_mov_b32_e32 v7, v207
	s_mov_b32 s26, 0xbfb8aa3b
	v_mov_b32_e32 v2, 0
	s_waitcnt vmcnt(1)
	v_add_f32_e32 v3, v3, v6
	v_mul_f32_e64 v4, |v3|, s26
	v_exp_f32_e32 v4, v4
	s_waitcnt vmcnt(0)
	v_mul_f32_e32 v5, 0x3fb8aa3b, v7
	s_mov_b32 s26, 0x3f2aaaab
	v_exp_f32_e32 v5, v5
	v_add_f32_e32 v8, 1.0, v4
	v_add_f32_e32 v9, -1.0, v8
	v_frexp_mant_f32_e32 v10, v8
	v_cvt_f64_f32_e32 v[6:7], v8
	v_sub_f32_e32 v11, v9, v8
	v_frexp_exp_i32_f64_e32 v6, v[6:7]
	v_cmp_gt_f32_e32 vcc, s26, v10
	v_sub_f32_e32 v9, v4, v9
	v_add_f32_e32 v7, 1.0, v11
	v_subbrev_co_u32_e32 v6, vcc, 0, v6, vcc
	v_add_f32_e32 v7, v9, v7
	v_sub_u32_e32 v9, 0, v6
	v_ldexp_f32 v8, v8, v9
	v_add_f32_e32 v10, -1.0, v8
	v_add_f32_e32 v11, 1.0, v8
	v_ldexp_f32 v7, v7, v9
	v_add_f32_e32 v9, 1.0, v10
	v_add_f32_e32 v12, -1.0, v11
	v_sub_f32_e32 v9, v8, v9
	v_sub_f32_e32 v8, v8, v12
	v_add_f32_e32 v12, v7, v9
	v_add_f32_e32 v7, v7, v8
	v_add_f32_e32 v14, v11, v7
	v_rcp_f32_e32 v15, v14
	v_add_f32_e32 v9, v10, v12
	v_sub_f32_e32 v10, v9, v10
	v_sub_f32_e32 v8, v14, v11
	v_mul_f32_e32 v17, v9, v15
	v_sub_f32_e32 v16, v12, v10
	v_mul_f32_e32 v10, v14, v17
	v_sub_f32_e32 v7, v7, v8
	v_fma_f32 v12, v17, v14, -v10
	v_fmac_f32_e32 v12, v17, v7
	v_add_f32_e32 v8, v10, v12
	v_sub_f32_e32 v11, v9, v8
	v_mov_b32_e32 v13, v8
	v_pk_add_f32 v[8:9], v[8:9], v[10:11] neg_lo:[0,1] neg_hi:[0,1]
	v_cvt_f32_i32_e32 v6, v6
	v_pk_add_f32 v[8:9], v[8:9], v[12:13] neg_lo:[0,1] neg_hi:[0,1]
	s_mov_b32 s26, 0x3f317218
	v_add_f32_e32 v9, v16, v9
	v_add_f32_e32 v8, v8, v9
	v_add_f32_e32 v9, v11, v8
	v_mul_f32_e32 v13, v15, v9
	v_mul_f32_e32 v10, v14, v13
	v_sub_f32_e32 v11, v11, v9
	v_add_f32_e32 v18, v17, v13
	v_fma_f32 v12, v13, v14, -v10
	v_add_f32_e32 v16, v8, v11
	v_sub_f32_e32 v8, v18, v17
	v_fmac_f32_e32 v12, v13, v7
	v_sub_f32_e32 v7, v13, v8
	v_add_f32_e32 v8, v10, v12
	v_sub_f32_e32 v11, v9, v8
	v_mov_b32_e32 v13, v8
	v_pk_add_f32 v[8:9], v[8:9], v[10:11] neg_lo:[0,1] neg_hi:[0,1]
	v_max_f32_e32 v3, 0, v3
	v_pk_add_f32 v[8:9], v[8:9], v[12:13] neg_lo:[0,1] neg_hi:[0,1]
	v_mov_b32_e32 v12, 0x3ecc95a3
	v_add_f32_e32 v9, v16, v9
	v_add_f32_e32 v8, v8, v9
	v_add_f32_e32 v8, v11, v8
	v_mul_f32_e32 v8, v15, v8
	v_add_f32_e32 v7, v7, v8
	v_add_f32_e32 v8, v18, v7
	v_mul_f32_e32 v10, v8, v8
	v_sub_f32_e32 v11, v8, v18
	v_fmamk_f32 v12, v10, 0x3e9b6dac, v12
	v_sub_f32_e32 v11, v7, v11
	v_mul_f32_e32 v7, v8, v10
	v_fmaak_f32 v215, v10, v12, 0x3f2aaada
	v_ldexp_f32 v13, v11, 1
	v_pk_mul_f32 v[10:11], v[6:7], v[214:215]
	v_ldexp_f32 v9, v8, 1
	v_fma_f32 v8, v6, s26, -v10
	v_fmac_f32_e32 v8, 0xb102e308, v6
	v_pk_add_f32 v[6:7], v[10:11], v[8:9]
	v_mov_b32_e32 v12, v10
	v_sub_f32_e32 v16, v7, v9
	v_pk_add_f32 v[14:15], v[6:7], v[10:11] neg_lo:[0,1] neg_hi:[0,1]
	v_sub_f32_e32 v10, v11, v16
	v_add_f32_e32 v13, v13, v10
	v_pk_add_f32 v[10:11], v[6:7], v[12:13]
	v_mov_b32_e32 v9, v6
	v_mov_b32_e32 v15, v11
	v_pk_add_f32 v[18:19], v[8:9], v[14:15] neg_lo:[0,1] neg_hi:[0,1]
	v_pk_add_f32 v[8:9], v[8:9], v[14:15]
	v_mov_b32_e32 v17, v6
	v_pk_add_f32 v[14:15], v[8:9], v[6:7] op_sel:[1,0] op_sel_hi:[0,1] neg_lo:[0,1] neg_hi:[0,1]
	v_mov_b32_e32 v16, v13
	v_mov_b32_e32 v12, v11
	v_mov_b32_e32 v13, v9
	v_pk_mov_b32 v[6:7], v[6:7], v[14:15] op_sel:[1,0]
	v_pk_add_f32 v[10:11], v[10:11], v[14:15] op_sel_hi:[1,0] neg_lo:[0,1] neg_hi:[0,1]
	v_pk_add_f32 v[6:7], v[12:13], v[6:7] neg_lo:[0,1] neg_hi:[0,1]
	v_mov_b32_e32 v10, v18
	v_pk_add_f32 v[6:7], v[16:17], v[6:7] neg_lo:[0,1] neg_hi:[0,1]
	v_mov_b32_e32 v19, v9
	v_pk_add_f32 v[10:11], v[10:11], v[6:7]
	s_mov_b32 s26, 0x7f800000
	v_pk_add_f32 v[12:13], v[10:11], v[10:11] op_sel:[0,1] op_sel_hi:[1,0]
	v_cmp_neq_f32_e32 vcc, s26, v4
	v_pk_add_f32 v[8:9], v[8:9], v[12:13] op_sel:[1,0] op_sel_hi:[0,1]
	v_mov_b32_e32 v11, v8
	v_mov_b32_e32 v7, v12
	v_pk_add_f32 v[12:13], v[10:11], v[18:19] neg_lo:[0,1] neg_hi:[0,1]
	s_mov_b32 s26, 0x33800000
	v_sub_f32_e32 v9, v10, v12
	v_pk_add_f32 v[6:7], v[6:7], v[12:13] neg_lo:[0,1] neg_hi:[0,1]
	v_sub_f32_e32 v9, v18, v9
	v_add_f32_e32 v6, v6, v9
	v_add_f32_e32 v6, v6, v7
	v_add_f32_e32 v6, v8, v6
	v_mov_b32_e32 v7, 0x7f800000
	v_cndmask_b32_e32 v6, v7, v6, vcc
	v_cmp_ngt_f32_e32 vcc, -1.0, v4
	v_mov_b32_e32 v7, 0x7fc00000
	s_nop 0
	v_cndmask_b32_e32 v6, v7, v6, vcc
	v_cmp_neq_f32_e32 vcc, -1.0, v4
	s_nop 1
	v_cndmask_b32_e32 v6, v225, v6, vcc
	v_cmp_lt_f32_e64 vcc, |v4|, s26
	v_readlane_b32 s26, v255, 14
	s_nop 0
	v_cndmask_b32_e32 v4, v6, v4, vcc
	v_add_f32_e32 v3, v3, v4
	v_mul_f32_e64 v4, v3, -v5
	v_lshl_add_u32 v3, v0, 2, s26
	ds_write_b32 v3, v4
	s_waitcnt lgkmcnt(0)

; #define PG8_STAGE(bufoff, gbase, voff) do { _Pragma("unroll") for (int _i = 0; _i < 2; ++_i) \
;         __builtin_amdgcn_global_load_lds((const unsigned*)((const char*)(gbase) + (voff)[_i]), (LAS unsigned*)(lds + (bufoff) + ldsw + _i * 8192), 16, 0, 0); } while (0)
; #define PG8_LDA(dst, b, h) do { _Pragma("unroll") for (int m = 0; m < 4; ++m) _Pragma("unroll") for (int k = 0; k < 2; ++k) dst[m][k] = *(const LAS bf16x8*)(lds + PG8_SA(b, h) + aoff + m * 2048 + k * 1024); } while (0)
; #define PG8_LDB(dst, b, h) do { _Pragma("unroll") for (int n = 0; n < 2; ++n) _Pragma("unroll") for (int k = 0; k < 2; ++k) dst[n][k] = *(const LAS bf16x8*)(lds + PG8_SB(b, h) + boff + n * 2048 + k * 1024); } while (0)
; #define PG8_MMA(ai, bj, At, Bt) do { __builtin_amdgcn_s_setprio(1); _Pragma("unroll") for (int m = 0; m < 4; ++m) _Pragma("unroll") for (int n = 0; n < 2; ++n) _Pragma("unroll") for (int k = 0; k < 2; ++k) \
;         acc[ai][bj][m][n] = __builtin_amdgcn_mfma_f32_16x16x32_bf16(Bt[n][k], At[m][k], acc[ai][bj][m][n], 0, 0, 0); __builtin_amdgcn_s_setprio(0); } while (0)
; #define PG8_WAIT_V(n) asm volatile("s_waitcnt vmcnt(" #n ")" ::: "memory")
; #define PG8_WAIT_L(n) asm volatile("s_waitcnt lgkmcnt(" #n ")" ::: "memory")
; #define PG8_BAR __builtin_amdgcn_s_barrier()
; #define PG8_SCHED __builtin_amdgcn_sched_barrier(0)
; template <class Epi>
; __device__ __forceinline__ void gemm_phase(LAS unsigned char* lds, const Gemm g, const Epi& E) {
;     ...
;             PG8_LDB(B0, 0, 0); PG8_SCHED; PG8_LDA(At, 0, 0); PG8_STAGE(PG8_SA(1, 1), a1 + hstep, voffA);
;             PG8_WAIT_L(8); PG8_BAR; PG8_WAIT_L(0); PG8_MMA(0, 0, At, B0); PG8_BAR; PG8_SCHED;
;             PG8_LDB(B1, 0, 1); PG8_STAGE(PG8_SB(0, 0), b2, voffB);
;             PG8_BAR; PG8_WAIT_L(0); PG8_MMA(0, 1, At, B1); PG8_BAR;
;             PG8_LDA(At, 0, 1); PG8_STAGE(PG8_SA(0, 0), a2, voffA);
;             PG8_BAR; PG8_WAIT_L(0); PG8_MMA(1, 0, At, B0); PG8_BAR; PG8_SCHED;
;             PG8_STAGE(PG8_SB(0, 1), b2 + hstep, voffB);
;             PG8_WAIT_V(6); PG8_BAR; PG8_MMA(1, 1, At, B1); PG8_BAR;
.LBB0_672:
	s_add_u32 s28, s26, 0xfff80080
	s_addc_u32 s29, s27, -1
	s_add_i32 s34, 0, 0x10000
	v_add_u32_e32 v160, s34, v163
	ds_read_b128 v[128:131], v160
	ds_read_b128 v[132:135], v160 offset:1024
	ds_read_b128 v[156:159], v160 offset:2048
	ds_read_b128 v[166:169], v160 offset:3072
	s_cmp_eq_u32 s39, 28
	s_cselect_b32 s37, s1, s29
	s_cselect_b32 s36, s2, s28
	s_cselect_b32 s29, s3, s38
	s_cselect_b32 s28, s30, s31
	s_add_i32 m0, s96, 0xc000
	ds_read_b128 v[170:173], v164
	ds_read_b128 v[174:177], v164 offset:1024
	ds_read_b128 v[178:181], v164 offset:2048
	ds_read_b128 v[182:185], v164 offset:3072
	ds_read_b128 v[186:189], v164 offset:4096
	ds_read_b128 v[190:193], v164 offset:5120
	ds_read_b128 v[194:197], v164 offset:6144
	ds_read_b128 v[198:201], v164 offset:7168
	global_load_lds_dwordx4 v152, s[26:27]
	s_add_i32 m0, s96, 0xe000
	s_nop 0
	global_load_lds_dwordx4 v154, s[26:27]
	s_waitcnt lgkmcnt(8)
	s_setprio 1
	s_barrier
	s_waitcnt lgkmcnt(0)
	v_mfma_f32_16x16x32_bf16 v[124:127], v[128:131], v[170:173], v[124:127]
	v_mfma_f32_16x16x32_bf16 v[120:123], v[156:159], v[170:173], v[120:123]
	v_mfma_f32_16x16x32_bf16 v[108:111], v[128:131], v[178:181], v[108:111]
	v_mfma_f32_16x16x32_bf16 v[104:107], v[156:159], v[178:181], v[104:107]
	v_mfma_f32_16x16x32_bf16 v[92:95], v[128:131], v[186:189], v[92:95]
	v_mfma_f32_16x16x32_bf16 v[88:91], v[156:159], v[186:189], v[88:91]
	v_mfma_f32_16x16x32_bf16 v[76:79], v[128:131], v[194:197], v[76:79]
	v_mfma_f32_16x16x32_bf16 v[72:75], v[156:159], v[194:197], v[72:75]
	v_mfma_f32_16x16x32_bf16 v[124:127], v[132:135], v[174:177], v[124:127]
	v_mfma_f32_16x16x32_bf16 v[120:123], v[166:169], v[174:177], v[120:123]
	v_mfma_f32_16x16x32_bf16 v[108:111], v[132:135], v[182:185], v[108:111]
	v_mfma_f32_16x16x32_bf16 v[104:107], v[166:169], v[182:185], v[104:107]
	v_mfma_f32_16x16x32_bf16 v[92:95], v[132:135], v[190:193], v[92:95]
	v_mfma_f32_16x16x32_bf16 v[88:91], v[166:169], v[190:193], v[88:91]
	v_mfma_f32_16x16x32_bf16 v[76:79], v[132:135], v[198:201], v[76:79]
	v_mfma_f32_16x16x32_bf16 v[72:75], v[166:169], v[198:201], v[72:75]
	s_setprio 0
	s_barrier
	s_add_i32 s35, 0, 0x14000
	v_add_u32_e32 v160, s35, v163
	s_add_i32 s34, s34, s71
	ds_read_b128 v[202:205], v160
	ds_read_b128 v[238:241], v160 offset:1024
	ds_read_b128 v[242:245], v160 offset:2048
	ds_read_b128 v[246:249], v160 offset:3072
	s_mov_b32 m0, s34
	s_nop 0
	global_load_lds_dwordx4 v138, s[28:29]
	s_add_i32 m0, s34, 0x2000
	s_nop 0
	global_load_lds_dwordx4 v142, s[28:29]
	s_setprio 1
	s_barrier
	s_waitcnt lgkmcnt(0)
	v_mfma_f32_16x16x32_bf16 v[116:119], v[202:205], v[170:173], v[116:119]
	v_mfma_f32_16x16x32_bf16 v[112:115], v[242:245], v[170:173], v[112:115]
	v_mfma_f32_16x16x32_bf16 v[100:103], v[202:205], v[178:181], v[100:103]
	v_mfma_f32_16x16x32_bf16 v[96:99], v[242:245], v[178:181], v[96:99]
	v_mfma_f32_16x16x32_bf16 v[84:87], v[202:205], v[186:189], v[84:87]
	v_mfma_f32_16x16x32_bf16 v[80:83], v[242:245], v[186:189], v[80:83]
	v_mfma_f32_16x16x32_bf16 v[68:71], v[202:205], v[194:197], v[68:71]
	v_mfma_f32_16x16x32_bf16 v[64:67], v[242:245], v[194:197], v[64:67]
	v_mfma_f32_16x16x32_bf16 v[116:119], v[238:241], v[174:177], v[116:119]
	v_mfma_f32_16x16x32_bf16 v[112:115], v[246:249], v[174:177], v[112:115]
	v_mfma_f32_16x16x32_bf16 v[100:103], v[238:241], v[182:185], v[100:103]
	v_mfma_f32_16x16x32_bf16 v[96:99], v[246:249], v[182:185], v[96:99]
	v_mfma_f32_16x16x32_bf16 v[84:87], v[238:241], v[190:193], v[84:87]
	v_mfma_f32_16x16x32_bf16 v[80:83], v[246:249], v[190:193], v[80:83]
	v_mfma_f32_16x16x32_bf16 v[68:71], v[238:241], v[198:201], v[68:71]
	v_mfma_f32_16x16x32_bf16 v[64:67], v[246:249], v[198:201], v[64:67]
	s_setprio 0
	s_mov_b32 m0, s96
	s_barrier
	ds_read_b128 v[170:173], v164 offset:16384
	ds_read_b128 v[174:177], v164 offset:17408
	ds_read_b128 v[178:181], v164 offset:18432
	ds_read_b128 v[182:185], v164 offset:19456
	ds_read_b128 v[186:189], v164 offset:20480
	ds_read_b128 v[190:193], v164 offset:21504
	ds_read_b128 v[194:197], v164 offset:22528
	ds_read_b128 v[198:201], v164 offset:23552
	global_load_lds_dwordx4 v136, s[36:37]
	s_mov_b32 m0, s97
	s_nop 0
	global_load_lds_dwordx4 v140, s[36:37]
	s_setprio 1
	s_barrier
	s_waitcnt lgkmcnt(0)
	v_mfma_f32_16x16x32_bf16 v[60:63], v[128:131], v[170:173], v[60:63]
	v_mfma_f32_16x16x32_bf16 v[56:59], v[156:159], v[170:173], v[56:59]
	v_mfma_f32_16x16x32_bf16 v[44:47], v[128:131], v[178:181], v[44:47]
	v_mfma_f32_16x16x32_bf16 v[40:43], v[156:159], v[178:181], v[40:43]
	v_mfma_f32_16x16x32_bf16 v[28:31], v[128:131], v[186:189], v[28:31]
	v_mfma_f32_16x16x32_bf16 v[24:27], v[156:159], v[186:189], v[24:27]
	v_mfma_f32_16x16x32_bf16 v[12:15], v[128:131], v[194:197], v[12:15]
	v_mfma_f32_16x16x32_bf16 v[8:11], v[156:159], v[194:197], v[8:11]
	v_mfma_f32_16x16x32_bf16 v[60:63], v[132:135], v[174:177], v[60:63]
	v_mfma_f32_16x16x32_bf16 v[56:59], v[166:169], v[174:177], v[56:59]
	v_mfma_f32_16x16x32_bf16 v[44:47], v[132:135], v[182:185], v[44:47]
	v_mfma_f32_16x16x32_bf16 v[40:43], v[166:169], v[182:185], v[40:43]
	v_mfma_f32_16x16x32_bf16 v[28:31], v[132:135], v[190:193], v[28:31]
	v_mfma_f32_16x16x32_bf16 v[24:27], v[166:169], v[190:193], v[24:27]
	v_mfma_f32_16x16x32_bf16 v[12:15], v[132:135], v[198:201], v[12:15]
	v_mfma_f32_16x16x32_bf16 v[8:11], v[166:169], v[198:201], v[8:11]
	s_setprio 0
	s_barrier
	s_add_u32 s48, s28, 0x80000
	s_addc_u32 s49, s29, 0
	s_add_i32 s34, s35, s71
	s_mov_b32 m0, s34
	s_nop 0
	global_load_lds_dwordx4 v138, s[48:49]
	s_add_i32 m0, s34, 0x2000
	s_nop 0
	global_load_lds_dwordx4 v142, s[48:49]
	s_waitcnt vmcnt(6)
	s_setprio 1
	s_barrier
; #define PG8_STAGE(bufoff, gbase, voff) do { _Pragma("unroll") for (int _i = 0; _i < 2; ++_i) \
;         __builtin_amdgcn_global_load_lds((const unsigned*)((const char*)(gbase) + (voff)[_i]), (LAS unsigned*)(lds + (bufoff) + ldsw + _i * 8192), 16, 0, 0); } while (0)
; #define PG8_LDA(dst, b, h) do { _Pragma("unroll") for (int m = 0; m < 4; ++m) _Pragma("unroll") for (int k = 0; k < 2; ++k) dst[m][k] = *(const LAS bf16x8*)(lds + PG8_SA(b, h) + aoff + m * 2048 + k * 1024); } while (0)
; #define PG8_LDB(dst, b, h) do { _Pragma("unroll") for (int n = 0; n < 2; ++n) _Pragma("unroll") for (int k = 0; k < 2; ++k) dst[n][k] = *(const LAS bf16x8*)(lds + PG8_SB(b, h) + boff + n * 2048 + k * 1024); } while (0)
; #define PG8_MMA(ai, bj, At, Bt) do { __builtin_amdgcn_s_setprio(1); _Pragma("unroll") for (int m = 0; m < 4; ++m) _Pragma("unroll") for (int n = 0; n < 2; ++n) _Pragma("unroll") for (int k = 0; k < 2; ++k) \
;         acc[ai][bj][m][n] = __builtin_amdgcn_mfma_f32_16x16x32_bf16(Bt[n][k], At[m][k], acc[ai][bj][m][n], 0, 0, 0); __builtin_amdgcn_s_setprio(0); } while (0)
; #define PG8_WAIT_V(n) asm volatile("s_waitcnt vmcnt(" #n ")" ::: "memory")
; #define PG8_WAIT_L(n) asm volatile("s_waitcnt lgkmcnt(" #n ")" ::: "memory")
; #define PG8_BAR __builtin_amdgcn_s_barrier()
; #define PG8_SCHED __builtin_amdgcn_sched_barrier(0)
; template <class Epi>
; __device__ __forceinline__ void gemm_phase(LAS unsigned char* lds, const Gemm g, const Epi& E) {
;     ...
;             PG8_WAIT_V(6); PG8_BAR; PG8_MMA(1, 1, At, B1); PG8_BAR;
;             PG8_LDB(B0, 1, 0); PG8_SCHED; PG8_LDA(At, 1, 0); PG8_STAGE(PG8_SA(0, 1), a2 + hstep, voffA);
;             PG8_WAIT_L(8); PG8_BAR; PG8_WAIT_L(0); PG8_MMA(0, 0, At, B0); PG8_BAR; PG8_SCHED;
;             PG8_LDB(B1, 1, 1); PG8_STAGE(PG8_SB(1, 0), b3, voffB);
;             PG8_BAR; PG8_WAIT_L(0); PG8_MMA(0, 1, At, B1); PG8_BAR;
;             PG8_LDA(At, 1, 1); PG8_STAGE(PG8_SA(1, 0), a3, voffA);
;             PG8_BAR; PG8_WAIT_L(0); PG8_MMA(1, 0, At, B0); PG8_BAR; PG8_SCHED;
	v_mfma_f32_16x16x32_bf16 v[52:55], v[202:205], v[170:173], v[52:55]
	v_mfma_f32_16x16x32_bf16 v[48:51], v[242:245], v[170:173], v[48:51]
	v_mfma_f32_16x16x32_bf16 v[36:39], v[202:205], v[178:181], v[36:39]
	v_mfma_f32_16x16x32_bf16 v[32:35], v[242:245], v[178:181], v[32:35]
	v_mfma_f32_16x16x32_bf16 v[20:23], v[202:205], v[186:189], v[20:23]
	v_mfma_f32_16x16x32_bf16 v[16:19], v[242:245], v[186:189], v[16:19]
	v_mfma_f32_16x16x32_bf16 v[4:7], v[202:205], v[194:197], v[4:7]
	v_mfma_f32_16x16x32_bf16 v[0:3], v[242:245], v[194:197], v[0:3]
	v_mfma_f32_16x16x32_bf16 v[52:55], v[238:241], v[174:177], v[52:55]
	v_mfma_f32_16x16x32_bf16 v[48:51], v[246:249], v[174:177], v[48:51]
	v_mfma_f32_16x16x32_bf16 v[36:39], v[238:241], v[182:185], v[36:39]
	v_mfma_f32_16x16x32_bf16 v[32:35], v[246:249], v[182:185], v[32:35]
	v_mfma_f32_16x16x32_bf16 v[20:23], v[238:241], v[190:193], v[20:23]
	v_mfma_f32_16x16x32_bf16 v[16:19], v[246:249], v[190:193], v[16:19]
	v_mfma_f32_16x16x32_bf16 v[4:7], v[238:241], v[198:201], v[4:7]
	v_mfma_f32_16x16x32_bf16 v[0:3], v[246:249], v[198:201], v[0:3]
	s_setprio 0
	s_add_i32 s34, 0, 0x18000
	v_add_u32_e32 v165, s34, v163
	s_barrier
	ds_read_b128 v[128:131], v165
	ds_read_b128 v[132:135], v165 offset:1024
	ds_read_b128 v[156:159], v165 offset:2048
	ds_read_b128 v[166:169], v165 offset:3072
	s_add_u32 s36, s36, 0x80000
	s_addc_u32 s37, s37, 0
	s_mov_b32 m0, s70
	ds_read_b128 v[170:173], v164 offset:32768
	ds_read_b128 v[174:177], v164 offset:33792
	ds_read_b128 v[178:181], v164 offset:34816
	ds_read_b128 v[182:185], v164 offset:35840
	ds_read_b128 v[186:189], v164 offset:36864
	ds_read_b128 v[190:193], v164 offset:37888
	ds_read_b128 v[194:197], v164 offset:38912
	ds_read_b128 v[198:201], v164 offset:39936
	global_load_lds_dwordx4 v136, s[36:37]
	s_mov_b32 m0, s69
	s_nop 0
	global_load_lds_dwordx4 v140, s[36:37]
	s_waitcnt lgkmcnt(8)
	s_setprio 1
	s_barrier
	s_waitcnt lgkmcnt(0)
	v_mfma_f32_16x16x32_bf16 v[124:127], v[128:131], v[170:173], v[124:127]
	v_mfma_f32_16x16x32_bf16 v[120:123], v[156:159], v[170:173], v[120:123]
	v_mfma_f32_16x16x32_bf16 v[108:111], v[128:131], v[178:181], v[108:111]
	v_mfma_f32_16x16x32_bf16 v[104:107], v[156:159], v[178:181], v[104:107]
	v_mfma_f32_16x16x32_bf16 v[92:95], v[128:131], v[186:189], v[92:95]
	v_mfma_f32_16x16x32_bf16 v[88:91], v[156:159], v[186:189], v[88:91]
	v_mfma_f32_16x16x32_bf16 v[76:79], v[128:131], v[194:197], v[76:79]
	v_mfma_f32_16x16x32_bf16 v[72:75], v[156:159], v[194:197], v[72:75]
	v_mfma_f32_16x16x32_bf16 v[124:127], v[132:135], v[174:177], v[124:127]
	v_mfma_f32_16x16x32_bf16 v[120:123], v[166:169], v[174:177], v[120:123]
	v_mfma_f32_16x16x32_bf16 v[108:111], v[132:135], v[182:185], v[108:111]
	v_mfma_f32_16x16x32_bf16 v[104:107], v[166:169], v[182:185], v[104:107]
	v_mfma_f32_16x16x32_bf16 v[92:95], v[132:135], v[190:193], v[92:95]
	v_mfma_f32_16x16x32_bf16 v[88:91], v[166:169], v[190:193], v[88:91]
	v_mfma_f32_16x16x32_bf16 v[76:79], v[132:135], v[198:201], v[76:79]
	v_mfma_f32_16x16x32_bf16 v[72:75], v[166:169], v[198:201], v[72:75]
	s_setprio 0
	s_barrier
	s_add_i32 s35, 0, 0x1c000
	s_add_i32 s34, s34, s71
	v_add_u32_e32 v165, s35, v163
	s_mov_b32 m0, s34
	ds_read_b128 v[202:205], v165
	ds_read_b128 v[238:241], v165 offset:1024
	ds_read_b128 v[242:245], v165 offset:2048
	ds_read_b128 v[246:249], v165 offset:3072
	s_add_u32 s98, s28, 0x80
	s_addc_u32 s99, s29, 0
	global_load_lds_dwordx4 v138, s[98:99]
	s_add_i32 m0, s34, 0x2000
	s_add_u32 s100, s28, 0x80
	s_addc_u32 s101, s29, 0
	global_load_lds_dwordx4 v142, s[100:101]
	s_setprio 1
	s_barrier
	s_waitcnt lgkmcnt(0)
	v_mfma_f32_16x16x32_bf16 v[116:119], v[202:205], v[170:173], v[116:119]
	v_mfma_f32_16x16x32_bf16 v[112:115], v[242:245], v[170:173], v[112:115]
	v_mfma_f32_16x16x32_bf16 v[100:103], v[202:205], v[178:181], v[100:103]
	v_mfma_f32_16x16x32_bf16 v[96:99], v[242:245], v[178:181], v[96:99]
	v_mfma_f32_16x16x32_bf16 v[84:87], v[202:205], v[186:189], v[84:87]
	v_mfma_f32_16x16x32_bf16 v[80:83], v[242:245], v[186:189], v[80:83]
	v_mfma_f32_16x16x32_bf16 v[68:71], v[202:205], v[194:197], v[68:71]
	v_mfma_f32_16x16x32_bf16 v[64:67], v[242:245], v[194:197], v[64:67]
	v_mfma_f32_16x16x32_bf16 v[116:119], v[238:241], v[174:177], v[116:119]
	v_mfma_f32_16x16x32_bf16 v[112:115], v[246:249], v[174:177], v[112:115]
	v_mfma_f32_16x16x32_bf16 v[100:103], v[238:241], v[182:185], v[100:103]
	v_mfma_f32_16x16x32_bf16 v[96:99], v[246:249], v[182:185], v[96:99]
	v_mfma_f32_16x16x32_bf16 v[84:87], v[238:241], v[190:193], v[84:87]
	v_mfma_f32_16x16x32_bf16 v[80:83], v[246:249], v[190:193], v[80:83]
	v_mfma_f32_16x16x32_bf16 v[68:71], v[238:241], v[198:201], v[68:71]
	v_mfma_f32_16x16x32_bf16 v[64:67], v[246:249], v[198:201], v[64:67]
	s_setprio 0
	s_mov_b32 m0, s68
	s_barrier
; __device__ __forceinline__ u32x2 pack4u(f32x4 a) { u32x2 w = {cvt_pk_bf16(a[0], a[1]), cvt_pk_bf16(a[2], a[3])}; return w; }
; #define PG8_STAGE(bufoff, gbase, voff) do { _Pragma("unroll") for (int _i = 0; _i < 2; ++_i) \
;         __builtin_amdgcn_global_load_lds((const unsigned*)((const char*)(gbase) + (voff)[_i]), (LAS unsigned*)(lds + (bufoff) + ldsw + _i * 8192), 16, 0, 0); } while (0)
; #define PG8_LDA(dst, b, h) do { _Pragma("unroll") for (int m = 0; m < 4; ++m) _Pragma("unroll") for (int k = 0; k < 2; ++k) dst[m][k] = *(const LAS bf16x8*)(lds + PG8_SA(b, h) + aoff + m * 2048 + k * 1024); } while (0)
; template <class Epi>
; __device__ __forceinline__ void gemm_phase(LAS unsigned char* lds, const Gemm g, const Epi& E) {
;     ...
;             PG8_BAR; PG8_WAIT_L(0); PG8_MMA(0, 1, At, B1); PG8_BAR;
;             PG8_LDA(At, 1, 1); PG8_STAGE(PG8_SA(1, 0), a3, voffA);
;             PG8_BAR; PG8_WAIT_L(0); PG8_MMA(1, 0, At, B0); PG8_BAR; PG8_SCHED;
;             PG8_STAGE(PG8_SB(1, 1), b3 + hstep, voffB);
;             PG8_WAIT_V(6); PG8_BAR; PG8_MMA(1, 1, At, B1); PG8_BAR;
;     __device__ __forceinline__ void operator()(const AccT& acc, const Unit& u, int wr, int wc, int fr, int fq) const {
;     ...
;             const int g8 = wc * 4 + fq;
; #pragma unroll
;             for (int ai = 0; ai < 2; ++ai)
; #pragma unroll
;                 for (int m = 0; m < 4; ++m) {
;                     const int row = u.pm * 256 + ai * 128 + wr * 64 + m * 16 + fr;
;                     const f32x4 v0 = acc[ai][0][m][0], v1 = acc[ai][0][m][1];
;                     if (g8 < 8) {
;                         const int i0 = 4 * g8;
;                         const f32x4 cs = *(const f32x4*)(COS + (size_t)row * 32 + i0), sn = *(const f32x4*)(SIN + (size_t)row * 32 + i0);
;                         const f32x4 o1 = v0 * cs - v1 * sn, o2 = v1 * cs + v0 * sn;
;                         const u32x2 w1 = pack4u(o1), w2 = pack4u(o2);
;                         const int b = row / SEQ, t = row % SEQ;
;                         bf16_t* kp = Kb + ((size_t)(b * NH) * SEQ + t) * DQK + 128 + i0;
; #pragma unroll
;                         for (int h = 0; h < NH; ++h) { *(u32x2*)(kp + (size_t)h * SEQ * DQK) = w1; *(u32x2*)(kp + (size_t)h * SEQ * DQK + 32) = w2; }
;                     } else if (g8 < 10) { float* bp = BA + (size_t)row * 16 + (g8 - 8) * 8; *(f32x4*)bp = v0; *(f32x4*)(bp + 4) = v1; }
	ds_read_b128 v[170:173], v164 offset:49152
	ds_read_b128 v[174:177], v164 offset:50176
	ds_read_b128 v[178:181], v164 offset:51200
	ds_read_b128 v[182:185], v164 offset:52224
	ds_read_b128 v[186:189], v164 offset:53248
	ds_read_b128 v[190:193], v164 offset:54272
	ds_read_b128 v[194:197], v164 offset:55296
	ds_read_b128 v[198:201], v164 offset:56320
	s_add_u32 s98, s36, 0xfff80080
	s_addc_u32 s99, s37, -1
	global_load_lds_dwordx4 v136, s[98:99]
	s_mov_b32 m0, s83
	s_add_u32 s100, s36, 0xfff80080
	s_addc_u32 s101, s37, -1
	global_load_lds_dwordx4 v140, s[100:101]
	s_setprio 1
	s_barrier
	s_waitcnt lgkmcnt(0)
	v_mfma_f32_16x16x32_bf16 v[60:63], v[128:131], v[170:173], v[60:63]
	v_mfma_f32_16x16x32_bf16 v[56:59], v[156:159], v[170:173], v[56:59]
	v_mfma_f32_16x16x32_bf16 v[44:47], v[128:131], v[178:181], v[44:47]
	v_mfma_f32_16x16x32_bf16 v[40:43], v[156:159], v[178:181], v[40:43]
	v_mfma_f32_16x16x32_bf16 v[28:31], v[128:131], v[186:189], v[28:31]
	v_mfma_f32_16x16x32_bf16 v[24:27], v[156:159], v[186:189], v[24:27]
	v_mfma_f32_16x16x32_bf16 v[12:15], v[128:131], v[194:197], v[12:15]
	v_mfma_f32_16x16x32_bf16 v[8:11], v[156:159], v[194:197], v[8:11]
	v_mfma_f32_16x16x32_bf16 v[60:63], v[132:135], v[174:177], v[60:63]
	v_mfma_f32_16x16x32_bf16 v[56:59], v[166:169], v[174:177], v[56:59]
	v_mfma_f32_16x16x32_bf16 v[44:47], v[132:135], v[182:185], v[44:47]
	v_mfma_f32_16x16x32_bf16 v[40:43], v[166:169], v[182:185], v[40:43]
	v_mfma_f32_16x16x32_bf16 v[28:31], v[132:135], v[190:193], v[28:31]
	v_mfma_f32_16x16x32_bf16 v[24:27], v[166:169], v[190:193], v[24:27]
	v_mfma_f32_16x16x32_bf16 v[12:15], v[132:135], v[198:201], v[12:15]
	v_mfma_f32_16x16x32_bf16 v[8:11], v[166:169], v[198:201], v[8:11]
	s_setprio 0
	s_barrier
	s_add_u32 s28, s28, 0x80080
	s_addc_u32 s29, s29, 0
	s_add_i32 s34, s35, s71
	s_mov_b32 m0, s34
	s_nop 0
	global_load_lds_dwordx4 v138, s[28:29]
	s_add_i32 m0, s34, 0x2000
	s_nop 0
	global_load_lds_dwordx4 v142, s[28:29]
	s_waitcnt vmcnt(6)
	s_setprio 1
	s_barrier
	v_mfma_f32_16x16x32_bf16 v[52:55], v[202:205], v[170:173], v[52:55]
	v_mfma_f32_16x16x32_bf16 v[48:51], v[242:245], v[170:173], v[48:51]
	v_mfma_f32_16x16x32_bf16 v[36:39], v[202:205], v[178:181], v[36:39]
	v_mfma_f32_16x16x32_bf16 v[32:35], v[242:245], v[178:181], v[32:35]
	v_mfma_f32_16x16x32_bf16 v[20:23], v[202:205], v[186:189], v[20:23]
	v_mfma_f32_16x16x32_bf16 v[16:19], v[242:245], v[186:189], v[16:19]
	v_mfma_f32_16x16x32_bf16 v[4:7], v[202:205], v[194:197], v[4:7]
	v_mfma_f32_16x16x32_bf16 v[0:3], v[242:245], v[194:197], v[0:3]
	v_mfma_f32_16x16x32_bf16 v[52:55], v[238:241], v[174:177], v[52:55]
	v_mfma_f32_16x16x32_bf16 v[48:51], v[246:249], v[174:177], v[48:51]
	v_mfma_f32_16x16x32_bf16 v[36:39], v[238:241], v[182:185], v[36:39]
	v_mfma_f32_16x16x32_bf16 v[32:35], v[246:249], v[182:185], v[32:35]
	v_mfma_f32_16x16x32_bf16 v[20:23], v[238:241], v[190:193], v[20:23]
	v_mfma_f32_16x16x32_bf16 v[16:19], v[246:249], v[190:193], v[16:19]
	v_mfma_f32_16x16x32_bf16 v[4:7], v[238:241], v[198:201], v[4:7]
	v_mfma_f32_16x16x32_bf16 v[0:3], v[246:249], v[198:201], v[0:3]
	s_setprio 0
	s_add_i32 s39, s39, 2
	s_add_u32 s26, s26, 0x100
	s_addc_u32 s27, s27, 0
	s_add_u32 s31, s31, 0x100
	s_addc_u32 s38, s38, 0
	s_cmp_gt_u32 s39, 29
	s_barrier
	s_cbranch_scc0 .LBB0_672
	s_mov_b64 s[26:27], -1
	s_cmp_gt_i32 s64, 35
	v_lshl_add_u32 v156, s46, 8, v162
	s_movk_i32 s95, 0x1ff
	s_cbranch_scc0 .LBB0_723
	v_mov_b32_e32 v220, v156
	v_ashrrev_i32_e32 v221, 31, v156
	v_lshlrev_b64 v[220:221], 7, v[220:221]
	v_lshl_add_u64 v[200:201], v[146:147], 0, v[220:221]
	v_lshl_add_u64 v[202:203], v[148:149], 0, v[220:221]
	s_mov_b64 s[98:99], 0x1000
	v_lshl_add_u64 v[204:205], v[200:201], 0, s[98:99]
	v_lshl_add_u64 v[206:207], v[202:203], 0, s[98:99]
	global_load_dwordx4 v[168:171], v[200:201], off
	global_load_dwordx4 v[172:175], v[202:203], off
	global_load_dwordx4 v[176:179], v[200:201], off offset:2048
	global_load_dwordx4 v[180:183], v[202:203], off offset:2048
	global_load_dwordx4 v[184:187], v[204:205], off
	global_load_dwordx4 v[188:191], v[206:207], off
	global_load_dwordx4 v[192:195], v[204:205], off offset:2048
	global_load_dwordx4 v[196:199], v[206:207], off offset:2048
	s_mov_b64 s[98:99], 0x4000
	v_lshl_add_u64 v[200:201], v[200:201], 0, s[98:99]
	v_lshl_add_u64 v[202:203], v[202:203], 0, s[98:99]
	v_lshl_add_u64 v[204:205], v[204:205], 0, s[98:99]
	v_lshl_add_u64 v[206:207], v[206:207], 0, s[98:99]
	s_and_b64 vcc, exec, s[52:53]
	s_cbranch_vccz .LBB0_678
	s_and_saveexec_b64 s[26:27], s[54:55]
	s_cbranch_execz .LBB0_677
	v_ashrrev_i32_e32 v157, 31, v156
	v_lshlrev_b64 v[128:129], 6, v[156:157]
	v_lshl_add_u64 v[128:129], v[144:145], 0, v[128:129]
	global_store_dwordx4 v[128:129], v[124:127], off offset:-256
	global_store_dwordx4 v[128:129], v[120:123], off offset:-240

; #define PG8_STAGE(bufoff, gbase, voff) do { _Pragma("unroll") for (int _i = 0; _i < 2; ++_i) \
;         __builtin_amdgcn_global_load_lds((const unsigned*)((const char*)(gbase) + (voff)[_i]), (LAS unsigned*)(lds + (bufoff) + ldsw + _i * 8192), 16, 0, 0); } while (0)
; #define PG8_LDA(dst, b, h) do { _Pragma("unroll") for (int m = 0; m < 4; ++m) _Pragma("unroll") for (int k = 0; k < 2; ++k) dst[m][k] = *(const LAS bf16x8*)(lds + PG8_SA(b, h) + aoff + m * 2048 + k * 1024); } while (0)
; #define PG8_LDB(dst, b, h) do { _Pragma("unroll") for (int n = 0; n < 2; ++n) _Pragma("unroll") for (int k = 0; k < 2; ++k) dst[n][k] = *(const LAS bf16x8*)(lds + PG8_SB(b, h) + boff + n * 2048 + k * 1024); } while (0)
; #define PG8_MMA(ai, bj, At, Bt) do { __builtin_amdgcn_s_setprio(1); _Pragma("unroll") for (int m = 0; m < 4; ++m) _Pragma("unroll") for (int n = 0; n < 2; ++n) _Pragma("unroll") for (int k = 0; k < 2; ++k) \
;         acc[ai][bj][m][n] = __builtin_amdgcn_mfma_f32_16x16x32_bf16(Bt[n][k], At[m][k], acc[ai][bj][m][n], 0, 0, 0); __builtin_amdgcn_s_setprio(0); } while (0)
; #define PG8_WAIT_V(n) asm volatile("s_waitcnt vmcnt(" #n ")" ::: "memory")
; #define PG8_WAIT_L(n) asm volatile("s_waitcnt lgkmcnt(" #n ")" ::: "memory")
; #define PG8_BAR __builtin_amdgcn_s_barrier()
; #define PG8_SCHED __builtin_amdgcn_sched_barrier(0)
; template <class Epi>
; __device__ __forceinline__ void gemm_phase(LAS unsigned char* lds, const Gemm g, const Epi& E) {
;     ...
;             PG8_LDB(B0, 0, 0); PG8_SCHED; PG8_LDA(At, 0, 0); PG8_STAGE(PG8_SA(1, 1), a1 + hstep, voffA);
;             PG8_WAIT_L(8); PG8_BAR; PG8_WAIT_L(0); PG8_MMA(0, 0, At, B0); PG8_BAR; PG8_SCHED;
;             PG8_LDB(B1, 0, 1); PG8_STAGE(PG8_SB(0, 0), b2, voffB);
;             PG8_BAR; PG8_WAIT_L(0); PG8_MMA(0, 1, At, B1); PG8_BAR;
;             PG8_LDA(At, 0, 1); PG8_STAGE(PG8_SA(0, 0), a2, voffA);
;             PG8_BAR; PG8_WAIT_L(0); PG8_MMA(1, 0, At, B0); PG8_BAR; PG8_SCHED;
;             PG8_STAGE(PG8_SB(0, 1), b2 + hstep, voffB);
;             PG8_WAIT_V(6); PG8_BAR; PG8_MMA(1, 1, At, B1); PG8_BAR;
.LBB0_873:
	s_add_u32 s28, s26, 0x100
	s_addc_u32 s29, s27, 0
	s_add_i32 s34, 0, 0x10000
	v_add_u32_e32 v140, s34, v160
	ds_read_b128 v[128:131], v140
	ds_read_b128 v[132:135], v140 offset:1024
	ds_read_b128 v[136:139], v140 offset:2048
	ds_read_b128 v[140:143], v140 offset:3072
	s_cmpk_eq_i32 s82, 0x54
	s_cselect_b32 s39, s1, s29
	s_cselect_b32 s38, s0, s28
	s_cselect_b32 s37, s43, s79
	s_cselect_b32 s36, s42, s78
	s_add_i32 m0, s44, 0xc000
	ds_read_b128 v[156:159], v161
	ds_read_b128 v[164:167], v161 offset:1024
	ds_read_b128 v[168:171], v161 offset:2048
	ds_read_b128 v[172:175], v161 offset:3072
	ds_read_b128 v[176:179], v161 offset:4096
	ds_read_b128 v[180:183], v161 offset:5120
	ds_read_b128 v[184:187], v161 offset:6144
	ds_read_b128 v[188:191], v161 offset:7168
	global_load_lds_dwordx4 v152, s[26:27]
	s_add_i32 m0, s44, 0xe000
	s_nop 0
	global_load_lds_dwordx4 v154, s[26:27]
	s_waitcnt lgkmcnt(8)
	s_setprio 1
	s_barrier
	s_waitcnt lgkmcnt(0)
	v_mfma_f32_16x16x32_bf16 v[124:127], v[128:131], v[156:159], v[124:127]
	v_mfma_f32_16x16x32_bf16 v[120:123], v[136:139], v[156:159], v[120:123]
	v_mfma_f32_16x16x32_bf16 v[108:111], v[128:131], v[168:171], v[108:111]
	v_mfma_f32_16x16x32_bf16 v[104:107], v[136:139], v[168:171], v[104:107]
	v_mfma_f32_16x16x32_bf16 v[92:95], v[128:131], v[176:179], v[92:95]
	v_mfma_f32_16x16x32_bf16 v[88:91], v[136:139], v[176:179], v[88:91]
	v_mfma_f32_16x16x32_bf16 v[76:79], v[128:131], v[184:187], v[76:79]
	v_mfma_f32_16x16x32_bf16 v[72:75], v[136:139], v[184:187], v[72:75]
	v_mfma_f32_16x16x32_bf16 v[124:127], v[132:135], v[164:167], v[124:127]
	v_mfma_f32_16x16x32_bf16 v[120:123], v[140:143], v[164:167], v[120:123]
	v_mfma_f32_16x16x32_bf16 v[108:111], v[132:135], v[172:175], v[108:111]
	v_mfma_f32_16x16x32_bf16 v[104:107], v[140:143], v[172:175], v[104:107]
	v_mfma_f32_16x16x32_bf16 v[92:95], v[132:135], v[180:183], v[92:95]
	v_mfma_f32_16x16x32_bf16 v[88:91], v[140:143], v[180:183], v[88:91]
	v_mfma_f32_16x16x32_bf16 v[76:79], v[132:135], v[188:191], v[76:79]
	v_mfma_f32_16x16x32_bf16 v[72:75], v[140:143], v[188:191], v[72:75]
	s_setprio 0
	s_barrier
	s_add_i32 s35, 0, 0x14000
	s_add_i32 s26, s34, s31
	v_add_u32_e32 v163, s35, v160
	s_mov_b32 m0, s26
	ds_read_b128 v[192:195], v163
	ds_read_b128 v[196:199], v163 offset:1024
	ds_read_b128 v[200:203], v163 offset:2048
	ds_read_b128 v[204:207], v163 offset:3072
	global_load_lds_dwordx4 v208, s[36:37]
	s_add_i32 m0, s26, 0x2000
	s_nop 0
	global_load_lds_dwordx4 v148, s[36:37]
	s_setprio 1
	s_barrier
	s_waitcnt lgkmcnt(0)
	v_mfma_f32_16x16x32_bf16 v[116:119], v[192:195], v[156:159], v[116:119]
	v_mfma_f32_16x16x32_bf16 v[112:115], v[200:203], v[156:159], v[112:115]
	v_mfma_f32_16x16x32_bf16 v[100:103], v[192:195], v[168:171], v[100:103]
	v_mfma_f32_16x16x32_bf16 v[96:99], v[200:203], v[168:171], v[96:99]
	v_mfma_f32_16x16x32_bf16 v[84:87], v[192:195], v[176:179], v[84:87]
	v_mfma_f32_16x16x32_bf16 v[80:83], v[200:203], v[176:179], v[80:83]
	v_mfma_f32_16x16x32_bf16 v[68:71], v[192:195], v[184:187], v[68:71]
	v_mfma_f32_16x16x32_bf16 v[64:67], v[200:203], v[184:187], v[64:67]
	v_mfma_f32_16x16x32_bf16 v[116:119], v[196:199], v[164:167], v[116:119]
	v_mfma_f32_16x16x32_bf16 v[112:115], v[204:207], v[164:167], v[112:115]
	v_mfma_f32_16x16x32_bf16 v[100:103], v[196:199], v[172:175], v[100:103]
	v_mfma_f32_16x16x32_bf16 v[96:99], v[204:207], v[172:175], v[96:99]
	v_mfma_f32_16x16x32_bf16 v[84:87], v[196:199], v[180:183], v[84:87]
	v_mfma_f32_16x16x32_bf16 v[80:83], v[204:207], v[180:183], v[80:83]
	v_mfma_f32_16x16x32_bf16 v[68:71], v[196:199], v[188:191], v[68:71]
	v_mfma_f32_16x16x32_bf16 v[64:67], v[204:207], v[188:191], v[64:67]
	s_setprio 0
	s_mov_b32 m0, s44
	s_barrier
	ds_read_b128 v[156:159], v161 offset:16384
	ds_read_b128 v[164:167], v161 offset:17408
	ds_read_b128 v[168:171], v161 offset:18432
	ds_read_b128 v[172:175], v161 offset:19456
	ds_read_b128 v[176:179], v161 offset:20480
	ds_read_b128 v[180:183], v161 offset:21504
	ds_read_b128 v[184:187], v161 offset:22528
	ds_read_b128 v[188:191], v161 offset:23552
	global_load_lds_dwordx4 v144, s[38:39]
	s_mov_b32 m0, s45
	s_nop 0
	global_load_lds_dwordx4 v146, s[38:39]
	s_setprio 1
	s_barrier
	s_waitcnt lgkmcnt(0)
	v_mfma_f32_16x16x32_bf16 v[60:63], v[128:131], v[156:159], v[60:63]
	v_mfma_f32_16x16x32_bf16 v[56:59], v[136:139], v[156:159], v[56:59]
	v_mfma_f32_16x16x32_bf16 v[44:47], v[128:131], v[168:171], v[44:47]
	v_mfma_f32_16x16x32_bf16 v[40:43], v[136:139], v[168:171], v[40:43]
	v_mfma_f32_16x16x32_bf16 v[28:31], v[128:131], v[176:179], v[28:31]
	v_mfma_f32_16x16x32_bf16 v[24:27], v[136:139], v[176:179], v[24:27]
	v_mfma_f32_16x16x32_bf16 v[12:15], v[128:131], v[184:187], v[12:15]
	v_mfma_f32_16x16x32_bf16 v[8:11], v[136:139], v[184:187], v[8:11]
	v_mfma_f32_16x16x32_bf16 v[60:63], v[132:135], v[164:167], v[60:63]
	v_mfma_f32_16x16x32_bf16 v[56:59], v[140:143], v[164:167], v[56:59]
	v_mfma_f32_16x16x32_bf16 v[44:47], v[132:135], v[172:175], v[44:47]
	v_mfma_f32_16x16x32_bf16 v[40:43], v[140:143], v[172:175], v[40:43]
	v_mfma_f32_16x16x32_bf16 v[28:31], v[132:135], v[180:183], v[28:31]
	v_mfma_f32_16x16x32_bf16 v[24:27], v[140:143], v[180:183], v[24:27]
	v_mfma_f32_16x16x32_bf16 v[12:15], v[132:135], v[188:191], v[12:15]
	v_mfma_f32_16x16x32_bf16 v[8:11], v[140:143], v[188:191], v[8:11]
	s_setprio 0
	s_barrier
	s_add_u32 s26, s36, 0x160000
	s_addc_u32 s27, s37, 0
	s_add_i32 s34, s35, s31
	s_mov_b32 m0, s34
	s_nop 0
	global_load_lds_dwordx4 v208, s[26:27]
	s_add_i32 m0, s34, 0x2000
	s_nop 0
	global_load_lds_dwordx4 v148, s[26:27]
	s_waitcnt vmcnt(6)
	s_setprio 1
	s_barrier
; #define PG8_STAGE(bufoff, gbase, voff) do { _Pragma("unroll") for (int _i = 0; _i < 2; ++_i) \
;         __builtin_amdgcn_global_load_lds((const unsigned*)((const char*)(gbase) + (voff)[_i]), (LAS unsigned*)(lds + (bufoff) + ldsw + _i * 8192), 16, 0, 0); } while (0)
; #define PG8_LDA(dst, b, h) do { _Pragma("unroll") for (int m = 0; m < 4; ++m) _Pragma("unroll") for (int k = 0; k < 2; ++k) dst[m][k] = *(const LAS bf16x8*)(lds + PG8_SA(b, h) + aoff + m * 2048 + k * 1024); } while (0)
; #define PG8_LDB(dst, b, h) do { _Pragma("unroll") for (int n = 0; n < 2; ++n) _Pragma("unroll") for (int k = 0; k < 2; ++k) dst[n][k] = *(const LAS bf16x8*)(lds + PG8_SB(b, h) + boff + n * 2048 + k * 1024); } while (0)
; #define PG8_MMA(ai, bj, At, Bt) do { __builtin_amdgcn_s_setprio(1); _Pragma("unroll") for (int m = 0; m < 4; ++m) _Pragma("unroll") for (int n = 0; n < 2; ++n) _Pragma("unroll") for (int k = 0; k < 2; ++k) \
;         acc[ai][bj][m][n] = __builtin_amdgcn_mfma_f32_16x16x32_bf16(Bt[n][k], At[m][k], acc[ai][bj][m][n], 0, 0, 0); __builtin_amdgcn_s_setprio(0); } while (0)
; #define PG8_WAIT_V(n) asm volatile("s_waitcnt vmcnt(" #n ")" ::: "memory")
; #define PG8_WAIT_L(n) asm volatile("s_waitcnt lgkmcnt(" #n ")" ::: "memory")
; #define PG8_BAR __builtin_amdgcn_s_barrier()
; #define PG8_SCHED __builtin_amdgcn_sched_barrier(0)
; template <class Epi>
; __device__ __forceinline__ void gemm_phase(LAS unsigned char* lds, const Gemm g, const Epi& E) {
;     ...
;             PG8_WAIT_V(6); PG8_BAR; PG8_MMA(1, 1, At, B1); PG8_BAR;
;             PG8_LDB(B0, 1, 0); PG8_SCHED; PG8_LDA(At, 1, 0); PG8_STAGE(PG8_SA(0, 1), a2 + hstep, voffA);
;             PG8_WAIT_L(8); PG8_BAR; PG8_WAIT_L(0); PG8_MMA(0, 0, At, B0); PG8_BAR; PG8_SCHED;
;             PG8_LDB(B1, 1, 1); PG8_STAGE(PG8_SB(1, 0), b3, voffB);
;             PG8_BAR; PG8_WAIT_L(0); PG8_MMA(0, 1, At, B1); PG8_BAR;
;             PG8_LDA(At, 1, 1); PG8_STAGE(PG8_SA(1, 0), a3, voffA);
;             PG8_BAR; PG8_WAIT_L(0); PG8_MMA(1, 0, At, B0); PG8_BAR; PG8_SCHED;
	v_mfma_f32_16x16x32_bf16 v[52:55], v[192:195], v[156:159], v[52:55]
	v_mfma_f32_16x16x32_bf16 v[48:51], v[200:203], v[156:159], v[48:51]
	v_mfma_f32_16x16x32_bf16 v[36:39], v[192:195], v[168:171], v[36:39]
	v_mfma_f32_16x16x32_bf16 v[32:35], v[200:203], v[168:171], v[32:35]
	v_mfma_f32_16x16x32_bf16 v[20:23], v[192:195], v[176:179], v[20:23]
	v_mfma_f32_16x16x32_bf16 v[16:19], v[200:203], v[176:179], v[16:19]
	v_mfma_f32_16x16x32_bf16 v[4:7], v[192:195], v[184:187], v[4:7]
	v_mfma_f32_16x16x32_bf16 v[0:3], v[200:203], v[184:187], v[0:3]
	v_mfma_f32_16x16x32_bf16 v[52:55], v[196:199], v[164:167], v[52:55]
	v_mfma_f32_16x16x32_bf16 v[48:51], v[204:207], v[164:167], v[48:51]
	v_mfma_f32_16x16x32_bf16 v[36:39], v[196:199], v[172:175], v[36:39]
	v_mfma_f32_16x16x32_bf16 v[32:35], v[204:207], v[172:175], v[32:35]
	v_mfma_f32_16x16x32_bf16 v[20:23], v[196:199], v[180:183], v[20:23]
	v_mfma_f32_16x16x32_bf16 v[16:19], v[204:207], v[180:183], v[16:19]
	v_mfma_f32_16x16x32_bf16 v[4:7], v[196:199], v[188:191], v[4:7]
	v_mfma_f32_16x16x32_bf16 v[0:3], v[204:207], v[188:191], v[0:3]
	s_setprio 0
	s_add_i32 s34, 0, 0x18000
	v_add_u32_e32 v140, s34, v160
	s_barrier
	ds_read_b128 v[128:131], v140
	ds_read_b128 v[132:135], v140 offset:1024
	ds_read_b128 v[136:139], v140 offset:2048
	ds_read_b128 v[140:143], v140 offset:3072
	s_add_u32 s26, s38, 0x160000
	s_addc_u32 s27, s39, 0
	s_mov_b32 m0, s46
	ds_read_b128 v[156:159], v161 offset:32768
	ds_read_b128 v[164:167], v161 offset:33792
	ds_read_b128 v[168:171], v161 offset:34816
	ds_read_b128 v[172:175], v161 offset:35840
	ds_read_b128 v[176:179], v161 offset:36864
	ds_read_b128 v[180:183], v161 offset:37888
	ds_read_b128 v[184:187], v161 offset:38912
	ds_read_b128 v[188:191], v161 offset:39936
	global_load_lds_dwordx4 v144, s[26:27]
	s_mov_b32 m0, s47
	s_nop 0
	global_load_lds_dwordx4 v146, s[26:27]
	s_waitcnt lgkmcnt(8)
	s_setprio 1
	s_barrier
	s_waitcnt lgkmcnt(0)
	v_mfma_f32_16x16x32_bf16 v[124:127], v[128:131], v[156:159], v[124:127]
	v_mfma_f32_16x16x32_bf16 v[120:123], v[136:139], v[156:159], v[120:123]
	v_mfma_f32_16x16x32_bf16 v[108:111], v[128:131], v[168:171], v[108:111]
	v_mfma_f32_16x16x32_bf16 v[104:107], v[136:139], v[168:171], v[104:107]
	v_mfma_f32_16x16x32_bf16 v[92:95], v[128:131], v[176:179], v[92:95]
	v_mfma_f32_16x16x32_bf16 v[88:91], v[136:139], v[176:179], v[88:91]
	v_mfma_f32_16x16x32_bf16 v[76:79], v[128:131], v[184:187], v[76:79]
	v_mfma_f32_16x16x32_bf16 v[72:75], v[136:139], v[184:187], v[72:75]
	v_mfma_f32_16x16x32_bf16 v[124:127], v[132:135], v[164:167], v[124:127]
	v_mfma_f32_16x16x32_bf16 v[120:123], v[140:143], v[164:167], v[120:123]
	v_mfma_f32_16x16x32_bf16 v[108:111], v[132:135], v[172:175], v[108:111]
	v_mfma_f32_16x16x32_bf16 v[104:107], v[140:143], v[172:175], v[104:107]
	v_mfma_f32_16x16x32_bf16 v[92:95], v[132:135], v[180:183], v[92:95]
	v_mfma_f32_16x16x32_bf16 v[88:91], v[140:143], v[180:183], v[88:91]
	v_mfma_f32_16x16x32_bf16 v[76:79], v[132:135], v[188:191], v[76:79]
	v_mfma_f32_16x16x32_bf16 v[72:75], v[140:143], v[188:191], v[72:75]
	s_setprio 0
	s_barrier
	s_add_i32 s35, 0, 0x1c000
	s_add_i32 s26, s34, s31
	v_add_u32_e32 v163, s35, v160
	s_mov_b32 m0, s26
	ds_read_b128 v[192:195], v163
	ds_read_b128 v[196:199], v163 offset:1024
	ds_read_b128 v[200:203], v163 offset:2048
	ds_read_b128 v[204:207], v163 offset:3072
	s_add_u32 s98, s36, 0x80
	s_addc_u32 s99, s37, 0
	global_load_lds_dwordx4 v208, s[98:99]
	s_add_i32 m0, s26, 0x2000
	s_add_u32 s100, s36, 0x80
	s_addc_u32 s101, s37, 0
	global_load_lds_dwordx4 v148, s[100:101]
	s_setprio 1
	s_barrier
	s_waitcnt lgkmcnt(0)
	v_mfma_f32_16x16x32_bf16 v[116:119], v[192:195], v[156:159], v[116:119]
	v_mfma_f32_16x16x32_bf16 v[112:115], v[200:203], v[156:159], v[112:115]
	v_mfma_f32_16x16x32_bf16 v[100:103], v[192:195], v[168:171], v[100:103]
	v_mfma_f32_16x16x32_bf16 v[96:99], v[200:203], v[168:171], v[96:99]
	v_mfma_f32_16x16x32_bf16 v[84:87], v[192:195], v[176:179], v[84:87]
	v_mfma_f32_16x16x32_bf16 v[80:83], v[200:203], v[176:179], v[80:83]
	v_mfma_f32_16x16x32_bf16 v[68:71], v[192:195], v[184:187], v[68:71]
	v_mfma_f32_16x16x32_bf16 v[64:67], v[200:203], v[184:187], v[64:67]
	v_mfma_f32_16x16x32_bf16 v[116:119], v[196:199], v[164:167], v[116:119]
	v_mfma_f32_16x16x32_bf16 v[112:115], v[204:207], v[164:167], v[112:115]
	v_mfma_f32_16x16x32_bf16 v[100:103], v[196:199], v[172:175], v[100:103]
	v_mfma_f32_16x16x32_bf16 v[96:99], v[204:207], v[172:175], v[96:99]
	v_mfma_f32_16x16x32_bf16 v[84:87], v[196:199], v[180:183], v[84:87]
	v_mfma_f32_16x16x32_bf16 v[80:83], v[204:207], v[180:183], v[80:83]
	v_mfma_f32_16x16x32_bf16 v[68:71], v[196:199], v[188:191], v[68:71]
	v_mfma_f32_16x16x32_bf16 v[64:67], v[204:207], v[188:191], v[64:67]
	s_setprio 0
	s_mov_b32 m0, s64
	s_barrier
	ds_read_b128 v[156:159], v161 offset:49152
	ds_read_b128 v[164:167], v161 offset:50176
	ds_read_b128 v[168:171], v161 offset:51200
	ds_read_b128 v[172:175], v161 offset:52224
	ds_read_b128 v[176:179], v161 offset:53248
	ds_read_b128 v[180:183], v161 offset:54272
	ds_read_b128 v[184:187], v161 offset:55296
	ds_read_b128 v[188:191], v161 offset:56320
	s_add_u32 s98, s38, 0x80
	s_addc_u32 s99, s39, 0
	global_load_lds_dwordx4 v144, s[98:99]
	s_mov_b32 m0, s65
	s_add_u32 s100, s38, 0x80
	s_addc_u32 s101, s39, 0
	global_load_lds_dwordx4 v146, s[100:101]
	s_setprio 1
	s_barrier
; __device__ __forceinline__ float bflo(unsigned w) { return __uint_as_float(w << 16); }
; __device__ __forceinline__ float bfhi(unsigned w) { return __uint_as_float(w & 0xffff0000u); }
; __device__ __forceinline__ u32x4 pack8u(f32x4 a, f32x4 b) { u32x4 w = {cvt_pk_bf16(a[0], a[1]), cvt_pk_bf16(a[2], a[3]), cvt_pk_bf16(b[0], b[1]), cvt_pk_bf16(b[2], b[3])}; return w; }
; #define PG8_LDA(dst, b, h) do { _Pragma("unroll") for (int m = 0; m < 4; ++m) _Pragma("unroll") for (int k = 0; k < 2; ++k) dst[m][k] = *(const LAS bf16x8*)(lds + PG8_SA(b, h) + aoff + m * 2048 + k * 1024); } while (0)
; template <class Epi>
; __device__ __forceinline__ void gemm_phase(LAS unsigned char* lds, const Gemm g, const Epi& E) {
;     ...
;             PG8_BAR; PG8_WAIT_L(0); PG8_MMA(0, 1, At, B1); PG8_BAR;
;             PG8_LDA(At, 1, 1); PG8_STAGE(PG8_SA(1, 0), a3, voffA);
;             PG8_BAR; PG8_WAIT_L(0); PG8_MMA(1, 0, At, B0); PG8_BAR; PG8_SCHED;
;             PG8_STAGE(PG8_SB(1, 1), b3 + hstep, voffB);
;             PG8_WAIT_V(6); PG8_BAR; PG8_MMA(1, 1, At, B1); PG8_BAR;
;         }
;         E(acc, cur, wr, wc, fr, fq);
;     __device__ __forceinline__ void operator()(const AccT& acc, const Unit& u, int wr, int wc, int fr, int fq) const {
;         const int b = (u.pm * 256) / SEQ;
;         f32x4 gt[2][2];
; #pragma unroll
;         for (int bj = 0; bj < 2; ++bj)
; #pragma unroll
;             for (int n = 0; n < 2; ++n) gt[bj][n] = *(const f32x4*)(GT + (size_t)b * 6 * D + u.pn * 256 + bj * 128 + wc * 32 + fq * 8 + 4 * n);
; #pragma unroll
;         for (int ai = 0; ai < 2; ++ai)
; #pragma unroll
;             for (int m = 0; m < 4; ++m) {
;                 const int row = u.pm * 256 + ai * 128 + wr * 64 + m * 16 + fr;
; #pragma unroll
;                 for (int bj = 0; bj < 2; ++bj) {
;                     const size_t off = (size_t)row * D + u.pn * 256 + bj * 128 + wc * 32 + fq * 8;
;                     f32x4 x0, x1;
;                     if (XINF) { x0 = *(const f32x4*)(XINF + off); x1 = *(const f32x4*)(XINF + off + 4); }
;                     else { const u32x4 w = *(const u32x4*)(XIN16 + off); x0 = (f32x4){bflo(w[0]), bfhi(w[0]), bflo(w[1]), bfhi(w[1])}; x1 = (f32x4){bflo(w[2]), bfhi(w[2]), bflo(w[3]), bfhi(w[3])}; }
;                     *(u32x4*)(XOUT + off) = pack8u(x0 + gt[bj][0] * acc[ai][bj][m][0], x1 + gt[bj][1] * acc[ai][bj][m][1]);
	s_waitcnt lgkmcnt(0)
	v_mfma_f32_16x16x32_bf16 v[60:63], v[128:131], v[156:159], v[60:63]
	v_mfma_f32_16x16x32_bf16 v[56:59], v[136:139], v[156:159], v[56:59]
	v_mfma_f32_16x16x32_bf16 v[44:47], v[128:131], v[168:171], v[44:47]
	v_mfma_f32_16x16x32_bf16 v[40:43], v[136:139], v[168:171], v[40:43]
	v_mfma_f32_16x16x32_bf16 v[28:31], v[128:131], v[176:179], v[28:31]
	v_mfma_f32_16x16x32_bf16 v[24:27], v[136:139], v[176:179], v[24:27]
	v_mfma_f32_16x16x32_bf16 v[12:15], v[128:131], v[184:187], v[12:15]
	v_mfma_f32_16x16x32_bf16 v[8:11], v[136:139], v[184:187], v[8:11]
	v_mfma_f32_16x16x32_bf16 v[60:63], v[132:135], v[164:167], v[60:63]
	v_mfma_f32_16x16x32_bf16 v[56:59], v[140:143], v[164:167], v[56:59]
	v_mfma_f32_16x16x32_bf16 v[44:47], v[132:135], v[172:175], v[44:47]
	v_mfma_f32_16x16x32_bf16 v[40:43], v[140:143], v[172:175], v[40:43]
	v_mfma_f32_16x16x32_bf16 v[28:31], v[132:135], v[180:183], v[28:31]
	v_mfma_f32_16x16x32_bf16 v[24:27], v[140:143], v[180:183], v[24:27]
	v_mfma_f32_16x16x32_bf16 v[12:15], v[132:135], v[188:191], v[12:15]
	v_mfma_f32_16x16x32_bf16 v[8:11], v[140:143], v[188:191], v[8:11]
	s_setprio 0
	s_barrier
	s_add_u32 s26, s36, 0x160080
	s_addc_u32 s27, s37, 0
	s_add_i32 s34, s35, s31
	s_mov_b32 m0, s34
	s_nop 0
	global_load_lds_dwordx4 v208, s[26:27]
	s_add_i32 m0, s34, 0x2000
	s_nop 0
	global_load_lds_dwordx4 v148, s[26:27]
	s_waitcnt vmcnt(6)
	s_setprio 1
	s_barrier
	v_mfma_f32_16x16x32_bf16 v[52:55], v[192:195], v[156:159], v[52:55]
	v_mfma_f32_16x16x32_bf16 v[48:51], v[200:203], v[156:159], v[48:51]
	v_mfma_f32_16x16x32_bf16 v[36:39], v[192:195], v[168:171], v[36:39]
	v_mfma_f32_16x16x32_bf16 v[32:35], v[200:203], v[168:171], v[32:35]
	v_mfma_f32_16x16x32_bf16 v[20:23], v[192:195], v[176:179], v[20:23]
	v_mfma_f32_16x16x32_bf16 v[16:19], v[200:203], v[176:179], v[16:19]
	v_mfma_f32_16x16x32_bf16 v[4:7], v[192:195], v[184:187], v[4:7]
	v_mfma_f32_16x16x32_bf16 v[0:3], v[200:203], v[184:187], v[0:3]
	v_mfma_f32_16x16x32_bf16 v[52:55], v[196:199], v[164:167], v[52:55]
	v_mfma_f32_16x16x32_bf16 v[48:51], v[204:207], v[164:167], v[48:51]
	v_mfma_f32_16x16x32_bf16 v[36:39], v[196:199], v[172:175], v[36:39]
	v_mfma_f32_16x16x32_bf16 v[32:35], v[204:207], v[172:175], v[32:35]
	v_mfma_f32_16x16x32_bf16 v[20:23], v[196:199], v[180:183], v[20:23]
	v_mfma_f32_16x16x32_bf16 v[16:19], v[204:207], v[180:183], v[16:19]
	v_mfma_f32_16x16x32_bf16 v[4:7], v[196:199], v[188:191], v[4:7]
	v_mfma_f32_16x16x32_bf16 v[0:3], v[204:207], v[188:191], v[0:3]
	s_setprio 0
	s_add_i32 s82, s82, 2
	s_add_u32 s78, s78, 0x100
	s_addc_u32 s79, s79, 0
	s_cmpk_gt_u32 s82, 0x55
	s_mov_b64 s[26:27], s[28:29]
	s_barrier
	s_cbranch_scc0 .LBB0_873
	s_ashr_i32 s26, s74, 31
	s_lshr_b32 s26, s26, 29
	s_add_i32 s26, s74, s26
	s_ashr_i32 s26, s26, 3
	s_mul_i32 s26, s26, 6
	s_ashr_i32 s27, s26, 31
	s_lshl_b64 s[26:27], s[26:27], 13
	s_add_u32 s28, s48, s26
	s_addc_u32 s29, s49, s27
	s_lshl_b32 s26, s76, 8
	s_ashr_i32 s27, s26, 31
	v_lshl_add_u32 v157, s74, 8, v151
	v_or_b32_e32 v158, s26, v150
	s_lshl_b64 s[26:27], s[26:27], 2
	s_add_u32 s26, s28, s26
	s_addc_u32 s27, s29, s27
	s_add_u32 s26, s26, s69
	s_addc_u32 s27, s27, 0
	global_load_dwordx4 v[140:143], v162, s[26:27]
	global_load_dwordx4 v[136:139], v162, s[26:27] offset:16
	global_load_dwordx4 v[132:135], v162, s[26:27] offset:512
	global_load_dwordx4 v[128:131], v162, s[26:27] offset:528
	v_lshlrev_b32_e32 v156, 1, v158
	v_lshl_add_u32 v156, v157, 12, v156
	v_add_u32_e32 v157, 0x0, v156
	global_load_dwordx4 v[164:167], v157, s[96:97] offset:0
	v_add_u32_e32 v157, 0x0, v156
	global_load_dwordx4 v[168:171], v157, s[96:97] offset:256
	v_add_u32_e32 v157, 0x10000, v156
	global_load_dwordx4 v[172:175], v157, s[96:97] offset:0
	v_add_u32_e32 v157, 0x10000, v156
	global_load_dwordx4 v[184:187], v157, s[96:97] offset:256
	v_add_u32_e32 v157, 0x20000, v156
	global_load_dwordx4 v[188:191], v157, s[96:97] offset:0
	v_add_u32_e32 v157, 0x20000, v156
	global_load_dwordx4 v[192:195], v157, s[96:97] offset:256
	v_add_u32_e32 v157, 0x30000, v156
	global_load_dwordx4 v[196:199], v157, s[96:97] offset:0
	v_add_u32_e32 v157, 0x30000, v156
	global_load_dwordx4 v[200:203], v157, s[96:97] offset:256
	v_add_u32_e32 v157, 0x80000, v156
	global_load_dwordx4 v[204:207], v157, s[96:97] offset:0
	v_add_u32_e32 v157, 0x80000, v156
	global_load_dwordx4 v[228:231], v157, s[96:97] offset:256
	s_waitcnt vmcnt(9)
	v_lshlrev_b32_e32 v176, 16, v164
	v_and_b32_e32 v177, 0xffff0000, v164
	v_lshlrev_b32_e32 v178, 16, v165
	v_and_b32_e32 v179, 0xffff0000, v165
	v_lshlrev_b32_e32 v180, 16, v166
	v_and_b32_e32 v181, 0xffff0000, v166
	v_lshlrev_b32_e32 v182, 16, v167
	v_and_b32_e32 v183, 0xffff0000, v167
	v_pk_fma_f32 v[124:125], v[124:125], v[140:141], v[176:177]
	v_pk_fma_f32 v[126:127], v[126:127], v[142:143], v[178:179]
	v_pk_fma_f32 v[120:121], v[120:121], v[136:137], v[180:181]
	v_pk_fma_f32 v[122:123], v[122:123], v[138:139], v[182:183]
	v_cvt_pk_bf16_f32 v124, v124, v125
	v_cvt_pk_bf16_f32 v125, v126, v127
	v_cvt_pk_bf16_f32 v126, v120, v121
	v_cvt_pk_bf16_f32 v127, v122, v123
	v_add_u32_e32 v158, 0x0, v156
	global_store_dwordx4 v158, v[124:127], s[96:97] offset:0
	v_add_u32_e32 v157, 0x90000, v156
	global_load_dwordx4 v[164:167], v157, s[96:97] offset:0
	v_add_u32_e32 v157, 0x90000, v156
	global_load_dwordx4 v[120:123], v157, s[96:97] offset:256
	s_waitcnt vmcnt(11)
; __device__ __forceinline__ float bflo(unsigned w) { return __uint_as_float(w << 16); }
; __device__ __forceinline__ float bfhi(unsigned w) { return __uint_as_float(w & 0xffff0000u); }
; __device__ __forceinline__ u32x4 pack8u(f32x4 a, f32x4 b) { u32x4 w = {cvt_pk_bf16(a[0], a[1]), cvt_pk_bf16(a[2], a[3]), cvt_pk_bf16(b[0], b[1]), cvt_pk_bf16(b[2], b[3])}; return w; }
;     __device__ __forceinline__ void operator()(const AccT& acc, const Unit& u, int wr, int wc, int fr, int fq) const {
;     ...
;         for (int ai = 0; ai < 2; ++ai)
; #pragma unroll
;             for (int m = 0; m < 4; ++m) {
;                 const int row = u.pm * 256 + ai * 128 + wr * 64 + m * 16 + fr;
; #pragma unroll
;                 for (int bj = 0; bj < 2; ++bj) {
;                     const size_t off = (size_t)row * D + u.pn * 256 + bj * 128 + wc * 32 + fq * 8;
;                     f32x4 x0, x1;
;                     if (XINF) { x0 = *(const f32x4*)(XINF + off); x1 = *(const f32x4*)(XINF + off + 4); }
;                     else { const u32x4 w = *(const u32x4*)(XIN16 + off); x0 = (f32x4){bflo(w[0]), bfhi(w[0]), bflo(w[1]), bfhi(w[1])}; x1 = (f32x4){bflo(w[2]), bfhi(w[2]), bflo(w[3]), bfhi(w[3])}; }
;                     *(u32x4*)(XOUT + off) = pack8u(x0 + gt[bj][0] * acc[ai][bj][m][0], x1 + gt[bj][1] * acc[ai][bj][m][1]);
	v_lshlrev_b32_e32 v176, 16, v168
	v_and_b32_e32 v177, 0xffff0000, v168
	v_lshlrev_b32_e32 v178, 16, v169
	v_and_b32_e32 v179, 0xffff0000, v169
	v_lshlrev_b32_e32 v180, 16, v170
	v_and_b32_e32 v181, 0xffff0000, v170
	v_lshlrev_b32_e32 v182, 16, v171
	v_and_b32_e32 v183, 0xffff0000, v171
	v_pk_fma_f32 v[116:117], v[116:117], v[132:133], v[176:177]
	v_pk_fma_f32 v[118:119], v[118:119], v[134:135], v[178:179]
	v_pk_fma_f32 v[112:113], v[112:113], v[128:129], v[180:181]
	v_pk_fma_f32 v[114:115], v[114:115], v[130:131], v[182:183]
	v_cvt_pk_bf16_f32 v116, v116, v117
	v_cvt_pk_bf16_f32 v117, v118, v119
	v_cvt_pk_bf16_f32 v118, v112, v113
	v_cvt_pk_bf16_f32 v119, v114, v115
	v_add_u32_e32 v158, 0x0, v156
	global_store_dwordx4 v158, v[116:119], s[96:97] offset:256
	v_add_u32_e32 v157, 0xa0000, v156
	global_load_dwordx4 v[168:171], v157, s[96:97] offset:0
	v_add_u32_e32 v157, 0xa0000, v156
	global_load_dwordx4 v[112:115], v157, s[96:97] offset:256
	s_waitcnt vmcnt(13)
	v_lshlrev_b32_e32 v176, 16, v172
	v_and_b32_e32 v177, 0xffff0000, v172
	v_lshlrev_b32_e32 v178, 16, v173
	v_and_b32_e32 v179, 0xffff0000, v173
	v_lshlrev_b32_e32 v180, 16, v174
	v_and_b32_e32 v181, 0xffff0000, v174
	v_lshlrev_b32_e32 v182, 16, v175
	v_and_b32_e32 v183, 0xffff0000, v175
	v_pk_fma_f32 v[108:109], v[108:109], v[140:141], v[176:177]
	v_pk_fma_f32 v[110:111], v[110:111], v[142:143], v[178:179]
	v_pk_fma_f32 v[104:105], v[104:105], v[136:137], v[180:181]
	v_pk_fma_f32 v[106:107], v[106:107], v[138:139], v[182:183]
	v_cvt_pk_bf16_f32 v108, v108, v109
	v_cvt_pk_bf16_f32 v109, v110, v111
	v_cvt_pk_bf16_f32 v110, v104, v105
	v_cvt_pk_bf16_f32 v111, v106, v107
	v_add_u32_e32 v158, 0x10000, v156
	global_store_dwordx4 v158, v[108:111], s[96:97] offset:0
	v_add_u32_e32 v157, 0xb0000, v156
	global_load_dwordx4 v[172:175], v157, s[96:97] offset:0
	v_add_u32_e32 v157, 0xb0000, v156
	global_load_dwordx4 v[104:107], v157, s[96:97] offset:256
	s_waitcnt vmcnt(15)
	v_lshlrev_b32_e32 v176, 16, v184
	v_and_b32_e32 v177, 0xffff0000, v184
	v_lshlrev_b32_e32 v178, 16, v185
	v_and_b32_e32 v179, 0xffff0000, v185
	v_lshlrev_b32_e32 v180, 16, v186
	v_and_b32_e32 v181, 0xffff0000, v186
	v_lshlrev_b32_e32 v182, 16, v187
	v_and_b32_e32 v183, 0xffff0000, v187
	v_pk_fma_f32 v[100:101], v[100:101], v[132:133], v[176:177]
	v_pk_fma_f32 v[102:103], v[102:103], v[134:135], v[178:179]
	v_pk_fma_f32 v[96:97], v[96:97], v[128:129], v[180:181]
	v_pk_fma_f32 v[98:99], v[98:99], v[130:131], v[182:183]
	v_cvt_pk_bf16_f32 v100, v100, v101
	v_cvt_pk_bf16_f32 v101, v102, v103
	v_cvt_pk_bf16_f32 v102, v96, v97
	v_cvt_pk_bf16_f32 v103, v98, v99
	v_add_u32_e32 v158, 0x10000, v156
	global_store_dwordx4 v158, v[100:103], s[96:97] offset:256
	s_waitcnt vmcnt(15)
	v_lshlrev_b32_e32 v176, 16, v188
	v_and_b32_e32 v177, 0xffff0000, v188
	v_lshlrev_b32_e32 v178, 16, v189
	v_and_b32_e32 v179, 0xffff0000, v189
	v_lshlrev_b32_e32 v180, 16, v190
	v_and_b32_e32 v181, 0xffff0000, v190
	v_lshlrev_b32_e32 v182, 16, v191
	v_and_b32_e32 v183, 0xffff0000, v191
	v_pk_fma_f32 v[92:93], v[92:93], v[140:141], v[176:177]
	v_pk_fma_f32 v[94:95], v[94:95], v[142:143], v[178:179]
	v_pk_fma_f32 v[88:89], v[88:89], v[136:137], v[180:181]
	v_pk_fma_f32 v[90:91], v[90:91], v[138:139], v[182:183]
	v_cvt_pk_bf16_f32 v92, v92, v93
	v_cvt_pk_bf16_f32 v93, v94, v95
	v_cvt_pk_bf16_f32 v94, v88, v89
	v_cvt_pk_bf16_f32 v95, v90, v91
	v_add_u32_e32 v158, 0x20000, v156
	global_store_dwordx4 v158, v[92:95], s[96:97] offset:0
	s_waitcnt vmcnt(15)
	v_lshlrev_b32_e32 v176, 16, v192
	v_and_b32_e32 v177, 0xffff0000, v192
	v_lshlrev_b32_e32 v178, 16, v193
	v_and_b32_e32 v179, 0xffff0000, v193
	v_lshlrev_b32_e32 v180, 16, v194
	v_and_b32_e32 v181, 0xffff0000, v194
	v_lshlrev_b32_e32 v182, 16, v195
	v_and_b32_e32 v183, 0xffff0000, v195
	v_pk_fma_f32 v[84:85], v[84:85], v[132:133], v[176:177]
	v_pk_fma_f32 v[86:87], v[86:87], v[134:135], v[178:179]
	v_pk_fma_f32 v[80:81], v[80:81], v[128:129], v[180:181]
	v_pk_fma_f32 v[82:83], v[82:83], v[130:131], v[182:183]
	v_cvt_pk_bf16_f32 v84, v84, v85
	v_cvt_pk_bf16_f32 v85, v86, v87
	v_cvt_pk_bf16_f32 v86, v80, v81
	v_cvt_pk_bf16_f32 v87, v82, v83
	v_add_u32_e32 v158, 0x20000, v156
	global_store_dwordx4 v158, v[84:87], s[96:97] offset:256
	s_waitcnt vmcnt(15)
	v_lshlrev_b32_e32 v176, 16, v196
	v_and_b32_e32 v177, 0xffff0000, v196
	v_lshlrev_b32_e32 v178, 16, v197
	v_and_b32_e32 v179, 0xffff0000, v197
	v_lshlrev_b32_e32 v180, 16, v198
	v_and_b32_e32 v181, 0xffff0000, v198
	v_lshlrev_b32_e32 v182, 16, v199
	v_and_b32_e32 v183, 0xffff0000, v199
	v_pk_fma_f32 v[76:77], v[76:77], v[140:141], v[176:177]
	v_pk_fma_f32 v[78:79], v[78:79], v[142:143], v[178:179]
	v_pk_fma_f32 v[72:73], v[72:73], v[136:137], v[180:181]
	v_pk_fma_f32 v[74:75], v[74:75], v[138:139], v[182:183]
	v_cvt_pk_bf16_f32 v76, v76, v77
	v_cvt_pk_bf16_f32 v77, v78, v79
	v_cvt_pk_bf16_f32 v78, v72, v73
	v_cvt_pk_bf16_f32 v79, v74, v75
	v_add_u32_e32 v158, 0x30000, v156
	global_store_dwordx4 v158, v[76:79], s[96:97] offset:0
	s_waitcnt vmcnt(15)
	v_lshlrev_b32_e32 v176, 16, v200
	v_and_b32_e32 v177, 0xffff0000, v200
	v_lshlrev_b32_e32 v178, 16, v201
	v_and_b32_e32 v179, 0xffff0000, v201
	v_lshlrev_b32_e32 v180, 16, v202
	v_and_b32_e32 v181, 0xffff0000, v202
	v_lshlrev_b32_e32 v182, 16, v203
	v_and_b32_e32 v183, 0xffff0000, v203
	v_pk_fma_f32 v[68:69], v[68:69], v[132:133], v[176:177]
	v_pk_fma_f32 v[70:71], v[70:71], v[134:135], v[178:179]
	v_pk_fma_f32 v[64:65], v[64:65], v[128:129], v[180:181]
	v_pk_fma_f32 v[66:67], v[66:67], v[130:131], v[182:183]
	v_cvt_pk_bf16_f32 v68, v68, v69
	v_cvt_pk_bf16_f32 v69, v70, v71
	v_cvt_pk_bf16_f32 v70, v64, v65
	v_cvt_pk_bf16_f32 v71, v66, v67
	v_add_u32_e32 v158, 0x30000, v156
	global_store_dwordx4 v158, v[68:71], s[96:97] offset:256
	s_waitcnt vmcnt(15)
; __device__ __forceinline__ float bflo(unsigned w) { return __uint_as_float(w << 16); }
; __device__ __forceinline__ float bfhi(unsigned w) { return __uint_as_float(w & 0xffff0000u); }
; __device__ __forceinline__ u32x4 pack8u(f32x4 a, f32x4 b) { u32x4 w = {cvt_pk_bf16(a[0], a[1]), cvt_pk_bf16(a[2], a[3]), cvt_pk_bf16(b[0], b[1]), cvt_pk_bf16(b[2], b[3])}; return w; }
; #define PG8_WAIT_V(n) asm volatile("s_waitcnt vmcnt(" #n ")" ::: "memory")
; #define PG8_BAR __builtin_amdgcn_s_barrier()
; template <class Epi>
; __device__ __forceinline__ void gemm_phase(LAS unsigned char* lds, const Gemm g, const Epi& E) {
;     ...
;         E(acc, cur, wr, wc, fr, fq);
;         if (!has_next) break;
; #pragma unroll
;         for (int a = 0; a < 2; ++a)
; #pragma unroll
;             for (int b = 0; b < 2; ++b)
; #pragma unroll
;                 for (int m = 0; m < 4; ++m)
; #pragma unroll
;                     for (int n = 0; n < 2; ++n) acc[a][b][m][n] = (f32x4){0.f, 0.f, 0.f, 0.f};
;         cur = nxt; cA = nA; cB = nB; ++ui;
;     }
;     PG8_WAIT_V(0);
;     if (wr == 0) PG8_BAR;
;     PG8_BAR;
;     __device__ __forceinline__ void operator()(const AccT& acc, const Unit& u, int wr, int wc, int fr, int fq) const {
;     ...
;                 for (int bj = 0; bj < 2; ++bj) {
;                     const size_t off = (size_t)row * D + u.pn * 256 + bj * 128 + wc * 32 + fq * 8;
;                     f32x4 x0, x1;
;                     if (XINF) { x0 = *(const f32x4*)(XINF + off); x1 = *(const f32x4*)(XINF + off + 4); }
;                     else { const u32x4 w = *(const u32x4*)(XIN16 + off); x0 = (f32x4){bflo(w[0]), bfhi(w[0]), bflo(w[1]), bfhi(w[1])}; x1 = (f32x4){bflo(w[2]), bfhi(w[2]), bflo(w[3]), bfhi(w[3])}; }
;                     *(u32x4*)(XOUT + off) = pack8u(x0 + gt[bj][0] * acc[ai][bj][m][0], x1 + gt[bj][1] * acc[ai][bj][m][1]);
	v_lshlrev_b32_e32 v176, 16, v204
	v_and_b32_e32 v177, 0xffff0000, v204
	v_lshlrev_b32_e32 v178, 16, v205
	v_and_b32_e32 v179, 0xffff0000, v205
	v_lshlrev_b32_e32 v180, 16, v206
	v_and_b32_e32 v181, 0xffff0000, v206
	v_lshlrev_b32_e32 v182, 16, v207
	v_and_b32_e32 v183, 0xffff0000, v207
	v_pk_fma_f32 v[60:61], v[60:61], v[140:141], v[176:177]
	v_pk_fma_f32 v[62:63], v[62:63], v[142:143], v[178:179]
	v_pk_fma_f32 v[56:57], v[56:57], v[136:137], v[180:181]
	v_pk_fma_f32 v[58:59], v[58:59], v[138:139], v[182:183]
	v_cvt_pk_bf16_f32 v60, v60, v61
	v_cvt_pk_bf16_f32 v61, v62, v63
	v_cvt_pk_bf16_f32 v62, v56, v57
	v_cvt_pk_bf16_f32 v63, v58, v59
	v_add_u32_e32 v158, 0x80000, v156
	global_store_dwordx4 v158, v[60:63], s[96:97] offset:0
	s_waitcnt vmcnt(15)
	v_lshlrev_b32_e32 v176, 16, v228
	v_and_b32_e32 v177, 0xffff0000, v228
	v_lshlrev_b32_e32 v178, 16, v229
	v_and_b32_e32 v179, 0xffff0000, v229
	v_lshlrev_b32_e32 v180, 16, v230
	v_and_b32_e32 v181, 0xffff0000, v230
	v_lshlrev_b32_e32 v182, 16, v231
	v_and_b32_e32 v183, 0xffff0000, v231
	v_pk_fma_f32 v[52:53], v[52:53], v[132:133], v[176:177]
	v_pk_fma_f32 v[54:55], v[54:55], v[134:135], v[178:179]
	v_pk_fma_f32 v[48:49], v[48:49], v[128:129], v[180:181]
	v_pk_fma_f32 v[50:51], v[50:51], v[130:131], v[182:183]
	v_cvt_pk_bf16_f32 v52, v52, v53
	v_cvt_pk_bf16_f32 v53, v54, v55
	v_cvt_pk_bf16_f32 v54, v48, v49
	v_cvt_pk_bf16_f32 v55, v50, v51
	v_add_u32_e32 v158, 0x80000, v156
	global_store_dwordx4 v158, v[52:55], s[96:97] offset:256
	s_waitcnt vmcnt(14)
	v_lshlrev_b32_e32 v176, 16, v164
	v_and_b32_e32 v177, 0xffff0000, v164
	v_lshlrev_b32_e32 v178, 16, v165
	v_and_b32_e32 v179, 0xffff0000, v165
	v_lshlrev_b32_e32 v180, 16, v166
	v_and_b32_e32 v181, 0xffff0000, v166
	v_lshlrev_b32_e32 v182, 16, v167
	v_and_b32_e32 v183, 0xffff0000, v167
	v_pk_fma_f32 v[44:45], v[44:45], v[140:141], v[176:177]
	v_pk_fma_f32 v[46:47], v[46:47], v[142:143], v[178:179]
	v_pk_fma_f32 v[40:41], v[40:41], v[136:137], v[180:181]
	v_pk_fma_f32 v[42:43], v[42:43], v[138:139], v[182:183]
	v_cvt_pk_bf16_f32 v44, v44, v45
	v_cvt_pk_bf16_f32 v45, v46, v47
	v_cvt_pk_bf16_f32 v46, v40, v41
	v_cvt_pk_bf16_f32 v47, v42, v43
	v_add_u32_e32 v158, 0x90000, v156
	global_store_dwordx4 v158, v[44:47], s[96:97] offset:0
	s_waitcnt vmcnt(14)
	v_lshlrev_b32_e32 v176, 16, v120
	v_and_b32_e32 v177, 0xffff0000, v120
	v_lshlrev_b32_e32 v178, 16, v121
	v_and_b32_e32 v179, 0xffff0000, v121
	v_lshlrev_b32_e32 v180, 16, v122
	v_and_b32_e32 v181, 0xffff0000, v122
	v_lshlrev_b32_e32 v182, 16, v123
	v_and_b32_e32 v183, 0xffff0000, v123
	v_pk_fma_f32 v[36:37], v[36:37], v[132:133], v[176:177]
	v_pk_fma_f32 v[38:39], v[38:39], v[134:135], v[178:179]
	v_pk_fma_f32 v[32:33], v[32:33], v[128:129], v[180:181]
	v_pk_fma_f32 v[34:35], v[34:35], v[130:131], v[182:183]
	v_cvt_pk_bf16_f32 v36, v36, v37
	v_cvt_pk_bf16_f32 v37, v38, v39
	v_cvt_pk_bf16_f32 v38, v32, v33
	v_cvt_pk_bf16_f32 v39, v34, v35
	v_add_u32_e32 v158, 0x90000, v156
	global_store_dwordx4 v158, v[36:39], s[96:97] offset:256
	s_waitcnt vmcnt(13)
	v_lshlrev_b32_e32 v176, 16, v168
	v_and_b32_e32 v177, 0xffff0000, v168
	v_lshlrev_b32_e32 v178, 16, v169
	v_and_b32_e32 v179, 0xffff0000, v169
	v_lshlrev_b32_e32 v180, 16, v170
	v_and_b32_e32 v181, 0xffff0000, v170
	v_lshlrev_b32_e32 v182, 16, v171
	v_and_b32_e32 v183, 0xffff0000, v171
	v_pk_fma_f32 v[28:29], v[28:29], v[140:141], v[176:177]
	v_pk_fma_f32 v[30:31], v[30:31], v[142:143], v[178:179]
	v_pk_fma_f32 v[24:25], v[24:25], v[136:137], v[180:181]
	v_pk_fma_f32 v[26:27], v[26:27], v[138:139], v[182:183]
	v_cvt_pk_bf16_f32 v28, v28, v29
	v_cvt_pk_bf16_f32 v29, v30, v31
	v_cvt_pk_bf16_f32 v30, v24, v25
	v_cvt_pk_bf16_f32 v31, v26, v27
	v_add_u32_e32 v158, 0xa0000, v156
	global_store_dwordx4 v158, v[28:31], s[96:97] offset:0
	s_waitcnt vmcnt(13)
	v_lshlrev_b32_e32 v176, 16, v112
	v_and_b32_e32 v177, 0xffff0000, v112
	v_lshlrev_b32_e32 v178, 16, v113
	v_and_b32_e32 v179, 0xffff0000, v113
	v_lshlrev_b32_e32 v180, 16, v114
	v_and_b32_e32 v181, 0xffff0000, v114
	v_lshlrev_b32_e32 v182, 16, v115
	v_and_b32_e32 v183, 0xffff0000, v115
	v_pk_fma_f32 v[20:21], v[20:21], v[132:133], v[176:177]
	v_pk_fma_f32 v[22:23], v[22:23], v[134:135], v[178:179]
	v_pk_fma_f32 v[16:17], v[16:17], v[128:129], v[180:181]
	v_pk_fma_f32 v[18:19], v[18:19], v[130:131], v[182:183]
	v_cvt_pk_bf16_f32 v20, v20, v21
	v_cvt_pk_bf16_f32 v21, v22, v23
	v_cvt_pk_bf16_f32 v22, v16, v17
	v_cvt_pk_bf16_f32 v23, v18, v19
	v_add_u32_e32 v158, 0xa0000, v156
	global_store_dwordx4 v158, v[20:23], s[96:97] offset:256
	s_waitcnt vmcnt(12)
	v_lshlrev_b32_e32 v176, 16, v172
	v_and_b32_e32 v177, 0xffff0000, v172
	v_lshlrev_b32_e32 v178, 16, v173
	v_and_b32_e32 v179, 0xffff0000, v173
	v_lshlrev_b32_e32 v180, 16, v174
	v_and_b32_e32 v181, 0xffff0000, v174
	v_lshlrev_b32_e32 v182, 16, v175
	v_and_b32_e32 v183, 0xffff0000, v175
	v_pk_fma_f32 v[12:13], v[12:13], v[140:141], v[176:177]
	v_pk_fma_f32 v[14:15], v[14:15], v[142:143], v[178:179]
	v_pk_fma_f32 v[8:9], v[8:9], v[136:137], v[180:181]
	v_pk_fma_f32 v[10:11], v[10:11], v[138:139], v[182:183]
	v_cvt_pk_bf16_f32 v12, v12, v13
	v_cvt_pk_bf16_f32 v13, v14, v15
	v_cvt_pk_bf16_f32 v14, v8, v9
	v_cvt_pk_bf16_f32 v15, v10, v11
	v_add_u32_e32 v158, 0xb0000, v156
	global_store_dwordx4 v158, v[12:15], s[96:97] offset:0
	s_waitcnt vmcnt(12)
	v_lshlrev_b32_e32 v176, 16, v104
	v_and_b32_e32 v177, 0xffff0000, v104
	v_lshlrev_b32_e32 v178, 16, v105
	v_and_b32_e32 v179, 0xffff0000, v105
	v_lshlrev_b32_e32 v180, 16, v106
	v_and_b32_e32 v181, 0xffff0000, v106
	v_lshlrev_b32_e32 v182, 16, v107
	v_and_b32_e32 v183, 0xffff0000, v107
	v_pk_fma_f32 v[4:5], v[4:5], v[132:133], v[176:177]
	v_pk_fma_f32 v[6:7], v[6:7], v[134:135], v[178:179]
	v_pk_fma_f32 v[0:1], v[0:1], v[128:129], v[180:181]
	v_pk_fma_f32 v[2:3], v[2:3], v[130:131], v[182:183]
	v_cvt_pk_bf16_f32 v4, v4, v5
	v_cvt_pk_bf16_f32 v5, v6, v7
	v_cvt_pk_bf16_f32 v6, v0, v1
	v_cvt_pk_bf16_f32 v7, v2, v3
	v_add_u32_e32 v158, 0xb0000, v156
	global_store_dwordx4 v158, v[4:7], s[96:97] offset:256
	s_mov_b64 s[28:29], s[42:43]
	s_mov_b64 s[26:27], s[0:1]
	s_mov_b32 s74, s71
	s_mov_b32 s76, s70
	s_and_b64 vcc, exec, s[40:41]
	v_readlane_b32 s82, v255, 24
	v_readlane_b32 s83, v255, 25
	s_cbranch_vccz .LBB0_862
	s_waitcnt vmcnt(0)
	s_cmpk_gt_u32 s3, 0xff
	s_cbranch_scc1 .LBB0_877
	s_barrier
